# comb5 + ds_read fragment loads interleaved with LDS-DMA issues inside each GEMM load segment (pure reorder)
# speedup vs baseline: 1.0035x; 1.0035x over previous
; #define PG8_STAGE(bufoff, gbase, voff) do { _Pragma("unroll") for (int _i = 0; _i < 2; ++_i) \
;         __builtin_amdgcn_global_load_lds((const unsigned*)((const char*)(gbase) + (voff)[_i]), (LAS unsigned*)(lds + (bufoff) + ldsw + _i * 8192), 16, 0, 0); } while (0)
; #define PG8_LDA(dst, b, h) do { _Pragma("unroll") for (int m = 0; m < 4; ++m) _Pragma("unroll") for (int k = 0; k < 2; ++k) dst[m][k] = *(const LAS bf16x8*)(lds + PG8_SA(b, h) + aoff + m * 2048 + k * 1024); } while (0)
; #define PG8_LDB(dst, b, h) do { _Pragma("unroll") for (int n = 0; n < 2; ++n) _Pragma("unroll") for (int k = 0; k < 2; ++k) dst[n][k] = *(const LAS bf16x8*)(lds + PG8_SB(b, h) + boff + n * 2048 + k * 1024); } while (0)
; #define PG8_MMA(ai, bj, At, Bt) do { __builtin_amdgcn_s_setprio(1); _Pragma("unroll") for (int m = 0; m < 4; ++m) _Pragma("unroll") for (int n = 0; n < 2; ++n) _Pragma("unroll") for (int k = 0; k < 2; ++k) \
;         acc[ai][bj][m][n] = __builtin_amdgcn_mfma_f32_16x16x32_bf16(Bt[n][k], At[m][k], acc[ai][bj][m][n], 0, 0, 0); __builtin_amdgcn_s_setprio(0); } while (0)
; #define PG8_WAIT_V(n) asm volatile("s_waitcnt vmcnt(" #n ")" ::: "memory")
; #define PG8_WAIT_L(n) asm volatile("s_waitcnt lgkmcnt(" #n ")" ::: "memory")
; #define PG8_BAR __builtin_amdgcn_s_barrier()
; #define PG8_SCHED __builtin_amdgcn_sched_barrier(0)
; template <class Epi, class Sched, bool ALIGN_EPI, class Hook = NoHook>
; __device__ __forceinline__ void gemm_phase(LAS unsigned char* lds, const Gemm g, const Sched& S, const Epi& E, const Hook& H = Hook()) {
;     ...
;             PG8_LDB(B0, 0, 0); PG8_LDB(B1, 0, 1); PG8_SCHED; PG8_LDA(At, 0, 0); PG8_STAGE(PG8_SA(1, 1), a1 + hA, voffA);
;             PG8_WAIT_V(8); PG8_WAIT_L(0); PG8_BAR; PG8_MMA(0, 0, At, B0); PG8_MMA(0, 1, At, B1); PG8_BAR; PG8_SCHED;
;             PG8_LDA(At, 0, 1); PG8_STAGE(PG8_SB(0, 0), b2, voffB); PG8_STAGE(PG8_SB(0, 1), b2 + hB, voffB); PG8_STAGE(PG8_SA(0, 0), a2, voffA);
;             PG8_WAIT_V(8); PG8_WAIT_L(0); PG8_BAR; PG8_MMA(1, 0, At, B0); PG8_MMA(1, 1, At, B1); PG8_BAR; PG8_SCHED;
.LBB0_199:
	ds_read_b128 v[130:133], v217
	ds_read_b128 v[134:137], v217 offset:1024
	s_add_u32 s34, s4, 0x100
	s_addc_u32 s35, s5, 0
	s_cmp_eq_u32 s64, 60
	s_cselect_b32 s39, s7, s35
	s_cselect_b32 s38, s8, s34
	s_cselect_b32 s37, s23, s63
	s_cselect_b32 s36, s25, s31
	s_add_i32 m0, s40, 0xc000
	s_nop 0
	global_load_lds_dwordx4 v172, s[4:5]
	ds_read_b128 v[138:141], v217 offset:2048
	ds_read_b128 v[142:145], v217 offset:3072
	ds_read_b128 v[146:149], v218
	ds_read_b128 v[150:153], v218 offset:1024
	ds_read_b128 v[154:157], v218 offset:2048
	ds_read_b128 v[158:161], v218 offset:3072
	ds_read_b128 v[180:183], v219
	s_add_i32 m0, s40, 0xe000
	s_nop 0
	global_load_lds_dwordx4 v174, s[4:5]
	ds_read_b128 v[184:187], v219 offset:1024
	ds_read_b128 v[188:191], v219 offset:2048
	ds_read_b128 v[192:195], v219 offset:3072
	ds_read_b128 v[196:199], v219 offset:4096
	ds_read_b128 v[200:203], v219 offset:5120
	ds_read_b128 v[204:207], v219 offset:6144
	ds_read_b128 v[208:211], v219 offset:7168
	s_waitcnt vmcnt(8)
	s_waitcnt lgkmcnt(0)
	s_barrier
	s_setprio 1
	s_waitcnt lgkmcnt(0)
	v_mfma_f32_16x16x32_bf16 v[126:129], v[130:133], v[180:183], v[126:129]
	v_mfma_f32_16x16x32_bf16 v[94:97], v[138:141], v[180:183], v[94:97]
	v_mfma_f32_16x16x32_bf16 v[122:125], v[130:133], v[188:191], v[122:125]
	v_mfma_f32_16x16x32_bf16 v[90:93], v[138:141], v[188:191], v[90:93]
	v_mfma_f32_16x16x32_bf16 v[118:121], v[130:133], v[196:199], v[118:121]
	v_mfma_f32_16x16x32_bf16 v[86:89], v[138:141], v[196:199], v[86:89]
	v_mfma_f32_16x16x32_bf16 v[114:117], v[130:133], v[204:207], v[114:117]
	v_mfma_f32_16x16x32_bf16 v[82:85], v[138:141], v[204:207], v[82:85]
	v_mfma_f32_16x16x32_bf16 v[126:129], v[134:137], v[184:187], v[126:129]
	v_mfma_f32_16x16x32_bf16 v[94:97], v[142:145], v[184:187], v[94:97]
	v_mfma_f32_16x16x32_bf16 v[122:125], v[134:137], v[192:195], v[122:125]
	v_mfma_f32_16x16x32_bf16 v[90:93], v[142:145], v[192:195], v[90:93]
	v_mfma_f32_16x16x32_bf16 v[118:121], v[134:137], v[200:203], v[118:121]
	v_mfma_f32_16x16x32_bf16 v[86:89], v[142:145], v[200:203], v[86:89]
	v_mfma_f32_16x16x32_bf16 v[114:117], v[134:137], v[208:211], v[114:117]
	v_mfma_f32_16x16x32_bf16 v[82:85], v[142:145], v[208:211], v[82:85]
	s_setprio 0
	s_setprio 1
	v_mfma_f32_16x16x32_bf16 v[62:65], v[146:149], v[180:183], v[62:65]
	v_mfma_f32_16x16x32_bf16 v[30:33], v[154:157], v[180:183], v[30:33]
	v_mfma_f32_16x16x32_bf16 v[58:61], v[146:149], v[188:191], v[58:61]
	v_mfma_f32_16x16x32_bf16 v[26:29], v[154:157], v[188:191], v[26:29]
	v_mfma_f32_16x16x32_bf16 v[54:57], v[146:149], v[196:199], v[54:57]
	v_mfma_f32_16x16x32_bf16 v[22:25], v[154:157], v[196:199], v[22:25]
	v_mfma_f32_16x16x32_bf16 v[50:53], v[146:149], v[204:207], v[50:53]
	v_mfma_f32_16x16x32_bf16 v[18:21], v[154:157], v[204:207], v[18:21]
	v_mfma_f32_16x16x32_bf16 v[62:65], v[150:153], v[184:187], v[62:65]
	v_mfma_f32_16x16x32_bf16 v[30:33], v[158:161], v[184:187], v[30:33]
	v_mfma_f32_16x16x32_bf16 v[58:61], v[150:153], v[192:195], v[58:61]
	v_mfma_f32_16x16x32_bf16 v[26:29], v[158:161], v[192:195], v[26:29]
	v_mfma_f32_16x16x32_bf16 v[54:57], v[150:153], v[200:203], v[54:57]
	v_mfma_f32_16x16x32_bf16 v[22:25], v[158:161], v[200:203], v[22:25]
	v_mfma_f32_16x16x32_bf16 v[50:53], v[150:153], v[208:211], v[50:53]
	v_mfma_f32_16x16x32_bf16 v[18:21], v[158:161], v[208:211], v[18:21]
	s_setprio 0
	s_barrier
	s_add_i32 s4, s59, s21
	s_mov_b32 m0, s4
	ds_read_b128 v[180:183], v219 offset:16384
	ds_read_b128 v[184:187], v219 offset:17408
	global_load_lds_dwordx4 v164, s[36:37]
	ds_read_b128 v[188:191], v219 offset:18432
	s_add_i32 m0, s4, 0x2000
	s_add_u32 s4, s36, 0x100000
	s_addc_u32 s5, s37, 0
	s_add_i32 s65, s60, s21
	global_load_lds_dwordx4 v168, s[36:37]
	ds_read_b128 v[192:195], v219 offset:19456
	s_mov_b32 m0, s65
	s_nop 0
	global_load_lds_dwordx4 v164, s[4:5]
	ds_read_b128 v[196:199], v219 offset:20480
	s_add_i32 m0, s65, 0x2000
	s_nop 0
	global_load_lds_dwordx4 v168, s[4:5]
	ds_read_b128 v[200:203], v219 offset:21504
	s_mov_b32 m0, s40
	s_nop 0
	global_load_lds_dwordx4 v162, s[38:39]
	ds_read_b128 v[204:207], v219 offset:22528
	s_mov_b32 m0, s41
	s_nop 0
	global_load_lds_dwordx4 v166, s[38:39]
	ds_read_b128 v[208:211], v219 offset:23552
	s_waitcnt vmcnt(8)
	s_waitcnt lgkmcnt(0)
	s_barrier
	s_setprio 1
	s_waitcnt lgkmcnt(0)
	v_mfma_f32_16x16x32_bf16 v[110:113], v[130:133], v[180:183], v[110:113]
	v_mfma_f32_16x16x32_bf16 v[78:81], v[138:141], v[180:183], v[78:81]
	v_mfma_f32_16x16x32_bf16 v[106:109], v[130:133], v[188:191], v[106:109]
	v_mfma_f32_16x16x32_bf16 v[74:77], v[138:141], v[188:191], v[74:77]
	v_mfma_f32_16x16x32_bf16 v[102:105], v[130:133], v[196:199], v[102:105]
	v_mfma_f32_16x16x32_bf16 v[70:73], v[138:141], v[196:199], v[70:73]
	v_mfma_f32_16x16x32_bf16 v[98:101], v[130:133], v[204:207], v[98:101]
	v_mfma_f32_16x16x32_bf16 v[66:69], v[138:141], v[204:207], v[66:69]
	v_mfma_f32_16x16x32_bf16 v[110:113], v[134:137], v[184:187], v[110:113]
	v_mfma_f32_16x16x32_bf16 v[78:81], v[142:145], v[184:187], v[78:81]
	v_mfma_f32_16x16x32_bf16 v[106:109], v[134:137], v[192:195], v[106:109]
	v_mfma_f32_16x16x32_bf16 v[74:77], v[142:145], v[192:195], v[74:77]
	v_mfma_f32_16x16x32_bf16 v[102:105], v[134:137], v[200:203], v[102:105]
	v_mfma_f32_16x16x32_bf16 v[70:73], v[142:145], v[200:203], v[70:73]
	v_mfma_f32_16x16x32_bf16 v[98:101], v[134:137], v[208:211], v[98:101]
	v_mfma_f32_16x16x32_bf16 v[66:69], v[142:145], v[208:211], v[66:69]
	s_setprio 0
	s_setprio 1
	v_mfma_f32_16x16x32_bf16 v[46:49], v[146:149], v[180:183], v[46:49]
	v_mfma_f32_16x16x32_bf16 v[14:17], v[154:157], v[180:183], v[14:17]
	v_mfma_f32_16x16x32_bf16 v[42:45], v[146:149], v[188:191], v[42:45]
	v_mfma_f32_16x16x32_bf16 v[10:13], v[154:157], v[188:191], v[10:13]
	v_mfma_f32_16x16x32_bf16 v[38:41], v[146:149], v[196:199], v[38:41]
	v_mfma_f32_16x16x32_bf16 v[6:9], v[154:157], v[196:199], v[6:9]
	v_mfma_f32_16x16x32_bf16 v[34:37], v[146:149], v[204:207], v[34:37]
	v_mfma_f32_16x16x32_bf16 v[2:5], v[154:157], v[204:207], v[2:5]
	v_mfma_f32_16x16x32_bf16 v[46:49], v[150:153], v[184:187], v[46:49]
	v_mfma_f32_16x16x32_bf16 v[14:17], v[158:161], v[184:187], v[14:17]
	v_mfma_f32_16x16x32_bf16 v[42:45], v[150:153], v[192:195], v[42:45]
	v_mfma_f32_16x16x32_bf16 v[10:13], v[158:161], v[192:195], v[10:13]
	v_mfma_f32_16x16x32_bf16 v[38:41], v[150:153], v[200:203], v[38:41]
	v_mfma_f32_16x16x32_bf16 v[6:9], v[158:161], v[200:203], v[6:9]
	v_mfma_f32_16x16x32_bf16 v[34:37], v[150:153], v[208:211], v[34:37]
	v_mfma_f32_16x16x32_bf16 v[2:5], v[158:161], v[208:211], v[2:5]
	s_setprio 0
	s_barrier
; #define PG8_STAGE(bufoff, gbase, voff) do { _Pragma("unroll") for (int _i = 0; _i < 2; ++_i) \
;         __builtin_amdgcn_global_load_lds((const unsigned*)((const char*)(gbase) + (voff)[_i]), (LAS unsigned*)(lds + (bufoff) + ldsw + _i * 8192), 16, 0, 0); } while (0)
; #define PG8_LDA(dst, b, h) do { _Pragma("unroll") for (int m = 0; m < 4; ++m) _Pragma("unroll") for (int k = 0; k < 2; ++k) dst[m][k] = *(const LAS bf16x8*)(lds + PG8_SA(b, h) + aoff + m * 2048 + k * 1024); } while (0)
; #define PG8_LDB(dst, b, h) do { _Pragma("unroll") for (int n = 0; n < 2; ++n) _Pragma("unroll") for (int k = 0; k < 2; ++k) dst[n][k] = *(const LAS bf16x8*)(lds + PG8_SB(b, h) + boff + n * 2048 + k * 1024); } while (0)
; #define PG8_MMA(ai, bj, At, Bt) do { __builtin_amdgcn_s_setprio(1); _Pragma("unroll") for (int m = 0; m < 4; ++m) _Pragma("unroll") for (int n = 0; n < 2; ++n) _Pragma("unroll") for (int k = 0; k < 2; ++k) \
;         acc[ai][bj][m][n] = __builtin_amdgcn_mfma_f32_16x16x32_bf16(Bt[n][k], At[m][k], acc[ai][bj][m][n], 0, 0, 0); __builtin_amdgcn_s_setprio(0); } while (0)
; #define PG8_WAIT_V(n) asm volatile("s_waitcnt vmcnt(" #n ")" ::: "memory")
; #define PG8_WAIT_L(n) asm volatile("s_waitcnt lgkmcnt(" #n ")" ::: "memory")
; #define PG8_BAR __builtin_amdgcn_s_barrier()
; #define PG8_SCHED __builtin_amdgcn_sched_barrier(0)
; template <class Epi, class Sched, bool ALIGN_EPI, class Hook = NoHook>
; __device__ __forceinline__ void gemm_phase(LAS unsigned char* lds, const Gemm g, const Sched& S, const Epi& E, const Hook& H = Hook()) {
;     ...
;             PG8_LDB(B0, 1, 0); PG8_LDB(B1, 1, 1); PG8_SCHED; PG8_LDA(At, 1, 0); PG8_STAGE(PG8_SA(0, 1), a2 + hA, voffA);
;             PG8_WAIT_V(8); PG8_WAIT_L(0); PG8_BAR; PG8_MMA(0, 0, At, B0); PG8_MMA(0, 1, At, B1); PG8_BAR; PG8_SCHED;
;             PG8_LDA(At, 1, 1); PG8_STAGE(PG8_SB(1, 0), b3, voffB); PG8_STAGE(PG8_SB(1, 1), b3 + hB, voffB); PG8_STAGE(PG8_SA(1, 0), a3, voffA);
;             PG8_WAIT_V(8); PG8_WAIT_L(0); PG8_BAR; PG8_MMA(1, 0, At, B0); PG8_MMA(1, 1, At, B1); PG8_BAR; PG8_SCHED;
;         }
	s_add_i32 s65, 0, 0x18000
	s_add_i32 s66, 0, 0x1c000
	v_add_u32_e32 v142, s65, v213
	v_add_u32_e32 v158, s66, v213
	ds_read_b128 v[130:133], v142
	ds_read_b128 v[134:137], v142 offset:1024
	s_add_u32 s4, s38, 0x8000
	s_addc_u32 s5, s39, 0
	s_mov_b32 m0, s42
	s_nop 0
	global_load_lds_dwordx4 v162, s[4:5]
	ds_read_b128 v[138:141], v142 offset:2048
	ds_read_b128 v[142:145], v142 offset:3072
	ds_read_b128 v[146:149], v158
	ds_read_b128 v[150:153], v158 offset:1024
	ds_read_b128 v[154:157], v158 offset:2048
	ds_read_b128 v[158:161], v158 offset:3072
	ds_read_b128 v[180:183], v219 offset:32768
	s_mov_b32 m0, s43
	s_nop 0
	global_load_lds_dwordx4 v166, s[4:5]
	ds_read_b128 v[184:187], v219 offset:33792
	ds_read_b128 v[188:191], v219 offset:34816
	ds_read_b128 v[192:195], v219 offset:35840
	ds_read_b128 v[196:199], v219 offset:36864
	ds_read_b128 v[200:203], v219 offset:37888
	ds_read_b128 v[204:207], v219 offset:38912
	ds_read_b128 v[208:211], v219 offset:39936
	s_waitcnt vmcnt(8)
	s_waitcnt lgkmcnt(0)
	s_barrier
	s_setprio 1
	s_waitcnt lgkmcnt(0)
	v_mfma_f32_16x16x32_bf16 v[126:129], v[130:133], v[180:183], v[126:129]
	v_mfma_f32_16x16x32_bf16 v[94:97], v[138:141], v[180:183], v[94:97]
	v_mfma_f32_16x16x32_bf16 v[122:125], v[130:133], v[188:191], v[122:125]
	v_mfma_f32_16x16x32_bf16 v[90:93], v[138:141], v[188:191], v[90:93]
	v_mfma_f32_16x16x32_bf16 v[118:121], v[130:133], v[196:199], v[118:121]
	v_mfma_f32_16x16x32_bf16 v[86:89], v[138:141], v[196:199], v[86:89]
	v_mfma_f32_16x16x32_bf16 v[114:117], v[130:133], v[204:207], v[114:117]
	v_mfma_f32_16x16x32_bf16 v[82:85], v[138:141], v[204:207], v[82:85]
	v_mfma_f32_16x16x32_bf16 v[126:129], v[134:137], v[184:187], v[126:129]
	v_mfma_f32_16x16x32_bf16 v[94:97], v[142:145], v[184:187], v[94:97]
	v_mfma_f32_16x16x32_bf16 v[122:125], v[134:137], v[192:195], v[122:125]
	v_mfma_f32_16x16x32_bf16 v[90:93], v[142:145], v[192:195], v[90:93]
	v_mfma_f32_16x16x32_bf16 v[118:121], v[134:137], v[200:203], v[118:121]
	v_mfma_f32_16x16x32_bf16 v[86:89], v[142:145], v[200:203], v[86:89]
	v_mfma_f32_16x16x32_bf16 v[114:117], v[134:137], v[208:211], v[114:117]
	v_mfma_f32_16x16x32_bf16 v[82:85], v[142:145], v[208:211], v[82:85]
	s_setprio 0
	s_setprio 1
	v_mfma_f32_16x16x32_bf16 v[62:65], v[146:149], v[180:183], v[62:65]
	v_mfma_f32_16x16x32_bf16 v[30:33], v[154:157], v[180:183], v[30:33]
	v_mfma_f32_16x16x32_bf16 v[58:61], v[146:149], v[188:191], v[58:61]
	v_mfma_f32_16x16x32_bf16 v[26:29], v[154:157], v[188:191], v[26:29]
	v_mfma_f32_16x16x32_bf16 v[54:57], v[146:149], v[196:199], v[54:57]
	v_mfma_f32_16x16x32_bf16 v[22:25], v[154:157], v[196:199], v[22:25]
	v_mfma_f32_16x16x32_bf16 v[50:53], v[146:149], v[204:207], v[50:53]
	v_mfma_f32_16x16x32_bf16 v[18:21], v[154:157], v[204:207], v[18:21]
	v_mfma_f32_16x16x32_bf16 v[62:65], v[150:153], v[184:187], v[62:65]
	v_mfma_f32_16x16x32_bf16 v[30:33], v[158:161], v[184:187], v[30:33]
	v_mfma_f32_16x16x32_bf16 v[58:61], v[150:153], v[192:195], v[58:61]
	v_mfma_f32_16x16x32_bf16 v[26:29], v[158:161], v[192:195], v[26:29]
	v_mfma_f32_16x16x32_bf16 v[54:57], v[150:153], v[200:203], v[54:57]
	v_mfma_f32_16x16x32_bf16 v[22:25], v[158:161], v[200:203], v[22:25]
	v_mfma_f32_16x16x32_bf16 v[50:53], v[150:153], v[208:211], v[50:53]
	v_mfma_f32_16x16x32_bf16 v[18:21], v[158:161], v[208:211], v[18:21]
	s_setprio 0
	s_barrier
	s_add_i32 s4, s65, s21
	s_add_u32 s68, s36, s14
	s_addc_u32 s69, s37, s15
	s_mov_b32 m0, s4
	ds_read_b128 v[180:183], v219 offset:49152
	ds_read_b128 v[184:187], v219 offset:50176
	global_load_lds_dwordx4 v164, s[68:69]
	ds_read_b128 v[188:191], v219 offset:51200
	s_add_i32 m0, s4, 0x2000
	s_add_u32 s4, s36, 0x100080
	s_addc_u32 s5, s37, 0
	s_add_i32 s36, s66, s21
	global_load_lds_dwordx4 v168, s[68:69]
	ds_read_b128 v[192:195], v219 offset:52224
	s_mov_b32 m0, s36
	s_nop 0
	global_load_lds_dwordx4 v164, s[4:5]
	ds_read_b128 v[196:199], v219 offset:53248
	s_add_i32 m0, s36, 0x2000
	s_nop 0
	global_load_lds_dwordx4 v168, s[4:5]
	ds_read_b128 v[200:203], v219 offset:54272
	s_add_u32 s70, s38, s14
	s_addc_u32 s71, s39, s15
	s_mov_b32 m0, s51
	s_nop 0
	global_load_lds_dwordx4 v162, s[70:71]
	ds_read_b128 v[204:207], v219 offset:55296
	s_mov_b32 m0, s52
	s_nop 0
	global_load_lds_dwordx4 v166, s[70:71]
	ds_read_b128 v[208:211], v219 offset:56320
	s_waitcnt vmcnt(8)
	s_waitcnt lgkmcnt(0)
	s_barrier
	s_setprio 1
	s_waitcnt lgkmcnt(0)
	v_mfma_f32_16x16x32_bf16 v[110:113], v[130:133], v[180:183], v[110:113]
	v_mfma_f32_16x16x32_bf16 v[78:81], v[138:141], v[180:183], v[78:81]
	v_mfma_f32_16x16x32_bf16 v[106:109], v[130:133], v[188:191], v[106:109]
	v_mfma_f32_16x16x32_bf16 v[74:77], v[138:141], v[188:191], v[74:77]
	v_mfma_f32_16x16x32_bf16 v[102:105], v[130:133], v[196:199], v[102:105]
	v_mfma_f32_16x16x32_bf16 v[70:73], v[138:141], v[196:199], v[70:73]
	v_mfma_f32_16x16x32_bf16 v[98:101], v[130:133], v[204:207], v[98:101]
	v_mfma_f32_16x16x32_bf16 v[66:69], v[138:141], v[204:207], v[66:69]
	v_mfma_f32_16x16x32_bf16 v[110:113], v[134:137], v[184:187], v[110:113]
	v_mfma_f32_16x16x32_bf16 v[78:81], v[142:145], v[184:187], v[78:81]
	v_mfma_f32_16x16x32_bf16 v[106:109], v[134:137], v[192:195], v[106:109]
	v_mfma_f32_16x16x32_bf16 v[74:77], v[142:145], v[192:195], v[74:77]
	v_mfma_f32_16x16x32_bf16 v[102:105], v[134:137], v[200:203], v[102:105]
	v_mfma_f32_16x16x32_bf16 v[70:73], v[142:145], v[200:203], v[70:73]
	v_mfma_f32_16x16x32_bf16 v[98:101], v[134:137], v[208:211], v[98:101]
	v_mfma_f32_16x16x32_bf16 v[66:69], v[142:145], v[208:211], v[66:69]
	s_setprio 0
	s_setprio 1
	v_mfma_f32_16x16x32_bf16 v[46:49], v[146:149], v[180:183], v[46:49]
	v_mfma_f32_16x16x32_bf16 v[14:17], v[154:157], v[180:183], v[14:17]
	v_mfma_f32_16x16x32_bf16 v[42:45], v[146:149], v[188:191], v[42:45]
	v_mfma_f32_16x16x32_bf16 v[10:13], v[154:157], v[188:191], v[10:13]
	v_mfma_f32_16x16x32_bf16 v[38:41], v[146:149], v[196:199], v[38:41]
	v_mfma_f32_16x16x32_bf16 v[6:9], v[154:157], v[196:199], v[6:9]
	v_mfma_f32_16x16x32_bf16 v[34:37], v[146:149], v[204:207], v[34:37]
	v_mfma_f32_16x16x32_bf16 v[2:5], v[154:157], v[204:207], v[2:5]
	v_mfma_f32_16x16x32_bf16 v[46:49], v[150:153], v[184:187], v[46:49]
	v_mfma_f32_16x16x32_bf16 v[14:17], v[158:161], v[184:187], v[14:17]
	v_mfma_f32_16x16x32_bf16 v[42:45], v[150:153], v[192:195], v[42:45]
	v_mfma_f32_16x16x32_bf16 v[10:13], v[158:161], v[192:195], v[10:13]
	v_mfma_f32_16x16x32_bf16 v[38:41], v[150:153], v[200:203], v[38:41]
	v_mfma_f32_16x16x32_bf16 v[6:9], v[158:161], v[200:203], v[6:9]
	v_mfma_f32_16x16x32_bf16 v[34:37], v[150:153], v[208:211], v[34:37]
	v_mfma_f32_16x16x32_bf16 v[2:5], v[158:161], v[208:211], v[2:5]
	s_setprio 0
	s_barrier
	s_add_i32 s64, s64, 2
	s_add_u32 s31, s31, 0x100
	s_addc_u32 s63, s63, 0
	s_cmp_gt_u32 s64, 61
	s_mov_b64 s[4:5], s[34:35]
	s_cbranch_scc0 .LBB0_199
	s_and_b64 vcc, exec, s[18:19]
	s_cbranch_vccz .LBB0_203
	s_barrier
	s_sub_i32 s4, s6, 32
	s_cmp_gt_u32 s4, 39
	s_mov_b64 s[4:5], -1
	s_cbranch_scc1 .LBB0_204

; #define PG8_STAGE(bufoff, gbase, voff) do { _Pragma("unroll") for (int _i = 0; _i < 2; ++_i) \
;         __builtin_amdgcn_global_load_lds((const unsigned*)((const char*)(gbase) + (voff)[_i]), (LAS unsigned*)(lds + (bufoff) + ldsw + _i * 8192), 16, 0, 0); } while (0)
; #define PG8_LDA(dst, b, h) do { _Pragma("unroll") for (int m = 0; m < 4; ++m) _Pragma("unroll") for (int k = 0; k < 2; ++k) dst[m][k] = *(const LAS bf16x8*)(lds + PG8_SA(b, h) + aoff + m * 2048 + k * 1024); } while (0)
; #define PG8_LDB(dst, b, h) do { _Pragma("unroll") for (int n = 0; n < 2; ++n) _Pragma("unroll") for (int k = 0; k < 2; ++k) dst[n][k] = *(const LAS bf16x8*)(lds + PG8_SB(b, h) + boff + n * 2048 + k * 1024); } while (0)
; #define PG8_MMA(ai, bj, At, Bt) do { __builtin_amdgcn_s_setprio(1); _Pragma("unroll") for (int m = 0; m < 4; ++m) _Pragma("unroll") for (int n = 0; n < 2; ++n) _Pragma("unroll") for (int k = 0; k < 2; ++k) \
;         acc[ai][bj][m][n] = __builtin_amdgcn_mfma_f32_16x16x32_bf16(Bt[n][k], At[m][k], acc[ai][bj][m][n], 0, 0, 0); __builtin_amdgcn_s_setprio(0); } while (0)
; #define PG8_WAIT_V(n) asm volatile("s_waitcnt vmcnt(" #n ")" ::: "memory")
; #define PG8_WAIT_L(n) asm volatile("s_waitcnt lgkmcnt(" #n ")" ::: "memory")
; #define PG8_BAR __builtin_amdgcn_s_barrier()
; #define PG8_SCHED __builtin_amdgcn_sched_barrier(0)
; template <class Epi, class Sched, bool ALIGN_EPI, class Hook = NoHook>
; __device__ __forceinline__ void gemm_phase(LAS unsigned char* lds, const Gemm g, const Sched& S, const Epi& E, const Hook& H = Hook()) {
;     ...
;             PG8_LDB(B0, 0, 0); PG8_LDB(B1, 0, 1); PG8_SCHED; PG8_LDA(At, 0, 0); PG8_STAGE(PG8_SA(1, 1), a1 + hA, voffA);
;             PG8_WAIT_V(8); PG8_WAIT_L(0); PG8_BAR; PG8_MMA(0, 0, At, B0); PG8_MMA(0, 1, At, B1); PG8_BAR; PG8_SCHED;
;             PG8_LDA(At, 0, 1); PG8_STAGE(PG8_SB(0, 0), b2, voffB); PG8_STAGE(PG8_SB(0, 1), b2 + hB, voffB); PG8_STAGE(PG8_SA(0, 0), a2, voffA);
;             PG8_WAIT_V(8); PG8_WAIT_L(0); PG8_BAR; PG8_MMA(1, 0, At, B0); PG8_MMA(1, 1, At, B1); PG8_BAR; PG8_SCHED;
.LBB0_262:
	ds_read_b128 v[148:151], v145
	ds_read_b128 v[152:155], v145 offset:1024
	s_add_u32 s22, s20, 0xfff00080
	s_addc_u32 s23, s21, -1
	s_cmp_eq_u32 s50, 4
	s_cselect_b32 s25, s11, s23
	s_cselect_b32 s24, s13, s22
	s_cselect_b32 s23, s40, s43
	s_cselect_b32 s22, s41, s42
	s_add_i32 m0, s5, 0xc000
	s_nop 0
	global_load_lds_dwordx4 v136, s[20:21]
	ds_read_b128 v[156:159], v145 offset:2048
	ds_read_b128 v[160:163], v145 offset:3072
	ds_read_b128 v[164:167], v146
	ds_read_b128 v[168:171], v146 offset:1024
	ds_read_b128 v[172:175], v146 offset:2048
	ds_read_b128 v[176:179], v146 offset:3072
	ds_read_b128 v[180:183], v147
	s_add_i32 m0, s5, 0xe000
	s_nop 0
	global_load_lds_dwordx4 v138, s[20:21]
	ds_read_b128 v[184:187], v147 offset:1024
	ds_read_b128 v[188:191], v147 offset:2048
	ds_read_b128 v[192:195], v147 offset:3072
	ds_read_b128 v[196:199], v147 offset:4096
	ds_read_b128 v[200:203], v147 offset:5120
	ds_read_b128 v[204:207], v147 offset:6144
	ds_read_b128 v[208:211], v147 offset:7168
	s_waitcnt vmcnt(8)
	s_waitcnt lgkmcnt(0)
	s_barrier
	s_setprio 1
	s_waitcnt lgkmcnt(0)
	v_mfma_f32_16x16x32_bf16 v[126:129], v[148:151], v[180:183], v[126:129]
	v_mfma_f32_16x16x32_bf16 v[122:125], v[156:159], v[180:183], v[122:125]
	v_mfma_f32_16x16x32_bf16 v[118:121], v[148:151], v[188:191], v[118:121]
	v_mfma_f32_16x16x32_bf16 v[114:117], v[156:159], v[188:191], v[114:117]
	v_mfma_f32_16x16x32_bf16 v[106:109], v[148:151], v[196:199], v[106:109]
	v_mfma_f32_16x16x32_bf16 v[98:101], v[156:159], v[196:199], v[98:101]
	v_mfma_f32_16x16x32_bf16 v[90:93], v[148:151], v[204:207], v[90:93]
	v_mfma_f32_16x16x32_bf16 v[82:85], v[156:159], v[204:207], v[82:85]
	v_mfma_f32_16x16x32_bf16 v[126:129], v[152:155], v[184:187], v[126:129]
	v_mfma_f32_16x16x32_bf16 v[122:125], v[160:163], v[184:187], v[122:125]
	v_mfma_f32_16x16x32_bf16 v[118:121], v[152:155], v[192:195], v[118:121]
	v_mfma_f32_16x16x32_bf16 v[114:117], v[160:163], v[192:195], v[114:117]
	v_mfma_f32_16x16x32_bf16 v[106:109], v[152:155], v[200:203], v[106:109]
	v_mfma_f32_16x16x32_bf16 v[98:101], v[160:163], v[200:203], v[98:101]
	v_mfma_f32_16x16x32_bf16 v[90:93], v[152:155], v[208:211], v[90:93]
	v_mfma_f32_16x16x32_bf16 v[82:85], v[160:163], v[208:211], v[82:85]
	s_setprio 0
	s_setprio 1
	v_mfma_f32_16x16x32_bf16 v[110:113], v[164:167], v[180:183], v[110:113]
	v_mfma_f32_16x16x32_bf16 v[102:105], v[172:175], v[180:183], v[102:105]
	v_mfma_f32_16x16x32_bf16 v[94:97], v[164:167], v[188:191], v[94:97]
	v_mfma_f32_16x16x32_bf16 v[86:89], v[172:175], v[188:191], v[86:89]
	v_mfma_f32_16x16x32_bf16 v[78:81], v[164:167], v[196:199], v[78:81]
	v_mfma_f32_16x16x32_bf16 v[74:77], v[172:175], v[196:199], v[74:77]
	v_mfma_f32_16x16x32_bf16 v[70:73], v[164:167], v[204:207], v[70:73]
	v_mfma_f32_16x16x32_bf16 v[66:69], v[172:175], v[204:207], v[66:69]
	v_mfma_f32_16x16x32_bf16 v[110:113], v[168:171], v[184:187], v[110:113]
	v_mfma_f32_16x16x32_bf16 v[102:105], v[176:179], v[184:187], v[102:105]
	v_mfma_f32_16x16x32_bf16 v[94:97], v[168:171], v[192:195], v[94:97]
	v_mfma_f32_16x16x32_bf16 v[86:89], v[176:179], v[192:195], v[86:89]
	v_mfma_f32_16x16x32_bf16 v[78:81], v[168:171], v[200:203], v[78:81]
	v_mfma_f32_16x16x32_bf16 v[74:77], v[176:179], v[200:203], v[74:77]
	v_mfma_f32_16x16x32_bf16 v[70:73], v[168:171], v[208:211], v[70:73]
	v_mfma_f32_16x16x32_bf16 v[66:69], v[176:179], v[208:211], v[66:69]
	s_setprio 0
	s_barrier
	s_add_i32 s51, s38, s29
	s_mov_b32 m0, s51
	ds_read_b128 v[180:183], v147 offset:16384
	ds_read_b128 v[184:187], v147 offset:17408
	global_load_lds_dwordx4 v132, s[22:23]
	ds_read_b128 v[188:191], v147 offset:18432
	s_add_i32 m0, s51, 0x2000
	s_add_u32 s52, s22, 0x100000
	s_addc_u32 s53, s23, 0
	s_add_i32 s51, s39, s29
	global_load_lds_dwordx4 v130, s[22:23]
	ds_read_b128 v[192:195], v147 offset:19456
	s_mov_b32 m0, s51
	s_nop 0
	global_load_lds_dwordx4 v132, s[52:53]
	ds_read_b128 v[196:199], v147 offset:20480
	s_add_i32 m0, s51, 0x2000
	s_nop 0
	global_load_lds_dwordx4 v130, s[52:53]
	ds_read_b128 v[200:203], v147 offset:21504
	s_add_u32 s56, s24, s8
	s_addc_u32 s57, s25, s9
	s_mov_b32 m0, s5
	s_nop 0
	global_load_lds_dwordx4 v132, s[24:25]
	ds_read_b128 v[204:207], v147 offset:22528
	s_mov_b32 m0, s7
	s_nop 0
	global_load_lds_dwordx4 v130, s[24:25]
	ds_read_b128 v[208:211], v147 offset:23552
	s_waitcnt vmcnt(8)
	s_waitcnt lgkmcnt(0)
	s_barrier
	s_setprio 1
	s_waitcnt lgkmcnt(0)
	v_mfma_f32_16x16x32_bf16 v[62:65], v[148:151], v[180:183], v[62:65]
	v_mfma_f32_16x16x32_bf16 v[58:61], v[156:159], v[180:183], v[58:61]
	v_mfma_f32_16x16x32_bf16 v[54:57], v[148:151], v[188:191], v[54:57]
	v_mfma_f32_16x16x32_bf16 v[50:53], v[156:159], v[188:191], v[50:53]
	v_mfma_f32_16x16x32_bf16 v[38:41], v[148:151], v[196:199], v[38:41]
	v_mfma_f32_16x16x32_bf16 v[34:37], v[156:159], v[196:199], v[34:37]
	v_mfma_f32_16x16x32_bf16 v[22:25], v[148:151], v[204:207], v[22:25]
	v_mfma_f32_16x16x32_bf16 v[18:21], v[156:159], v[204:207], v[18:21]
	v_mfma_f32_16x16x32_bf16 v[62:65], v[152:155], v[184:187], v[62:65]
	v_mfma_f32_16x16x32_bf16 v[58:61], v[160:163], v[184:187], v[58:61]
	v_mfma_f32_16x16x32_bf16 v[54:57], v[152:155], v[192:195], v[54:57]
	v_mfma_f32_16x16x32_bf16 v[50:53], v[160:163], v[192:195], v[50:53]
	v_mfma_f32_16x16x32_bf16 v[38:41], v[152:155], v[200:203], v[38:41]
	v_mfma_f32_16x16x32_bf16 v[34:37], v[160:163], v[200:203], v[34:37]
	v_mfma_f32_16x16x32_bf16 v[22:25], v[152:155], v[208:211], v[22:25]
	v_mfma_f32_16x16x32_bf16 v[18:21], v[160:163], v[208:211], v[18:21]
	s_setprio 0
	s_setprio 1
	v_mfma_f32_16x16x32_bf16 v[46:49], v[164:167], v[180:183], v[46:49]
	v_mfma_f32_16x16x32_bf16 v[42:45], v[172:175], v[180:183], v[42:45]
	v_mfma_f32_16x16x32_bf16 v[30:33], v[164:167], v[188:191], v[30:33]
	v_mfma_f32_16x16x32_bf16 v[26:29], v[172:175], v[188:191], v[26:29]
	v_mfma_f32_16x16x32_bf16 v[14:17], v[164:167], v[196:199], v[14:17]
	v_mfma_f32_16x16x32_bf16 v[10:13], v[172:175], v[196:199], v[10:13]
	v_mfma_f32_16x16x32_bf16 v[6:9], v[164:167], v[204:207], v[6:9]
	v_mfma_f32_16x16x32_bf16 v[2:5], v[172:175], v[204:207], v[2:5]
	v_mfma_f32_16x16x32_bf16 v[46:49], v[168:171], v[184:187], v[46:49]
	v_mfma_f32_16x16x32_bf16 v[42:45], v[176:179], v[184:187], v[42:45]
	v_mfma_f32_16x16x32_bf16 v[30:33], v[168:171], v[192:195], v[30:33]
	v_mfma_f32_16x16x32_bf16 v[26:29], v[176:179], v[192:195], v[26:29]
	v_mfma_f32_16x16x32_bf16 v[14:17], v[168:171], v[200:203], v[14:17]
	v_mfma_f32_16x16x32_bf16 v[10:13], v[176:179], v[200:203], v[10:13]
	v_mfma_f32_16x16x32_bf16 v[6:9], v[168:171], v[208:211], v[6:9]
	v_mfma_f32_16x16x32_bf16 v[2:5], v[176:179], v[208:211], v[2:5]
	s_setprio 0
	s_barrier
; #define PG8_STAGE(bufoff, gbase, voff) do { _Pragma("unroll") for (int _i = 0; _i < 2; ++_i) \
;         __builtin_amdgcn_global_load_lds((const unsigned*)((const char*)(gbase) + (voff)[_i]), (LAS unsigned*)(lds + (bufoff) + ldsw + _i * 8192), 16, 0, 0); } while (0)
; #define PG8_LDA(dst, b, h) do { _Pragma("unroll") for (int m = 0; m < 4; ++m) _Pragma("unroll") for (int k = 0; k < 2; ++k) dst[m][k] = *(const LAS bf16x8*)(lds + PG8_SA(b, h) + aoff + m * 2048 + k * 1024); } while (0)
; #define PG8_LDB(dst, b, h) do { _Pragma("unroll") for (int n = 0; n < 2; ++n) _Pragma("unroll") for (int k = 0; k < 2; ++k) dst[n][k] = *(const LAS bf16x8*)(lds + PG8_SB(b, h) + boff + n * 2048 + k * 1024); } while (0)
; #define PG8_MMA(ai, bj, At, Bt) do { __builtin_amdgcn_s_setprio(1); _Pragma("unroll") for (int m = 0; m < 4; ++m) _Pragma("unroll") for (int n = 0; n < 2; ++n) _Pragma("unroll") for (int k = 0; k < 2; ++k) \
;         acc[ai][bj][m][n] = __builtin_amdgcn_mfma_f32_16x16x32_bf16(Bt[n][k], At[m][k], acc[ai][bj][m][n], 0, 0, 0); __builtin_amdgcn_s_setprio(0); } while (0)
; #define PG8_WAIT_V(n) asm volatile("s_waitcnt vmcnt(" #n ")" ::: "memory")
; #define PG8_WAIT_L(n) asm volatile("s_waitcnt lgkmcnt(" #n ")" ::: "memory")
; #define PG8_BAR __builtin_amdgcn_s_barrier()
; #define PG8_SCHED __builtin_amdgcn_sched_barrier(0)
; template <class Epi, class Sched, bool ALIGN_EPI, class Hook = NoHook>
; __device__ __forceinline__ void gemm_phase(LAS unsigned char* lds, const Gemm g, const Sched& S, const Epi& E, const Hook& H = Hook()) {
;     ...
;             PG8_LDB(B0, 1, 0); PG8_LDB(B1, 1, 1); PG8_SCHED; PG8_LDA(At, 1, 0); PG8_STAGE(PG8_SA(0, 1), a2 + hA, voffA);
;             PG8_WAIT_V(8); PG8_WAIT_L(0); PG8_BAR; PG8_MMA(0, 0, At, B0); PG8_MMA(0, 1, At, B1); PG8_BAR; PG8_SCHED;
;             PG8_LDA(At, 1, 1); PG8_STAGE(PG8_SB(1, 0), b3, voffB); PG8_STAGE(PG8_SB(1, 1), b3 + hB, voffB); PG8_STAGE(PG8_SA(1, 0), a3, voffA);
	s_add_i32 s51, 0, 0x18000
	s_add_i32 s52, 0, 0x1c000
	v_add_u32_e32 v160, s51, v144
	v_add_u32_e32 v176, s52, v144
	ds_read_b128 v[148:151], v160
	ds_read_b128 v[152:155], v160 offset:1024
	s_add_u32 s24, s24, 0x100000
	s_addc_u32 s25, s25, 0
	s_mov_b32 m0, s30
	s_nop 0
	global_load_lds_dwordx4 v132, s[24:25]
	ds_read_b128 v[156:159], v160 offset:2048
	ds_read_b128 v[160:163], v160 offset:3072
	ds_read_b128 v[164:167], v176
	ds_read_b128 v[168:171], v176 offset:1024
	ds_read_b128 v[172:175], v176 offset:2048
	ds_read_b128 v[176:179], v176 offset:3072
	ds_read_b128 v[180:183], v147 offset:32768
	s_mov_b32 m0, s31
	s_nop 0
	global_load_lds_dwordx4 v130, s[24:25]
	ds_read_b128 v[184:187], v147 offset:33792
	ds_read_b128 v[188:191], v147 offset:34816
	ds_read_b128 v[192:195], v147 offset:35840
	ds_read_b128 v[196:199], v147 offset:36864
	ds_read_b128 v[200:203], v147 offset:37888
	ds_read_b128 v[204:207], v147 offset:38912
	ds_read_b128 v[208:211], v147 offset:39936
	s_waitcnt vmcnt(8)
	s_waitcnt lgkmcnt(0)
	s_barrier
	s_setprio 1
	s_waitcnt lgkmcnt(0)
	v_mfma_f32_16x16x32_bf16 v[126:129], v[148:151], v[180:183], v[126:129]
	v_mfma_f32_16x16x32_bf16 v[122:125], v[156:159], v[180:183], v[122:125]
	v_mfma_f32_16x16x32_bf16 v[118:121], v[148:151], v[188:191], v[118:121]
	v_mfma_f32_16x16x32_bf16 v[114:117], v[156:159], v[188:191], v[114:117]
	v_mfma_f32_16x16x32_bf16 v[106:109], v[148:151], v[196:199], v[106:109]
	v_mfma_f32_16x16x32_bf16 v[98:101], v[156:159], v[196:199], v[98:101]
	v_mfma_f32_16x16x32_bf16 v[90:93], v[148:151], v[204:207], v[90:93]
	v_mfma_f32_16x16x32_bf16 v[82:85], v[156:159], v[204:207], v[82:85]
	v_mfma_f32_16x16x32_bf16 v[126:129], v[152:155], v[184:187], v[126:129]
	v_mfma_f32_16x16x32_bf16 v[122:125], v[160:163], v[184:187], v[122:125]
	v_mfma_f32_16x16x32_bf16 v[118:121], v[152:155], v[192:195], v[118:121]
	v_mfma_f32_16x16x32_bf16 v[114:117], v[160:163], v[192:195], v[114:117]
	v_mfma_f32_16x16x32_bf16 v[106:109], v[152:155], v[200:203], v[106:109]
	v_mfma_f32_16x16x32_bf16 v[98:101], v[160:163], v[200:203], v[98:101]
	v_mfma_f32_16x16x32_bf16 v[90:93], v[152:155], v[208:211], v[90:93]
	v_mfma_f32_16x16x32_bf16 v[82:85], v[160:163], v[208:211], v[82:85]
	s_setprio 0
	s_setprio 1
	v_mfma_f32_16x16x32_bf16 v[110:113], v[164:167], v[180:183], v[110:113]
	v_mfma_f32_16x16x32_bf16 v[102:105], v[172:175], v[180:183], v[102:105]
	v_mfma_f32_16x16x32_bf16 v[94:97], v[164:167], v[188:191], v[94:97]
	v_mfma_f32_16x16x32_bf16 v[86:89], v[172:175], v[188:191], v[86:89]
	v_mfma_f32_16x16x32_bf16 v[78:81], v[164:167], v[196:199], v[78:81]
	v_mfma_f32_16x16x32_bf16 v[74:77], v[172:175], v[196:199], v[74:77]
	v_mfma_f32_16x16x32_bf16 v[70:73], v[164:167], v[204:207], v[70:73]
	v_mfma_f32_16x16x32_bf16 v[66:69], v[172:175], v[204:207], v[66:69]
	v_mfma_f32_16x16x32_bf16 v[110:113], v[168:171], v[184:187], v[110:113]
	v_mfma_f32_16x16x32_bf16 v[102:105], v[176:179], v[184:187], v[102:105]
	v_mfma_f32_16x16x32_bf16 v[94:97], v[168:171], v[192:195], v[94:97]
	v_mfma_f32_16x16x32_bf16 v[86:89], v[176:179], v[192:195], v[86:89]
	v_mfma_f32_16x16x32_bf16 v[78:81], v[168:171], v[200:203], v[78:81]
	v_mfma_f32_16x16x32_bf16 v[74:77], v[176:179], v[200:203], v[74:77]
	v_mfma_f32_16x16x32_bf16 v[70:73], v[168:171], v[208:211], v[70:73]
	v_mfma_f32_16x16x32_bf16 v[66:69], v[176:179], v[208:211], v[66:69]
	s_setprio 0
	s_barrier
	s_add_i32 s24, s51, s29
	s_add_u32 s54, s22, s8
	s_addc_u32 s55, s23, s9
	s_mov_b32 m0, s24
	ds_read_b128 v[180:183], v147 offset:49152
	ds_read_b128 v[184:187], v147 offset:50176
	global_load_lds_dwordx4 v132, s[54:55]
	ds_read_b128 v[188:191], v147 offset:51200
	s_add_i32 m0, s24, 0x2000
	s_add_u32 s22, s22, 0x100080
	s_addc_u32 s23, s23, 0
	s_add_i32 s24, s52, s29
	global_load_lds_dwordx4 v130, s[54:55]
	ds_read_b128 v[192:195], v147 offset:52224
	s_mov_b32 m0, s24
	s_nop 0
	global_load_lds_dwordx4 v132, s[22:23]
	ds_read_b128 v[196:199], v147 offset:53248
	s_add_i32 m0, s24, 0x2000
	s_nop 0
	global_load_lds_dwordx4 v130, s[22:23]
	ds_read_b128 v[200:203], v147 offset:54272
	s_mov_b32 m0, s35
	s_nop 0
	global_load_lds_dwordx4 v132, s[56:57]
	ds_read_b128 v[204:207], v147 offset:55296
	s_mov_b32 m0, s36
	s_nop 0
	global_load_lds_dwordx4 v130, s[56:57]
	ds_read_b128 v[208:211], v147 offset:56320
	s_waitcnt vmcnt(8)
	s_waitcnt lgkmcnt(0)
	s_barrier
; #define PG8_MMA(ai, bj, At, Bt) do { __builtin_amdgcn_s_setprio(1); _Pragma("unroll") for (int m = 0; m < 4; ++m) _Pragma("unroll") for (int n = 0; n < 2; ++n) _Pragma("unroll") for (int k = 0; k < 2; ++k) \
;         acc[ai][bj][m][n] = __builtin_amdgcn_mfma_f32_16x16x32_bf16(Bt[n][k], At[m][k], acc[ai][bj][m][n], 0, 0, 0); __builtin_amdgcn_s_setprio(0); } while (0)
; #define PG8_WAIT_V(n) asm volatile("s_waitcnt vmcnt(" #n ")" ::: "memory")
; #define PG8_WAIT_L(n) asm volatile("s_waitcnt lgkmcnt(" #n ")" ::: "memory")
; #define PG8_BAR __builtin_amdgcn_s_barrier()
; #define PG8_SCHED __builtin_amdgcn_sched_barrier(0)
;     __device__ __forceinline__ void operator()(const f32x4 (&acc)[2][2][4][2], const Unit& u, int wr, int wc, int fr, int fq) const {
;         float* base = C + (size_t)(u.ka / kslab) * slab_stride;
;         const int row0 = u.pm * BM + wr * 64 + fr, col0 = wc * 32 + 4 * fq;
; #pragma unroll
;         for (int ai = 0; ai < 2; ++ai)
; #pragma unroll
;             for (int m = 0; m < 4; ++m) { float* rowp = base + (size_t)(row0 + ai * HALF + m * 16) * 256 + col0;
; #pragma unroll
;                 for (int bj = 0; bj < 2; ++bj)
; #pragma unroll
;                     for (int n = 0; n < 2; ++n) *(f32x4*)(rowp + bj * HALF + n * 16) = acc[ai][bj][m][n]; }
;     }
; template <class Epi, class Sched, bool ALIGN_EPI, class Hook = NoHook>
; __device__ __forceinline__ void gemm_phase(LAS unsigned char* lds, const Gemm g, const Sched& S, const Epi& E, const Hook& H = Hook()) {
;     ...
;             PG8_WAIT_V(8); PG8_WAIT_L(0); PG8_BAR; PG8_MMA(1, 0, At, B0); PG8_MMA(1, 1, At, B1); PG8_BAR; PG8_SCHED;
;         }
;         if constexpr (Hook::ON) H.after(te, acc, cur, wr, wc, fr, fq);
;         }
;         if constexpr (ALIGN_EPI) { if (wr == 0) PG8_BAR; }
;         if constexpr (!Epi::AFTER_DRAIN) { E(acc, cur, wr, wc, fr, fq); S.done(cur); }
	s_setprio 1
	s_waitcnt lgkmcnt(0)
	v_mfma_f32_16x16x32_bf16 v[62:65], v[148:151], v[180:183], v[62:65]
	v_mfma_f32_16x16x32_bf16 v[58:61], v[156:159], v[180:183], v[58:61]
	v_mfma_f32_16x16x32_bf16 v[54:57], v[148:151], v[188:191], v[54:57]
	v_mfma_f32_16x16x32_bf16 v[50:53], v[156:159], v[188:191], v[50:53]
	v_mfma_f32_16x16x32_bf16 v[38:41], v[148:151], v[196:199], v[38:41]
	v_mfma_f32_16x16x32_bf16 v[34:37], v[156:159], v[196:199], v[34:37]
	v_mfma_f32_16x16x32_bf16 v[22:25], v[148:151], v[204:207], v[22:25]
	v_mfma_f32_16x16x32_bf16 v[18:21], v[156:159], v[204:207], v[18:21]
	v_mfma_f32_16x16x32_bf16 v[62:65], v[152:155], v[184:187], v[62:65]
	v_mfma_f32_16x16x32_bf16 v[58:61], v[160:163], v[184:187], v[58:61]
	v_mfma_f32_16x16x32_bf16 v[54:57], v[152:155], v[192:195], v[54:57]
	v_mfma_f32_16x16x32_bf16 v[50:53], v[160:163], v[192:195], v[50:53]
	v_mfma_f32_16x16x32_bf16 v[38:41], v[152:155], v[200:203], v[38:41]
	v_mfma_f32_16x16x32_bf16 v[34:37], v[160:163], v[200:203], v[34:37]
	v_mfma_f32_16x16x32_bf16 v[22:25], v[152:155], v[208:211], v[22:25]
	v_mfma_f32_16x16x32_bf16 v[18:21], v[160:163], v[208:211], v[18:21]
	s_setprio 0
	s_setprio 1
	v_mfma_f32_16x16x32_bf16 v[46:49], v[164:167], v[180:183], v[46:49]
	v_mfma_f32_16x16x32_bf16 v[42:45], v[172:175], v[180:183], v[42:45]
	v_mfma_f32_16x16x32_bf16 v[30:33], v[164:167], v[188:191], v[30:33]
	v_mfma_f32_16x16x32_bf16 v[26:29], v[172:175], v[188:191], v[26:29]
	v_mfma_f32_16x16x32_bf16 v[14:17], v[164:167], v[196:199], v[14:17]
	v_mfma_f32_16x16x32_bf16 v[10:13], v[172:175], v[196:199], v[10:13]
	v_mfma_f32_16x16x32_bf16 v[6:9], v[164:167], v[204:207], v[6:9]
	v_mfma_f32_16x16x32_bf16 v[2:5], v[172:175], v[204:207], v[2:5]
	v_mfma_f32_16x16x32_bf16 v[46:49], v[168:171], v[184:187], v[46:49]
	v_mfma_f32_16x16x32_bf16 v[42:45], v[176:179], v[184:187], v[42:45]
	v_mfma_f32_16x16x32_bf16 v[30:33], v[168:171], v[192:195], v[30:33]
	v_mfma_f32_16x16x32_bf16 v[26:29], v[176:179], v[192:195], v[26:29]
	v_mfma_f32_16x16x32_bf16 v[14:17], v[168:171], v[200:203], v[14:17]
	v_mfma_f32_16x16x32_bf16 v[10:13], v[176:179], v[200:203], v[10:13]
	v_mfma_f32_16x16x32_bf16 v[6:9], v[168:171], v[208:211], v[6:9]
	v_mfma_f32_16x16x32_bf16 v[2:5], v[176:179], v[208:211], v[2:5]
	s_setprio 0
	s_barrier
	s_add_i32 s50, s50, 2
	s_add_u32 s20, s20, 0x100
	s_addc_u32 s21, s21, 0
	s_add_u32 s42, s42, 0x100
	s_addc_u32 s43, s43, 0
	s_cmp_gt_u32 s50, 5
	s_cbranch_scc0 .LBB0_262
	s_ashr_i32 s11, s6, 31
	s_lshr_b32 s11, s11, 23
	s_add_i32 s6, s6, s11
	s_ashr_i32 s20, s6, 9
	s_ashr_i32 s21, s20, 31
	v_lshl_add_u32 v148, s4, 8, v1
	s_lshl_b64 s[20:21], s[20:21], 23
	v_ashrrev_i32_e32 v149, 31, v148
	v_lshl_add_u64 v[150:151], v[134:135], 0, s[20:21]
	v_lshlrev_b64 v[152:153], 10, v[148:149]
	v_lshl_add_u64 v[152:153], v[150:151], 0, v[152:153]
	global_store_dwordx4 v[152:153], v[126:129], off
	global_store_dwordx4 v[152:153], v[122:125], off offset:64
	global_store_dwordx4 v[152:153], v[110:113], off offset:512
	global_store_dwordx4 v[152:153], v[102:105], off offset:576
	s_mov_b32 s4, 0x20000
	s_mov_b64 s[20:21], 0x20000
	v_or_b32_e32 v102, 16, v148
	v_ashrrev_i32_e32 v103, 31, v102
	v_lshlrev_b64 v[102:103], 10, v[102:103]
	v_lshl_add_u64 v[102:103], v[150:151], 0, v[102:103]
	global_store_dwordx4 v[102:103], v[118:121], off
	global_store_dwordx4 v[102:103], v[114:117], off offset:64
	global_store_dwordx4 v[102:103], v[94:97], off offset:512
	global_store_dwordx4 v[102:103], v[86:89], off offset:576
	s_mov_b32 s6, s12
	s_mov_b64 s[22:23], s[18:19]
	v_or_b32_e32 v86, 32, v148
	v_ashrrev_i32_e32 v87, 31, v86
	v_lshlrev_b64 v[86:87], 10, v[86:87]
	v_lshl_add_u64 v[86:87], v[150:151], 0, v[86:87]
	global_store_dwordx4 v[86:87], v[106:109], off
	global_store_dwordx4 v[86:87], v[98:101], off offset:64
	global_store_dwordx4 v[86:87], v[78:81], off offset:512
	global_store_dwordx4 v[86:87], v[74:77], off offset:576
	s_nop 1
	v_or_b32_e32 v74, 48, v148
	v_ashrrev_i32_e32 v75, 31, v74
	v_lshlrev_b64 v[74:75], 10, v[74:75]
	v_lshl_add_u64 v[74:75], v[150:151], 0, v[74:75]
	global_store_dwordx4 v[74:75], v[90:93], off
	global_store_dwordx4 v[74:75], v[82:85], off offset:64
	global_store_dwordx4 v[74:75], v[70:73], off offset:512
	global_store_dwordx4 v[74:75], v[66:69], off offset:576
	s_nop 1
	v_add_co_u32_e32 v68, vcc, s4, v152
	s_mov_b32 s4, 0x24000
	s_nop 0
	v_addc_co_u32_e32 v69, vcc, 0, v153, vcc
	v_lshl_add_u64 v[66:67], v[152:153], 0, s[20:21]
	global_store_dwordx4 v[68:69], v[62:65], off
	global_store_dwordx4 v[66:67], v[58:61], off offset:64
	global_store_dwordx4 v[66:67], v[46:49], off offset:512
	global_store_dwordx4 v[66:67], v[42:45], off offset:576
	s_mov_b64 s[20:21], 0x24000
	s_nop 0
	v_add_co_u32_e32 v44, vcc, s4, v152
	s_mov_b32 s4, 0x28000
	s_nop 0
	v_addc_co_u32_e32 v45, vcc, 0, v153, vcc
	v_lshl_add_u64 v[42:43], v[152:153], 0, s[20:21]
	global_store_dwordx4 v[44:45], v[54:57], off
	global_store_dwordx4 v[42:43], v[50:53], off offset:64
	global_store_dwordx4 v[42:43], v[30:33], off offset:512
	global_store_dwordx4 v[42:43], v[26:29], off offset:576
	s_mov_b64 s[20:21], 0x28000
	s_nop 0
	v_add_co_u32_e32 v28, vcc, s4, v152
	v_lshl_add_u64 v[26:27], v[152:153], 0, s[20:21]
	s_nop 0
	v_addc_co_u32_e32 v29, vcc, 0, v153, vcc
	global_store_dwordx4 v[28:29], v[38:41], off
	global_store_dwordx4 v[26:27], v[34:37], off offset:64
	global_store_dwordx4 v[26:27], v[14:17], off offset:512
	global_store_dwordx4 v[26:27], v[10:13], off offset:576
	s_mov_b64 s[20:21], 0x2c000
	s_mov_b32 s4, s10
	v_add_co_u32_e32 v12, vcc, 0x2c000, v152
	v_lshl_add_u64 v[10:11], v[152:153], 0, s[20:21]
	s_nop 0
	v_addc_co_u32_e32 v13, vcc, 0, v153, vcc
	s_and_b64 vcc, exec, s[2:3]
	s_mov_b64 s[20:21], s[14:15]
	global_store_dwordx4 v[12:13], v[22:25], off
	global_store_dwordx4 v[10:11], v[18:21], off offset:64
	global_store_dwordx4 v[10:11], v[6:9], off offset:512
	global_store_dwordx4 v[10:11], v[2:5], off offset:576
	s_cbranch_vccz .LBB0_259
	s_waitcnt vmcnt(0)
	s_cmpk_gt_u32 s26, 0xff
	s_cbranch_scc1 .LBB0_266
	s_barrier

; #define PG8_STAGE(bufoff, gbase, voff) do { _Pragma("unroll") for (int _i = 0; _i < 2; ++_i) \
;         __builtin_amdgcn_global_load_lds((const unsigned*)((const char*)(gbase) + (voff)[_i]), (LAS unsigned*)(lds + (bufoff) + ldsw + _i * 8192), 16, 0, 0); } while (0)
; #define PG8_LDA(dst, b, h) do { _Pragma("unroll") for (int m = 0; m < 4; ++m) _Pragma("unroll") for (int k = 0; k < 2; ++k) dst[m][k] = *(const LAS bf16x8*)(lds + PG8_SA(b, h) + aoff + m * 2048 + k * 1024); } while (0)
; #define PG8_LDB(dst, b, h) do { _Pragma("unroll") for (int n = 0; n < 2; ++n) _Pragma("unroll") for (int k = 0; k < 2; ++k) dst[n][k] = *(const LAS bf16x8*)(lds + PG8_SB(b, h) + boff + n * 2048 + k * 1024); } while (0)
; #define PG8_MMA(ai, bj, At, Bt) do { __builtin_amdgcn_s_setprio(1); _Pragma("unroll") for (int m = 0; m < 4; ++m) _Pragma("unroll") for (int n = 0; n < 2; ++n) _Pragma("unroll") for (int k = 0; k < 2; ++k) \
;         acc[ai][bj][m][n] = __builtin_amdgcn_mfma_f32_16x16x32_bf16(Bt[n][k], At[m][k], acc[ai][bj][m][n], 0, 0, 0); __builtin_amdgcn_s_setprio(0); } while (0)
; #define PG8_WAIT_V(n) asm volatile("s_waitcnt vmcnt(" #n ")" ::: "memory")
; #define PG8_WAIT_L(n) asm volatile("s_waitcnt lgkmcnt(" #n ")" ::: "memory")
; template <class Epi, class Sched, bool ALIGN_EPI, class Hook = NoHook>
; __device__ __forceinline__ void gemm_phase(LAS unsigned char* lds, const Gemm g, const Sched& S, const Epi& E, const Hook& H = Hook()) {
;     ...
;         for (int t = tb; t < te; t += 2) {
;             const bool last = (t == nt - 2);
;             const char* a1 = cA + (size_t)(t + 1) * kstep;
;             const char* a2 = last ? nA : cA + (size_t)(t + 2) * kstep; const char* b2 = last ? nB : cB + (size_t)(t + 2) * kstep;
;             const char* a3 = a2 + kstep; const char* b3 = b2 + kstep;
;             if (last && has_next) S.a_ready(nxt);
;             PG8_LDB(B0, 0, 0); PG8_LDB(B1, 0, 1); PG8_SCHED; PG8_LDA(At, 0, 0); PG8_STAGE(PG8_SA(1, 1), a1 + hA, voffA);
;             PG8_WAIT_V(8); PG8_WAIT_L(0); PG8_BAR; PG8_MMA(0, 0, At, B0); PG8_MMA(0, 1, At, B1); PG8_BAR; PG8_SCHED;
;             PG8_LDA(At, 0, 1); PG8_STAGE(PG8_SB(0, 0), b2, voffB); PG8_STAGE(PG8_SB(0, 1), b2 + hB, voffB); PG8_STAGE(PG8_SA(0, 0), a2, voffA);
;             PG8_WAIT_V(8); PG8_WAIT_L(0); PG8_BAR; PG8_MMA(1, 0, At, B0); PG8_MMA(1, 1, At, B1); PG8_BAR; PG8_SCHED;
.LBB0_783:
	v_add_u32_e32 v3, s56, v222
	s_add_i32 s67, s67, 2
	ds_read_b128 v[126:129], v3
	ds_read_b128 v[130:133], v3 offset:1024
	ds_read_b128 v[142:145], v3 offset:2048
	ds_read_b128 v[146:149], v3 offset:3072
	v_add_u32_e32 v3, s57, v222
	s_add_u32 s28, s22, s26
	s_addc_u32 s29, s23, s27
	s_add_u32 s28, s28, 0x100
	s_addc_u32 s29, s29, 0
	s_add_u32 s68, s63, s26
	s_addc_u32 s69, s64, s27
	s_cmpk_eq_i32 s26, 0x5f00
	s_cselect_b32 s31, s5, s29
	s_cselect_b32 s30, s4, s28
	s_cselect_b32 s29, s21, s69
	s_cselect_b32 s28, s20, s68
	ds_read_b128 v[150:153], v3
	ds_read_b128 v[154:157], v3 offset:1024
	ds_read_b128 v[158:161], v3 offset:2048
	ds_read_b128 v[162:165], v3 offset:3072
	v_lshl_add_u64 v[4:5], v[182:183], 0, s[26:27]
	s_add_i32 m0, s37, 0xc000
	s_nop 0
	global_load_lds_dwordx4 v[4:5], off
	ds_read_b128 v[186:189], v224
	ds_read_b128 v[190:193], v224 offset:1024
	ds_read_b128 v[194:197], v224 offset:2048
	ds_read_b128 v[198:201], v224 offset:3072
	ds_read_b128 v[202:205], v224 offset:4096
	ds_read_b128 v[206:209], v224 offset:5120
	ds_read_b128 v[210:213], v224 offset:6144
	ds_read_b128 v[214:217], v224 offset:7168
	v_lshl_add_u64 v[4:5], v[184:185], 0, s[26:27]
	s_add_i32 m0, s37, 0xe000
	s_nop 0
	global_load_lds_dwordx4 v[4:5], off
	s_waitcnt vmcnt(8)
	s_waitcnt lgkmcnt(0)
	s_barrier
	s_setprio 1
	s_waitcnt lgkmcnt(0)
	v_mfma_f32_16x16x32_bf16 v[138:141], v[126:129], v[186:189], v[138:141]
	v_mfma_f32_16x16x32_bf16 v[134:137], v[142:145], v[186:189], v[134:137]
	v_mfma_f32_16x16x32_bf16 v[122:125], v[126:129], v[194:197], v[122:125]
	v_mfma_f32_16x16x32_bf16 v[118:121], v[142:145], v[194:197], v[118:121]
	v_mfma_f32_16x16x32_bf16 v[114:117], v[126:129], v[202:205], v[114:117]
	v_mfma_f32_16x16x32_bf16 v[110:113], v[142:145], v[202:205], v[110:113]
	v_mfma_f32_16x16x32_bf16 v[106:109], v[126:129], v[210:213], v[106:109]
	v_mfma_f32_16x16x32_bf16 v[102:105], v[142:145], v[210:213], v[102:105]
	v_mfma_f32_16x16x32_bf16 v[138:141], v[130:133], v[190:193], v[138:141]
	v_mfma_f32_16x16x32_bf16 v[134:137], v[146:149], v[190:193], v[134:137]
	v_mfma_f32_16x16x32_bf16 v[122:125], v[130:133], v[198:201], v[122:125]
	v_mfma_f32_16x16x32_bf16 v[118:121], v[146:149], v[198:201], v[118:121]
	v_mfma_f32_16x16x32_bf16 v[114:117], v[130:133], v[206:209], v[114:117]
	v_mfma_f32_16x16x32_bf16 v[110:113], v[146:149], v[206:209], v[110:113]
	v_mfma_f32_16x16x32_bf16 v[106:109], v[130:133], v[214:217], v[106:109]
	v_mfma_f32_16x16x32_bf16 v[102:105], v[146:149], v[214:217], v[102:105]
	s_setprio 0
	s_setprio 1
	v_mfma_f32_16x16x32_bf16 v[66:69], v[150:153], v[186:189], v[66:69]
	v_mfma_f32_16x16x32_bf16 v[62:65], v[158:161], v[186:189], v[62:65]
	v_mfma_f32_16x16x32_bf16 v[58:61], v[150:153], v[194:197], v[58:61]
	v_mfma_f32_16x16x32_bf16 v[54:57], v[158:161], v[194:197], v[54:57]
	v_mfma_f32_16x16x32_bf16 v[50:53], v[150:153], v[202:205], v[50:53]
	v_mfma_f32_16x16x32_bf16 v[46:49], v[158:161], v[202:205], v[46:49]
	v_mfma_f32_16x16x32_bf16 v[42:45], v[150:153], v[210:213], v[42:45]
	v_mfma_f32_16x16x32_bf16 v[38:41], v[158:161], v[210:213], v[38:41]
	v_mfma_f32_16x16x32_bf16 v[66:69], v[154:157], v[190:193], v[66:69]
	v_mfma_f32_16x16x32_bf16 v[62:65], v[162:165], v[190:193], v[62:65]
	v_mfma_f32_16x16x32_bf16 v[58:61], v[154:157], v[198:201], v[58:61]
	v_mfma_f32_16x16x32_bf16 v[54:57], v[162:165], v[198:201], v[54:57]
	v_mfma_f32_16x16x32_bf16 v[50:53], v[154:157], v[206:209], v[50:53]
	v_mfma_f32_16x16x32_bf16 v[46:49], v[162:165], v[206:209], v[46:49]
	v_mfma_f32_16x16x32_bf16 v[42:45], v[154:157], v[214:217], v[42:45]
	v_mfma_f32_16x16x32_bf16 v[38:41], v[162:165], v[214:217], v[38:41]
	s_setprio 0
	s_barrier
	s_add_i32 s68, s56, s35
	s_mov_b32 m0, s68
	ds_read_b128 v[186:189], v224 offset:16384
	ds_read_b128 v[190:193], v224 offset:17408
	global_load_lds_dwordx4 v168, s[28:29]
	ds_read_b128 v[194:197], v224 offset:18432
	s_add_i32 m0, s68, 0x2000
	s_add_u32 s68, s28, 0x300000
	s_addc_u32 s69, s29, 0
	s_add_i32 s70, s57, s35
	global_load_lds_dwordx4 v172, s[28:29]
	ds_read_b128 v[198:201], v224 offset:19456
	s_mov_b32 m0, s70
	s_add_u32 s74, s30, s14
	s_addc_u32 s75, s31, s15
	global_load_lds_dwordx4 v168, s[68:69]
	ds_read_b128 v[202:205], v224 offset:20480
	s_add_i32 m0, s70, 0x2000
	s_nop 0
	global_load_lds_dwordx4 v172, s[68:69]
	ds_read_b128 v[206:209], v224 offset:21504
	s_mov_b32 m0, s37
	s_nop 0
	global_load_lds_dwordx4 v166, s[30:31]
	ds_read_b128 v[210:213], v224 offset:22528
	s_mov_b32 m0, s38
	s_nop 0
	global_load_lds_dwordx4 v170, s[30:31]
	ds_read_b128 v[214:217], v224 offset:23552
	s_waitcnt vmcnt(8)
	s_waitcnt lgkmcnt(0)
	s_barrier
; #define PG8_STAGE(bufoff, gbase, voff) do { _Pragma("unroll") for (int _i = 0; _i < 2; ++_i) \
;         __builtin_amdgcn_global_load_lds((const unsigned*)((const char*)(gbase) + (voff)[_i]), (LAS unsigned*)(lds + (bufoff) + ldsw + _i * 8192), 16, 0, 0); } while (0)
; #define PG8_LDA(dst, b, h) do { _Pragma("unroll") for (int m = 0; m < 4; ++m) _Pragma("unroll") for (int k = 0; k < 2; ++k) dst[m][k] = *(const LAS bf16x8*)(lds + PG8_SA(b, h) + aoff + m * 2048 + k * 1024); } while (0)
; #define PG8_LDB(dst, b, h) do { _Pragma("unroll") for (int n = 0; n < 2; ++n) _Pragma("unroll") for (int k = 0; k < 2; ++k) dst[n][k] = *(const LAS bf16x8*)(lds + PG8_SB(b, h) + boff + n * 2048 + k * 1024); } while (0)
; #define PG8_MMA(ai, bj, At, Bt) do { __builtin_amdgcn_s_setprio(1); _Pragma("unroll") for (int m = 0; m < 4; ++m) _Pragma("unroll") for (int n = 0; n < 2; ++n) _Pragma("unroll") for (int k = 0; k < 2; ++k) \
;         acc[ai][bj][m][n] = __builtin_amdgcn_mfma_f32_16x16x32_bf16(Bt[n][k], At[m][k], acc[ai][bj][m][n], 0, 0, 0); __builtin_amdgcn_s_setprio(0); } while (0)
; #define PG8_WAIT_V(n) asm volatile("s_waitcnt vmcnt(" #n ")" ::: "memory")
; #define PG8_WAIT_L(n) asm volatile("s_waitcnt lgkmcnt(" #n ")" ::: "memory")
; #define PG8_BAR __builtin_amdgcn_s_barrier()
; #define PG8_SCHED __builtin_amdgcn_sched_barrier(0)
; template <class Epi, class Sched, bool ALIGN_EPI, class Hook = NoHook>
; __device__ __forceinline__ void gemm_phase(LAS unsigned char* lds, const Gemm g, const Sched& S, const Epi& E, const Hook& H = Hook()) {
;     ...
;             PG8_WAIT_V(8); PG8_WAIT_L(0); PG8_BAR; PG8_MMA(1, 0, At, B0); PG8_MMA(1, 1, At, B1); PG8_BAR; PG8_SCHED;
;             PG8_LDB(B0, 1, 0); PG8_LDB(B1, 1, 1); PG8_SCHED; PG8_LDA(At, 1, 0); PG8_STAGE(PG8_SA(0, 1), a2 + hA, voffA);
;             PG8_WAIT_V(8); PG8_WAIT_L(0); PG8_BAR; PG8_MMA(0, 0, At, B0); PG8_MMA(0, 1, At, B1); PG8_BAR; PG8_SCHED;
;             PG8_LDA(At, 1, 1); PG8_STAGE(PG8_SB(1, 0), b3, voffB); PG8_STAGE(PG8_SB(1, 1), b3 + hB, voffB); PG8_STAGE(PG8_SA(1, 0), a3, voffA);
	s_setprio 1
	s_waitcnt lgkmcnt(0)
	v_mfma_f32_16x16x32_bf16 v[98:101], v[126:129], v[186:189], v[98:101]
	v_mfma_f32_16x16x32_bf16 v[94:97], v[142:145], v[186:189], v[94:97]
	v_mfma_f32_16x16x32_bf16 v[90:93], v[126:129], v[194:197], v[90:93]
	v_mfma_f32_16x16x32_bf16 v[86:89], v[142:145], v[194:197], v[86:89]
	v_mfma_f32_16x16x32_bf16 v[82:85], v[126:129], v[202:205], v[82:85]
	v_mfma_f32_16x16x32_bf16 v[78:81], v[142:145], v[202:205], v[78:81]
	v_mfma_f32_16x16x32_bf16 v[74:77], v[126:129], v[210:213], v[74:77]
	v_mfma_f32_16x16x32_bf16 v[70:73], v[142:145], v[210:213], v[70:73]
	v_mfma_f32_16x16x32_bf16 v[98:101], v[130:133], v[190:193], v[98:101]
	v_mfma_f32_16x16x32_bf16 v[94:97], v[146:149], v[190:193], v[94:97]
	v_mfma_f32_16x16x32_bf16 v[90:93], v[130:133], v[198:201], v[90:93]
	v_mfma_f32_16x16x32_bf16 v[86:89], v[146:149], v[198:201], v[86:89]
	v_mfma_f32_16x16x32_bf16 v[82:85], v[130:133], v[206:209], v[82:85]
	v_mfma_f32_16x16x32_bf16 v[78:81], v[146:149], v[206:209], v[78:81]
	v_mfma_f32_16x16x32_bf16 v[74:77], v[130:133], v[214:217], v[74:77]
	v_mfma_f32_16x16x32_bf16 v[70:73], v[146:149], v[214:217], v[70:73]
	s_setprio 0
	s_setprio 1
	v_mfma_f32_16x16x32_bf16 v[34:37], v[150:153], v[186:189], v[34:37]
	v_mfma_f32_16x16x32_bf16 v[30:33], v[158:161], v[186:189], v[30:33]
	v_mfma_f32_16x16x32_bf16 v[26:29], v[150:153], v[194:197], v[26:29]
	v_mfma_f32_16x16x32_bf16 v[22:25], v[158:161], v[194:197], v[22:25]
	v_mfma_f32_16x16x32_bf16 v[18:21], v[150:153], v[202:205], v[18:21]
	v_mfma_f32_16x16x32_bf16 v[14:17], v[158:161], v[202:205], v[14:17]
	v_mfma_f32_16x16x32_bf16 v[10:13], v[150:153], v[210:213], v[10:13]
	v_mfma_f32_16x16x32_bf16 v[4:7], v[158:161], v[210:213], v[6:9]
	v_mfma_f32_16x16x32_bf16 v[34:37], v[154:157], v[190:193], v[34:37]
	v_mfma_f32_16x16x32_bf16 v[30:33], v[162:165], v[190:193], v[30:33]
	v_mfma_f32_16x16x32_bf16 v[26:29], v[154:157], v[198:201], v[26:29]
	v_mfma_f32_16x16x32_bf16 v[22:25], v[162:165], v[198:201], v[22:25]
	v_mfma_f32_16x16x32_bf16 v[18:21], v[154:157], v[206:209], v[18:21]
	v_mfma_f32_16x16x32_bf16 v[14:17], v[162:165], v[206:209], v[14:17]
	v_mfma_f32_16x16x32_bf16 v[10:13], v[154:157], v[214:217], v[10:13]
	v_mfma_f32_16x16x32_bf16 v[4:7], v[162:165], v[214:217], v[4:7]
	s_setprio 0
	s_barrier
	s_add_i32 s68, 0, 0x18000
	v_add_u32_e32 v3, s68, v222
	s_add_i32 s69, 0, 0x1c000
	ds_read_b128 v[126:129], v3
	ds_read_b128 v[130:133], v3 offset:1024
	ds_read_b128 v[142:145], v3 offset:2048
	ds_read_b128 v[146:149], v3 offset:3072
	v_add_u32_e32 v3, s69, v222
	s_add_u32 s30, s30, 0x300000
	s_addc_u32 s31, s31, 0
	s_mov_b32 m0, s39
	s_nop 0
	global_load_lds_dwordx4 v166, s[30:31]
	ds_read_b128 v[150:153], v3
	ds_read_b128 v[154:157], v3 offset:1024
	ds_read_b128 v[158:161], v3 offset:2048
	ds_read_b128 v[162:165], v3 offset:3072
	ds_read_b128 v[186:189], v224 offset:32768
	ds_read_b128 v[190:193], v224 offset:33792
	ds_read_b128 v[194:197], v224 offset:34816
	s_mov_b32 m0, s40
	s_nop 0
	global_load_lds_dwordx4 v170, s[30:31]
	ds_read_b128 v[198:201], v224 offset:35840
	ds_read_b128 v[202:205], v224 offset:36864
	ds_read_b128 v[206:209], v224 offset:37888
	ds_read_b128 v[210:213], v224 offset:38912
	ds_read_b128 v[214:217], v224 offset:39936
	s_waitcnt vmcnt(8)
	s_waitcnt lgkmcnt(0)
	s_barrier
	s_setprio 1
	s_waitcnt lgkmcnt(0)
	v_mfma_f32_16x16x32_bf16 v[138:141], v[126:129], v[186:189], v[138:141]
	v_mfma_f32_16x16x32_bf16 v[134:137], v[142:145], v[186:189], v[134:137]
	v_mfma_f32_16x16x32_bf16 v[122:125], v[126:129], v[194:197], v[122:125]
	v_mfma_f32_16x16x32_bf16 v[118:121], v[142:145], v[194:197], v[118:121]
	v_mfma_f32_16x16x32_bf16 v[114:117], v[126:129], v[202:205], v[114:117]
	v_mfma_f32_16x16x32_bf16 v[110:113], v[142:145], v[202:205], v[110:113]
	v_mfma_f32_16x16x32_bf16 v[106:109], v[126:129], v[210:213], v[106:109]
	v_mfma_f32_16x16x32_bf16 v[102:105], v[142:145], v[210:213], v[102:105]
	v_mfma_f32_16x16x32_bf16 v[138:141], v[130:133], v[190:193], v[138:141]
	v_mfma_f32_16x16x32_bf16 v[134:137], v[146:149], v[190:193], v[134:137]
	v_mfma_f32_16x16x32_bf16 v[122:125], v[130:133], v[198:201], v[122:125]
	v_mfma_f32_16x16x32_bf16 v[118:121], v[146:149], v[198:201], v[118:121]
	v_mfma_f32_16x16x32_bf16 v[114:117], v[130:133], v[206:209], v[114:117]
	v_mfma_f32_16x16x32_bf16 v[110:113], v[146:149], v[206:209], v[110:113]
	v_mfma_f32_16x16x32_bf16 v[106:109], v[130:133], v[214:217], v[106:109]
	v_mfma_f32_16x16x32_bf16 v[102:105], v[146:149], v[214:217], v[102:105]
	s_setprio 0
	s_setprio 1
	v_mfma_f32_16x16x32_bf16 v[66:69], v[150:153], v[186:189], v[66:69]
	v_mfma_f32_16x16x32_bf16 v[62:65], v[158:161], v[186:189], v[62:65]
	v_mfma_f32_16x16x32_bf16 v[58:61], v[150:153], v[194:197], v[58:61]
	v_mfma_f32_16x16x32_bf16 v[54:57], v[158:161], v[194:197], v[54:57]
	v_mfma_f32_16x16x32_bf16 v[50:53], v[150:153], v[202:205], v[50:53]
	v_mfma_f32_16x16x32_bf16 v[46:49], v[158:161], v[202:205], v[46:49]
	v_mfma_f32_16x16x32_bf16 v[42:45], v[150:153], v[210:213], v[42:45]
	v_mfma_f32_16x16x32_bf16 v[38:41], v[158:161], v[210:213], v[38:41]
	v_mfma_f32_16x16x32_bf16 v[66:69], v[154:157], v[190:193], v[66:69]
	v_mfma_f32_16x16x32_bf16 v[62:65], v[162:165], v[190:193], v[62:65]
	v_mfma_f32_16x16x32_bf16 v[58:61], v[154:157], v[198:201], v[58:61]
	v_mfma_f32_16x16x32_bf16 v[54:57], v[162:165], v[198:201], v[54:57]
	v_mfma_f32_16x16x32_bf16 v[50:53], v[154:157], v[206:209], v[50:53]
	v_mfma_f32_16x16x32_bf16 v[46:49], v[162:165], v[206:209], v[46:49]
	v_mfma_f32_16x16x32_bf16 v[42:45], v[154:157], v[214:217], v[42:45]
	v_mfma_f32_16x16x32_bf16 v[38:41], v[162:165], v[214:217], v[38:41]
	s_setprio 0
	s_barrier
; #define PG8_STAGE(bufoff, gbase, voff) do { _Pragma("unroll") for (int _i = 0; _i < 2; ++_i) \
;         __builtin_amdgcn_global_load_lds((const unsigned*)((const char*)(gbase) + (voff)[_i]), (LAS unsigned*)(lds + (bufoff) + ldsw + _i * 8192), 16, 0, 0); } while (0)
; #define PG8_LDA(dst, b, h) do { _Pragma("unroll") for (int m = 0; m < 4; ++m) _Pragma("unroll") for (int k = 0; k < 2; ++k) dst[m][k] = *(const LAS bf16x8*)(lds + PG8_SA(b, h) + aoff + m * 2048 + k * 1024); } while (0)
; #define PG8_MMA(ai, bj, At, Bt) do { __builtin_amdgcn_s_setprio(1); _Pragma("unroll") for (int m = 0; m < 4; ++m) _Pragma("unroll") for (int n = 0; n < 2; ++n) _Pragma("unroll") for (int k = 0; k < 2; ++k) \
;         acc[ai][bj][m][n] = __builtin_amdgcn_mfma_f32_16x16x32_bf16(Bt[n][k], At[m][k], acc[ai][bj][m][n], 0, 0, 0); __builtin_amdgcn_s_setprio(0); } while (0)
; #define PG8_WAIT_V(n) asm volatile("s_waitcnt vmcnt(" #n ")" ::: "memory")
; #define PG8_WAIT_L(n) asm volatile("s_waitcnt lgkmcnt(" #n ")" ::: "memory")
; #define PG8_BAR __builtin_amdgcn_s_barrier()
; #define PG8_SCHED __builtin_amdgcn_sched_barrier(0)
;     __device__ __forceinline__ void after(int te, f32x4 (&acc)[2][2][4][2], const Unit& u, int wr, int wc, int fr, int fq) const {
;         if (te > D_INNER / BK) return;
;         const int g = (te >> 4) - 1;
;         asm volatile("" : "+v"(fr), "+v"(fq));
; #pragma unroll
;         for (int ai = 0; ai < 2; ++ai)
; #pragma unroll
;             for (int m = 0; m < 4; ++m) { const float f = tab[(ai * HALF + wr * 64 + m * 16 + fr) * 8 + g];
; #pragma unroll
;                 for (int bj = 0; bj < 2; ++bj)
; #pragma unroll
;                     for (int n = 0; n < 2; ++n) acc[ai][bj][m][n] *= f; }
; template <class Epi, class Sched, bool ALIGN_EPI, class Hook = NoHook>
; __device__ __forceinline__ void gemm_phase(LAS unsigned char* lds, const Gemm g, const Sched& S, const Epi& E, const Hook& H = Hook()) {
;     ...
;             PG8_LDA(At, 1, 1); PG8_STAGE(PG8_SB(1, 0), b3, voffB); PG8_STAGE(PG8_SB(1, 1), b3 + hB, voffB); PG8_STAGE(PG8_SA(1, 0), a3, voffA);
;             PG8_WAIT_V(8); PG8_WAIT_L(0); PG8_BAR; PG8_MMA(1, 0, At, B0); PG8_MMA(1, 1, At, B1); PG8_BAR; PG8_SCHED;
;         }
;         if constexpr (Hook::ON) H.after(te, acc, cur, wr, wc, fr, fq);
	s_add_i32 s30, s68, s35
	s_add_u32 s72, s28, s14
	s_addc_u32 s73, s29, s15
	s_mov_b32 m0, s30
	ds_read_b128 v[186:189], v224 offset:49152
	ds_read_b128 v[190:193], v224 offset:50176
	global_load_lds_dwordx4 v168, s[72:73]
	ds_read_b128 v[194:197], v224 offset:51200
	s_add_i32 m0, s30, 0x2000
	s_add_u32 s28, s28, 0x300080
	s_addc_u32 s29, s29, 0
	s_add_i32 s30, s69, s35
	global_load_lds_dwordx4 v172, s[72:73]
	ds_read_b128 v[198:201], v224 offset:52224
	s_mov_b32 m0, s30
	s_nop 0
	global_load_lds_dwordx4 v168, s[28:29]
	ds_read_b128 v[202:205], v224 offset:53248
	s_add_i32 m0, s30, 0x2000
	s_nop 0
	global_load_lds_dwordx4 v172, s[28:29]
	ds_read_b128 v[206:209], v224 offset:54272
	s_mov_b32 m0, s45
	s_nop 0
	global_load_lds_dwordx4 v166, s[74:75]
	ds_read_b128 v[210:213], v224 offset:55296
	s_mov_b32 m0, s46
	s_nop 0
	global_load_lds_dwordx4 v170, s[74:75]
	ds_read_b128 v[214:217], v224 offset:56320
	s_waitcnt vmcnt(8)
	s_waitcnt lgkmcnt(0)
	s_barrier
	s_setprio 1
	s_waitcnt lgkmcnt(0)
	v_mfma_f32_16x16x32_bf16 v[98:101], v[126:129], v[186:189], v[98:101]
	v_mfma_f32_16x16x32_bf16 v[94:97], v[142:145], v[186:189], v[94:97]
	v_mfma_f32_16x16x32_bf16 v[90:93], v[126:129], v[194:197], v[90:93]
	v_mfma_f32_16x16x32_bf16 v[86:89], v[142:145], v[194:197], v[86:89]
	v_mfma_f32_16x16x32_bf16 v[82:85], v[126:129], v[202:205], v[82:85]
	v_mfma_f32_16x16x32_bf16 v[78:81], v[142:145], v[202:205], v[78:81]
	v_mfma_f32_16x16x32_bf16 v[74:77], v[126:129], v[210:213], v[74:77]
	v_mfma_f32_16x16x32_bf16 v[70:73], v[142:145], v[210:213], v[70:73]
	v_mfma_f32_16x16x32_bf16 v[98:101], v[130:133], v[190:193], v[98:101]
	v_mfma_f32_16x16x32_bf16 v[94:97], v[146:149], v[190:193], v[94:97]
	v_mfma_f32_16x16x32_bf16 v[90:93], v[130:133], v[198:201], v[90:93]
	v_mfma_f32_16x16x32_bf16 v[86:89], v[146:149], v[198:201], v[86:89]
	v_mfma_f32_16x16x32_bf16 v[82:85], v[130:133], v[206:209], v[82:85]
	v_mfma_f32_16x16x32_bf16 v[78:81], v[146:149], v[206:209], v[78:81]
	v_mfma_f32_16x16x32_bf16 v[74:77], v[130:133], v[214:217], v[74:77]
	v_mfma_f32_16x16x32_bf16 v[70:73], v[146:149], v[214:217], v[70:73]
	s_setprio 0
	s_setprio 1
	v_mfma_f32_16x16x32_bf16 v[34:37], v[150:153], v[186:189], v[34:37]
	v_mfma_f32_16x16x32_bf16 v[30:33], v[158:161], v[186:189], v[30:33]
	v_mfma_f32_16x16x32_bf16 v[26:29], v[150:153], v[194:197], v[26:29]
	v_mfma_f32_16x16x32_bf16 v[22:25], v[158:161], v[194:197], v[22:25]
	v_mfma_f32_16x16x32_bf16 v[18:21], v[150:153], v[202:205], v[18:21]
	v_mfma_f32_16x16x32_bf16 v[14:17], v[158:161], v[202:205], v[14:17]
	v_mfma_f32_16x16x32_bf16 v[8:11], v[150:153], v[210:213], v[10:13]
	v_mfma_f32_16x16x32_bf16 v[4:7], v[158:161], v[210:213], v[4:7]
	v_mfma_f32_16x16x32_bf16 v[34:37], v[154:157], v[190:193], v[34:37]
	v_mfma_f32_16x16x32_bf16 v[30:33], v[162:165], v[190:193], v[30:33]
	v_mfma_f32_16x16x32_bf16 v[26:29], v[154:157], v[198:201], v[26:29]
	v_mfma_f32_16x16x32_bf16 v[22:25], v[162:165], v[198:201], v[22:25]
	v_mfma_f32_16x16x32_bf16 v[18:21], v[154:157], v[206:209], v[18:21]
	v_mfma_f32_16x16x32_bf16 v[14:17], v[162:165], v[206:209], v[14:17]
	v_mfma_f32_16x16x32_bf16 v[10:13], v[154:157], v[214:217], v[8:11]
	v_mfma_f32_16x16x32_bf16 v[6:9], v[162:165], v[214:217], v[4:7]
	s_setprio 0
	s_barrier
	s_add_u32 s26, s26, 0x100
	s_addc_u32 s27, s27, 0
	s_cmp_ge_u32 s67, s66
	s_cbranch_scc0 .LBB0_783
	s_cmpk_gt_u32 s65, 0x7f
	s_cbranch_scc1 .LBB0_787
	s_lshr_b32 s26, s66, 4
	s_add_i32 s26, s26, -1
	v_mov_b32_e32 v3, v1
	v_mov_b32_e32 v4, v220
	s_lshl_b32 s27, s26, 2
	s_add_i32 s28, s27, s48
	v_lshlrev_b32_e32 v5, 5, v3
	v_add_u32_e32 v126, s28, v5
	ds_read_b32 v126, v126
	s_add_i32 s28, s27, s49
	s_waitcnt lgkmcnt(0)
	v_pk_mul_f32 v[140:141], v[140:141], v[126:127] op_sel_hi:[1,0]
	v_pk_mul_f32 v[138:139], v[138:139], v[126:127] op_sel_hi:[1,0]
	v_pk_mul_f32 v[136:137], v[136:137], v[126:127] op_sel_hi:[1,0]
	v_pk_mul_f32 v[134:135], v[134:135], v[126:127] op_sel_hi:[1,0]
	v_pk_mul_f32 v[68:69], v[68:69], v[126:127] op_sel_hi:[1,0]
	v_pk_mul_f32 v[66:67], v[66:67], v[126:127] op_sel_hi:[1,0]
	v_pk_mul_f32 v[64:65], v[64:65], v[126:127] op_sel_hi:[1,0]
	v_pk_mul_f32 v[62:63], v[62:63], v[126:127] op_sel_hi:[1,0]
	v_add_u32_e32 v126, s28, v5
	ds_read_b32 v126, v126
	s_add_i32 s28, s27, s50
	s_waitcnt lgkmcnt(0)
	v_pk_mul_f32 v[124:125], v[124:125], v[126:127] op_sel_hi:[1,0]
	v_pk_mul_f32 v[122:123], v[122:123], v[126:127] op_sel_hi:[1,0]
	v_pk_mul_f32 v[120:121], v[120:121], v[126:127] op_sel_hi:[1,0]
	v_pk_mul_f32 v[118:119], v[118:119], v[126:127] op_sel_hi:[1,0]
	v_pk_mul_f32 v[60:61], v[60:61], v[126:127] op_sel_hi:[1,0]
	v_pk_mul_f32 v[58:59], v[58:59], v[126:127] op_sel_hi:[1,0]
	v_pk_mul_f32 v[56:57], v[56:57], v[126:127] op_sel_hi:[1,0]
	v_pk_mul_f32 v[54:55], v[54:55], v[126:127] op_sel_hi:[1,0]
	v_add_u32_e32 v126, s28, v5
	ds_read_b32 v126, v126
	s_add_i32 s28, s27, s51
	s_waitcnt lgkmcnt(0)
	v_pk_mul_f32 v[116:117], v[116:117], v[126:127] op_sel_hi:[1,0]
	v_pk_mul_f32 v[114:115], v[114:115], v[126:127] op_sel_hi:[1,0]
	v_pk_mul_f32 v[112:113], v[112:113], v[126:127] op_sel_hi:[1,0]
	v_pk_mul_f32 v[110:111], v[110:111], v[126:127] op_sel_hi:[1,0]
	v_pk_mul_f32 v[52:53], v[52:53], v[126:127] op_sel_hi:[1,0]
	v_pk_mul_f32 v[50:51], v[50:51], v[126:127] op_sel_hi:[1,0]
	v_pk_mul_f32 v[48:49], v[48:49], v[126:127] op_sel_hi:[1,0]
	v_pk_mul_f32 v[46:47], v[46:47], v[126:127] op_sel_hi:[1,0]
	v_add_u32_e32 v126, s28, v5
	ds_read_b32 v126, v126
	s_add_i32 s28, s27, s52
	s_waitcnt lgkmcnt(0)
;     __device__ __forceinline__ void after(int te, f32x4 (&acc)[2][2][4][2], const Unit& u, int wr, int wc, int fr, int fq) const {
;     ...
;             for (int m = 0; m < 4; ++m) { const float f = tab[(ai * HALF + wr * 64 + m * 16 + fr) * 8 + g];
; #pragma unroll
;                 for (int bj = 0; bj < 2; ++bj)
; #pragma unroll
;                     for (int n = 0; n < 2; ++n) acc[ai][bj][m][n] *= f; }
;         if (g == 7) {
;             const int row0 = u.pm * BM + wr * 64 + fr, col0 = u.pn * BM + wc * 32 + 8 * fq;
; #pragma unroll
;             for (int bj = 0; bj < 2; ++bj) { const int c = col0 + bj * HALF;
;                 const f32x4 s0 = *(const f32x4*)(gb + c), s1 = *(const f32x4*)(gb + c + 4), a0 = *(const f32x4*)(gb + D_MODEL + c), a1 = *(const f32x4*)(gb + D_MODEL + c + 4);
; #pragma unroll
;                 for (int ai = 0; ai < 2; ++ai) {
;                     u32x4 gs[4], ga[4];
; #pragma unroll
;                     for (int m = 0; m < 4; ++m) { const size_t r = (size_t)(row0 + ai * HALF + m * 16); gs[m] = *(const u32x4*)(proj + r * LDP + PGS + c); ga[m] = *(const u32x4*)(proj + r * LDP + PGA + c); }
	v_pk_mul_f32 v[108:109], v[108:109], v[126:127] op_sel_hi:[1,0]
	v_pk_mul_f32 v[106:107], v[106:107], v[126:127] op_sel_hi:[1,0]
	v_pk_mul_f32 v[104:105], v[104:105], v[126:127] op_sel_hi:[1,0]
	v_pk_mul_f32 v[102:103], v[102:103], v[126:127] op_sel_hi:[1,0]
	v_pk_mul_f32 v[44:45], v[44:45], v[126:127] op_sel_hi:[1,0]
	v_pk_mul_f32 v[42:43], v[42:43], v[126:127] op_sel_hi:[1,0]
	v_pk_mul_f32 v[40:41], v[40:41], v[126:127] op_sel_hi:[1,0]
	v_pk_mul_f32 v[38:39], v[38:39], v[126:127] op_sel_hi:[1,0]
	v_add_u32_e32 v126, s28, v5
	ds_read_b32 v126, v126
	s_add_i32 s28, s27, s53
	s_waitcnt lgkmcnt(0)
	v_pk_mul_f32 v[100:101], v[100:101], v[126:127] op_sel_hi:[1,0]
	v_pk_mul_f32 v[98:99], v[98:99], v[126:127] op_sel_hi:[1,0]
	v_pk_mul_f32 v[96:97], v[96:97], v[126:127] op_sel_hi:[1,0]
	v_pk_mul_f32 v[94:95], v[94:95], v[126:127] op_sel_hi:[1,0]
	v_pk_mul_f32 v[36:37], v[36:37], v[126:127] op_sel_hi:[1,0]
	v_pk_mul_f32 v[34:35], v[34:35], v[126:127] op_sel_hi:[1,0]
	v_pk_mul_f32 v[32:33], v[32:33], v[126:127] op_sel_hi:[1,0]
	v_pk_mul_f32 v[30:31], v[30:31], v[126:127] op_sel_hi:[1,0]
	v_add_u32_e32 v126, s28, v5
	ds_read_b32 v126, v126
	s_add_i32 s28, s27, s54
	s_add_i32 s27, s27, s55
	s_cmp_lg_u32 s26, 7
	s_waitcnt lgkmcnt(0)
	v_pk_mul_f32 v[92:93], v[92:93], v[126:127] op_sel_hi:[1,0]
	v_pk_mul_f32 v[90:91], v[90:91], v[126:127] op_sel_hi:[1,0]
	v_pk_mul_f32 v[88:89], v[88:89], v[126:127] op_sel_hi:[1,0]
	v_pk_mul_f32 v[86:87], v[86:87], v[126:127] op_sel_hi:[1,0]
	v_pk_mul_f32 v[28:29], v[28:29], v[126:127] op_sel_hi:[1,0]
	v_pk_mul_f32 v[26:27], v[26:27], v[126:127] op_sel_hi:[1,0]
	v_pk_mul_f32 v[24:25], v[24:25], v[126:127] op_sel_hi:[1,0]
	v_pk_mul_f32 v[22:23], v[22:23], v[126:127] op_sel_hi:[1,0]
	v_add_u32_e32 v126, s28, v5
	ds_read_b32 v126, v126
	v_add_u32_e32 v5, s27, v5
	s_waitcnt lgkmcnt(0)
	v_pk_mul_f32 v[84:85], v[84:85], v[126:127] op_sel_hi:[1,0]
	v_pk_mul_f32 v[82:83], v[82:83], v[126:127] op_sel_hi:[1,0]
	v_pk_mul_f32 v[80:81], v[80:81], v[126:127] op_sel_hi:[1,0]
	v_pk_mul_f32 v[78:79], v[78:79], v[126:127] op_sel_hi:[1,0]
	v_pk_mul_f32 v[20:21], v[20:21], v[126:127] op_sel_hi:[1,0]
	v_pk_mul_f32 v[18:19], v[18:19], v[126:127] op_sel_hi:[1,0]
	v_pk_mul_f32 v[16:17], v[16:17], v[126:127] op_sel_hi:[1,0]
	v_pk_mul_f32 v[14:15], v[14:15], v[126:127] op_sel_hi:[1,0]
	ds_read_b32 v126, v5
	s_waitcnt lgkmcnt(0)
	v_pk_mul_f32 v[76:77], v[76:77], v[126:127] op_sel_hi:[1,0]
	v_pk_mul_f32 v[74:75], v[74:75], v[126:127] op_sel_hi:[1,0]
	v_pk_mul_f32 v[72:73], v[72:73], v[126:127] op_sel_hi:[1,0]
	v_pk_mul_f32 v[70:71], v[70:71], v[126:127] op_sel_hi:[1,0]
	v_pk_mul_f32 v[12:13], v[12:13], v[126:127] op_sel_hi:[1,0]
	v_pk_mul_f32 v[10:11], v[10:11], v[126:127] op_sel_hi:[1,0]
	v_pk_mul_f32 v[8:9], v[8:9], v[126:127] op_sel_hi:[1,0]
	v_pk_mul_f32 v[6:7], v[6:7], v[126:127] op_sel_hi:[1,0]
	s_cbranch_scc1 .LBB0_787
	v_add_u32_e32 v126, s62, v3
	v_ashrrev_i32_e32 v127, 31, v126
	v_lshl_add_u32 v4, v4, 3, s61
	v_lshlrev_b64 v[126:127], 14, v[126:127]
	v_ashrrev_i32_e32 v5, 31, v4
	v_lshl_add_u64 v[126:127], s[76:77], 0, v[126:127]
	v_lshl_add_u64 v[192:193], v[4:5], 1, v[126:127]
	v_readlane_b32 s68, v254, 20
	global_load_dwordx4 v[204:207], v[192:193], off
	v_add_co_u32_e32 v126, vcc, s41, v192
	v_lshlrev_b64 v[4:5], 2, v[4:5]
	v_readlane_b32 s70, v254, 22
	v_readlane_b32 s71, v254, 23
	v_addc_co_u32_e32 v127, vcc, 0, v193, vcc
	s_nop 0
	v_lshl_add_u64 v[196:197], s[70:71], 0, v[4:5]
	global_load_dwordx4 v[208:211], v[126:127], off
	global_load_dwordx4 v[142:145], v[196:197], off
	s_nop 0
	global_load_dwordx4 v[126:129], v[196:197], off offset:16
	v_lshl_add_u64 v[198:199], s[12:13], 0, v[4:5]
	global_load_dwordx4 v[146:149], v[198:199], off
	global_load_dwordx4 v[130:133], v[198:199], off offset:16
	s_mov_b64 s[26:27], 0x40000
	v_lshl_add_u64 v[4:5], v[192:193], 0, s[26:27]
	s_mov_b32 s26, 0x40000
	v_add_co_u32_e32 v150, vcc, s26, v192
	s_mov_b64 s[26:27], 0x42000
	s_nop 0
	v_addc_co_u32_e32 v151, vcc, 0, v193, vcc
	v_lshl_add_u64 v[186:187], v[192:193], 0, s[26:27]
	s_mov_b32 s26, 0x42000
	v_add_co_u32_e32 v152, vcc, s26, v192
	s_mov_b64 s[26:27], 0x80000
	s_nop 0
	v_addc_co_u32_e32 v153, vcc, 0, v193, vcc
	v_lshl_add_u64 v[188:189], v[192:193], 0, s[26:27]
	s_mov_b32 s26, 0x80000
	v_add_co_u32_e32 v154, vcc, s26, v192
	s_mov_b64 s[26:27], 0x82000
	s_nop 0
	v_addc_co_u32_e32 v155, vcc, 0, v193, vcc
	v_lshl_add_u64 v[190:191], v[192:193], 0, s[26:27]
	s_mov_b32 s26, 0x82000
	v_add_co_u32_e32 v156, vcc, s26, v192
	s_mov_b64 s[26:27], 0xc0000
	s_nop 0
	v_addc_co_u32_e32 v157, vcc, 0, v193, vcc
	v_lshl_add_u64 v[194:195], v[192:193], 0, s[26:27]
	s_mov_b32 s26, 0xc0000
	v_add_co_u32_e32 v228, vcc, s26, v192
	s_mov_b64 s[26:27], 0xc2000
	s_nop 0
	v_addc_co_u32_e32 v229, vcc, 0, v193, vcc
	v_lshl_add_u64 v[200:201], v[192:193], 0, s[26:27]
	s_mov_b32 s26, 0xc2000
	v_add_co_u32_e32 v230, vcc, s26, v192
	s_mov_b32 s26, 0x200000
	s_nop 0
	v_addc_co_u32_e32 v231, vcc, 0, v193, vcc
	global_load_dwordx4 v[212:215], v[150:151], off
	global_load_dwordx4 v[216:219], v[152:153], off
	global_load_dwordx4 v[162:165], v[154:155], off
	global_load_dwordx4 v[158:161], v[156:157], off
	s_nop 0
	global_load_dwordx4 v[154:157], v[228:229], off
	global_load_dwordx4 v[150:153], v[230:231], off
	v_lshl_add_u64 v[202:203], v[192:193], 0, s[18:19]
	v_readlane_b32 s76, v254, 28
	v_readlane_b32 s77, v254, 29
	v_readlane_b32 s76, v255, 8
	v_readlane_b32 s77, v255, 9
	v_readlane_b32 s69, v254, 21
	v_readlane_b32 s72, v254, 24
	v_readlane_b32 s73, v254, 25
	v_readlane_b32 s74, v254, 26
	v_readlane_b32 s75, v254, 27
	v_readlane_b32 s78, v254, 30
	v_readlane_b32 s79, v254, 31
	v_readlane_b32 s80, v254, 32
	v_readlane_b32 s81, v254, 33
	v_readlane_b32 s82, v254, 34
	v_readlane_b32 s83, v254, 35
	s_waitcnt vmcnt(0)
; __device__ __forceinline__ void unpack8(const u32x4 w, float (&v)[8]) { v[0] = bf_lo(w.x); v[1] = bf_hi(w.x); v[2] = bf_lo(w.y); v[3] = bf_hi(w.y); v[4] = bf_lo(w.z); v[5] = bf_hi(w.z); v[6] = bf_lo(w.w); v[7] = bf_hi(w.w); }
;     __device__ __forceinline__ void after(int te, f32x4 (&acc)[2][2][4][2], const Unit& u, int wr, int wc, int fr, int fq) const {
;     ...
;                     for (int m = 0; m < 4; ++m) { float vs[8], va[8]; unpack8(gs[m], vs); unpack8(ga[m], va);
; #pragma unroll
;                         for (int e = 0; e < 4; ++e) {
;                             acc[ai][bj][m][0][e] *= (1.f + __expf(-(va[e] + a0[e]))) * __builtin_amdgcn_rcpf(1.f + __expf(-(vs[e] + s0[e])));
;                             acc[ai][bj][m][1][e] *= (1.f + __expf(-(va[4 + e] + a1[e]))) * __builtin_amdgcn_rcpf(1.f + __expf(-(vs[4 + e] + s1[e]))); } }
	v_lshlrev_b32_e32 v3, 16, v204
	v_and_b32_e32 v204, 0xffff0000, v204
	v_lshlrev_b32_e32 v225, 16, v205
	v_and_b32_e32 v227, 0xffff0000, v205
	v_lshlrev_b32_e32 v205, 16, v206
	v_and_b32_e32 v228, 0xffff0000, v206
	v_lshlrev_b32_e32 v229, 16, v207
	v_and_b32_e32 v233, 0xffff0000, v207
	v_add_f32_e32 v3, v142, v3
	v_add_f32_e32 v204, v143, v204
	v_mul_f32_e32 v3, 0xbfb8aa3b, v3
	v_mul_f32_e32 v204, 0xbfb8aa3b, v204
	v_exp_f32_e32 v3, v3
	v_lshlrev_b32_e32 v230, 16, v209
	v_and_b32_e32 v231, 0xffff0000, v209
	v_exp_f32_e32 v209, v204
	v_lshlrev_b32_e32 v206, 16, v208
	v_and_b32_e32 v207, 0xffff0000, v208
	v_lshlrev_b32_e32 v208, 16, v210
	v_add_f32_e32 v206, v146, v206
	v_add_f32_e32 v208, v130, v208
	v_mul_f32_e32 v206, 0xbfb8aa3b, v206
	v_mul_f32_e32 v208, 0xbfb8aa3b, v208
	v_add_f32_e32 v3, 1.0, v3
	v_exp_f32_e32 v204, v206
	v_exp_f32_e32 v206, v208
	v_rcp_f32_e32 v208, v3
	v_add_f32_e32 v3, 1.0, v209
	v_rcp_f32_e32 v209, v3
	v_add_f32_e32 v3, v127, v228
	v_mul_f32_e32 v3, 0xbfb8aa3b, v3
	v_exp_f32_e32 v3, v3
	v_lshlrev_b32_e32 v234, 16, v211
	v_and_b32_e32 v235, 0xffff0000, v211
	v_add_f32_e32 v205, v126, v205
	v_add_f32_e32 v3, 1.0, v3
	v_rcp_f32_e32 v211, v3
	v_add_f32_e32 v3, v144, v225
	v_mul_f32_e32 v3, 0xbfb8aa3b, v3
	v_exp_f32_e32 v3, v3
	v_mul_f32_e32 v205, 0xbfb8aa3b, v205
	v_exp_f32_e32 v205, v205
	v_add_f32_e32 v225, v148, v230
	v_add_f32_e32 v3, 1.0, v3
	v_rcp_f32_e32 v230, v3
	v_add_f32_e32 v3, v128, v229
	v_mul_f32_e32 v3, 0xbfb8aa3b, v3
	v_add_f32_e32 v227, v145, v227
	v_mul_f32_e32 v225, 0xbfb8aa3b, v225
	v_exp_f32_e32 v3, v3
	v_mul_f32_e32 v227, 0xbfb8aa3b, v227
	v_add_f32_e32 v207, v147, v207
	v_exp_f32_e32 v228, v225
	v_add_f32_e32 v225, v132, v234
	v_exp_f32_e32 v227, v227
	v_and_b32_e32 v232, 0xffff0000, v210
	v_mul_f32_e32 v207, 0xbfb8aa3b, v207
	v_add_f32_e32 v205, 1.0, v205
	v_mul_f32_e32 v225, 0xbfb8aa3b, v225
	v_rcp_f32_e32 v210, v205
	v_exp_f32_e32 v205, v207
	v_add_f32_e32 v207, v131, v232
	v_exp_f32_e32 v232, v225
	v_add_f32_e32 v225, v149, v231
	v_add_f32_e32 v3, 1.0, v3
	v_mul_f32_e32 v225, 0xbfb8aa3b, v225
	v_exp_f32_e32 v229, v225
	v_rcp_f32_e32 v234, v3
	v_add_f32_e32 v3, 1.0, v227
	v_rcp_f32_e32 v231, v3
	v_pk_add_f32 v[228:229], v[228:229], 1.0 op_sel_hi:[1,0]
	v_pk_add_f32 v[204:205], v[204:205], 1.0 op_sel_hi:[1,0]
	v_add_f32_e32 v3, v133, v235
	v_pk_mul_f32 v[204:205], v[204:205], v[208:209]
	v_pk_mul_f32 v[208:209], v[228:229], v[230:231]
	v_mul_f32_e32 v3, 0xbfb8aa3b, v3
	v_pk_mul_f32 v[140:141], v[140:141], v[208:209]
	v_add_f32_e32 v208, v129, v233
	v_mul_f32_e32 v208, 0xbfb8aa3b, v208
	v_exp_f32_e32 v208, v208
	v_exp_f32_e32 v233, v3
	v_mul_f32_e32 v207, 0xbfb8aa3b, v207
	v_exp_f32_e32 v207, v207
	v_add_f32_e32 v3, 1.0, v208
	v_rcp_f32_e32 v235, v3
	v_lshlrev_b32_e32 v3, 16, v212
	v_add_f32_e32 v3, v142, v3
	v_mul_f32_e32 v3, 0xbfb8aa3b, v3
	v_exp_f32_e32 v3, v3
	v_pk_add_f32 v[206:207], v[206:207], 1.0 op_sel_hi:[1,0]
	v_pk_mul_f32 v[138:139], v[138:139], v[204:205]
	v_pk_mul_f32 v[206:207], v[206:207], v[210:211]
	v_add_f32_e32 v3, 1.0, v3
	v_pk_mul_f32 v[134:135], v[134:135], v[206:207]
	v_lshlrev_b32_e32 v207, 16, v214
	v_rcp_f32_e32 v206, v3
	v_add_f32_e32 v3, v126, v207
	v_mul_f32_e32 v3, 0xbfb8aa3b, v3
	v_exp_f32_e32 v3, v3
	v_pk_add_f32 v[204:205], v[232:233], 1.0 op_sel_hi:[1,0]
	v_lshlrev_b32_e32 v208, 16, v218
	v_pk_mul_f32 v[204:205], v[204:205], v[234:235]
	v_add_f32_e32 v3, 1.0, v3
	v_pk_mul_f32 v[136:137], v[136:137], v[204:205]
	v_and_b32_e32 v205, 0xffff0000, v212
	v_rcp_f32_e32 v210, v3
	v_add_f32_e32 v3, v143, v205
	v_mul_f32_e32 v3, 0xbfb8aa3b, v3
	v_exp_f32_e32 v3, v3
	v_add_f32_e32 v207, v130, v208
	v_and_b32_e32 v209, 0xffff0000, v214
	v_mul_f32_e32 v207, 0xbfb8aa3b, v207
	v_add_f32_e32 v3, 1.0, v3
	v_exp_f32_e32 v208, v207
	v_rcp_f32_e32 v207, v3
	v_add_f32_e32 v3, v127, v209
	v_mul_f32_e32 v3, 0xbfb8aa3b, v3
	v_exp_f32_e32 v3, v3
	v_lshlrev_b32_e32 v212, 16, v213
	v_and_b32_e32 v211, 0xffff0000, v216
	v_add_f32_e32 v205, v147, v211
	v_add_f32_e32 v3, 1.0, v3
	v_rcp_f32_e32 v211, v3
	v_add_f32_e32 v3, v144, v212
	v_mul_f32_e32 v3, 0xbfb8aa3b, v3
	v_exp_f32_e32 v3, v3
	v_lshlrev_b32_e32 v225, 16, v215
	v_lshlrev_b32_e32 v214, 16, v217
	v_and_b32_e32 v213, 0xffff0000, v213
	v_add_f32_e32 v3, 1.0, v3
	v_add_f32_e32 v212, v148, v214
	v_rcp_f32_e32 v214, v3
	v_add_f32_e32 v3, v128, v225
	v_mul_f32_e32 v3, 0xbfb8aa3b, v3
	v_add_f32_e32 v213, v145, v213
	v_and_b32_e32 v227, 0xffff0000, v215
	v_lshlrev_b32_e32 v204, 16, v216
	v_and_b32_e32 v215, 0xffff0000, v217
	v_and_b32_e32 v216, 0xffff0000, v218
	v_lshlrev_b32_e32 v217, 16, v219
	v_exp_f32_e32 v3, v3
	v_mul_f32_e32 v213, 0xbfb8aa3b, v213
	v_add_f32_e32 v209, v131, v216
	v_add_f32_e32 v216, v132, v217
	v_exp_f32_e32 v217, v213
	v_add_f32_e32 v204, v146, v204
	v_add_f32_e32 v215, v149, v215
	v_mul_f32_e32 v204, 0xbfb8aa3b, v204
	v_mul_f32_e32 v205, 0xbfb8aa3b, v205
	v_mul_f32_e32 v212, 0xbfb8aa3b, v212
	v_add_f32_e32 v3, 1.0, v3
	v_mul_f32_e32 v213, 0xbfb8aa3b, v215
	v_exp_f32_e32 v204, v204
	v_exp_f32_e32 v205, v205
	v_exp_f32_e32 v212, v212
	v_exp_f32_e32 v213, v213
	v_rcp_f32_e32 v218, v3
	v_add_f32_e32 v3, 1.0, v217
	v_rcp_f32_e32 v215, v3
	v_pk_add_f32 v[212:213], v[212:213], 1.0 op_sel_hi:[1,0]
	v_pk_add_f32 v[204:205], v[204:205], 1.0 op_sel_hi:[1,0]
	v_and_b32_e32 v219, 0xffff0000, v219
	v_pk_mul_f32 v[204:205], v[204:205], v[206:207]
	v_pk_mul_f32 v[206:207], v[212:213], v[214:215]
	v_add_f32_e32 v3, v133, v219
	v_pk_mul_f32 v[124:125], v[124:125], v[206:207]
	v_add_f32_e32 v206, v129, v227
	v_mul_f32_e32 v206, 0xbfb8aa3b, v206
	v_exp_f32_e32 v206, v206
	v_mul_f32_e32 v3, 0xbfb8aa3b, v3
	v_exp_f32_e32 v217, v3
; __device__ __forceinline__ void unpack8(const u32x4 w, float (&v)[8]) { v[0] = bf_lo(w.x); v[1] = bf_hi(w.x); v[2] = bf_lo(w.y); v[3] = bf_hi(w.y); v[4] = bf_lo(w.z); v[5] = bf_hi(w.z); v[6] = bf_lo(w.w); v[7] = bf_hi(w.w); }
;     __device__ __forceinline__ void after(int te, f32x4 (&acc)[2][2][4][2], const Unit& u, int wr, int wc, int fr, int fq) const {
;     ...
;                     for (int m = 0; m < 4; ++m) { float vs[8], va[8]; unpack8(gs[m], vs); unpack8(ga[m], va);
; #pragma unroll
;                         for (int e = 0; e < 4; ++e) {
;                             acc[ai][bj][m][0][e] *= (1.f + __expf(-(va[e] + a0[e]))) * __builtin_amdgcn_rcpf(1.f + __expf(-(vs[e] + s0[e])));
;                             acc[ai][bj][m][1][e] *= (1.f + __expf(-(va[4 + e] + a1[e]))) * __builtin_amdgcn_rcpf(1.f + __expf(-(vs[4 + e] + s1[e]))); } }
	v_mul_f32_e32 v216, 0xbfb8aa3b, v216
	v_add_f32_e32 v3, 1.0, v206
	v_rcp_f32_e32 v219, v3
	v_lshlrev_b32_e32 v3, 16, v162
	v_mul_f32_e32 v209, 0xbfb8aa3b, v209
	v_exp_f32_e32 v216, v216
	v_add_f32_e32 v3, v142, v3
	v_exp_f32_e32 v209, v209
	v_mul_f32_e32 v3, 0xbfb8aa3b, v3
	v_exp_f32_e32 v3, v3
	v_pk_mul_f32 v[122:123], v[122:123], v[204:205]
	v_pk_add_f32 v[204:205], v[216:217], 1.0 op_sel_hi:[1,0]
	v_pk_add_f32 v[206:207], v[208:209], 1.0 op_sel_hi:[1,0]
	v_pk_mul_f32 v[204:205], v[204:205], v[218:219]
	v_pk_mul_f32 v[206:207], v[206:207], v[210:211]
	v_pk_mul_f32 v[120:121], v[120:121], v[204:205]
	v_and_b32_e32 v204, 0xffff0000, v162
	v_lshlrev_b32_e32 v162, 16, v164
	v_add_f32_e32 v3, 1.0, v3
	v_pk_mul_f32 v[118:119], v[118:119], v[206:207]
	v_lshlrev_b32_e32 v206, 16, v159
	v_and_b32_e32 v210, 0xffff0000, v159
	v_lshlrev_b32_e32 v159, 16, v160
	v_and_b32_e32 v211, 0xffff0000, v160
	v_rcp_f32_e32 v160, v3
	v_add_f32_e32 v3, v126, v162
	v_mul_f32_e32 v3, 0xbfb8aa3b, v3
	v_exp_f32_e32 v3, v3
	v_lshlrev_b32_e32 v205, 16, v163
	v_and_b32_e32 v207, 0xffff0000, v163
	v_and_b32_e32 v163, 0xffff0000, v164
	v_lshlrev_b32_e32 v164, 16, v158
	v_add_f32_e32 v3, 1.0, v3
	v_lshlrev_b32_e32 v208, 16, v165
	v_and_b32_e32 v209, 0xffff0000, v165
	v_and_b32_e32 v165, 0xffff0000, v158
	v_add_f32_e32 v158, v146, v164
	v_rcp_f32_e32 v164, v3
	v_add_f32_e32 v3, v143, v204
	v_mul_f32_e32 v3, 0xbfb8aa3b, v3
	v_exp_f32_e32 v3, v3
	v_lshlrev_b32_e32 v212, 16, v161
	v_and_b32_e32 v213, 0xffff0000, v161
	v_add_f32_e32 v159, v130, v159
	v_add_f32_e32 v3, 1.0, v3
	v_rcp_f32_e32 v161, v3
	v_add_f32_e32 v3, v127, v163
	v_mul_f32_e32 v3, 0xbfb8aa3b, v3
	v_exp_f32_e32 v3, v3
	v_mul_f32_e32 v159, 0xbfb8aa3b, v159
	v_exp_f32_e32 v162, v159
	v_add_f32_e32 v159, v147, v165
	v_add_f32_e32 v3, 1.0, v3
	v_rcp_f32_e32 v165, v3
	v_add_f32_e32 v3, v144, v205
	v_mul_f32_e32 v3, 0xbfb8aa3b, v3
	v_exp_f32_e32 v3, v3
	v_add_f32_e32 v204, v148, v206
	v_add_f32_e32 v207, v145, v207
	v_mul_f32_e32 v207, 0xbfb8aa3b, v207
	v_add_f32_e32 v3, 1.0, v3
	v_rcp_f32_e32 v206, v3
	v_add_f32_e32 v3, v128, v208
	v_mul_f32_e32 v3, 0xbfb8aa3b, v3
	v_exp_f32_e32 v3, v3
	v_add_f32_e32 v205, v132, v212
	v_exp_f32_e32 v207, v207
	v_mul_f32_e32 v205, 0xbfb8aa3b, v205
	v_exp_f32_e32 v208, v205
	v_add_f32_e32 v205, v149, v210
	v_mul_f32_e32 v158, 0xbfb8aa3b, v158
	v_mul_f32_e32 v159, 0xbfb8aa3b, v159
	v_mul_f32_e32 v204, 0xbfb8aa3b, v204
	v_add_f32_e32 v3, 1.0, v3
	v_mul_f32_e32 v205, 0xbfb8aa3b, v205
	v_exp_f32_e32 v158, v158
	v_exp_f32_e32 v159, v159
	v_exp_f32_e32 v204, v204
	v_exp_f32_e32 v205, v205
	v_rcp_f32_e32 v210, v3
	v_add_f32_e32 v3, 1.0, v207
	v_rcp_f32_e32 v207, v3
	v_pk_add_f32 v[204:205], v[204:205], 1.0 op_sel_hi:[1,0]
	v_pk_add_f32 v[158:159], v[158:159], 1.0 op_sel_hi:[1,0]
	v_add_f32_e32 v3, v133, v213
	v_pk_mul_f32 v[158:159], v[158:159], v[160:161]
	v_pk_mul_f32 v[160:161], v[204:205], v[206:207]
	v_mul_f32_e32 v3, 0xbfb8aa3b, v3
	v_pk_mul_f32 v[116:117], v[116:117], v[160:161]
	v_add_f32_e32 v160, v129, v209
	v_mul_f32_e32 v160, 0xbfb8aa3b, v160
	v_exp_f32_e32 v160, v160
	v_exp_f32_e32 v209, v3
	v_add_f32_e32 v163, v131, v211
	v_mul_f32_e32 v163, 0xbfb8aa3b, v163
	v_add_f32_e32 v3, 1.0, v160
	v_rcp_f32_e32 v211, v3
	v_lshlrev_b32_e32 v3, 16, v154
	v_add_f32_e32 v3, v142, v3
	v_exp_f32_e32 v163, v163
	v_mul_f32_e32 v3, 0xbfb8aa3b, v3
	v_exp_f32_e32 v3, v3
	v_pk_mul_f32 v[114:115], v[114:115], v[158:159]
	v_pk_add_f32 v[158:159], v[208:209], 1.0 op_sel_hi:[1,0]
	v_pk_add_f32 v[160:161], v[162:163], 1.0 op_sel_hi:[1,0]
	v_pk_mul_f32 v[158:159], v[158:159], v[210:211]
	v_pk_mul_f32 v[160:161], v[160:161], v[164:165]
	v_pk_mul_f32 v[112:113], v[112:113], v[158:159]
	v_and_b32_e32 v158, 0xffff0000, v154
	v_lshlrev_b32_e32 v154, 16, v156
	v_add_f32_e32 v3, 1.0, v3
	v_pk_mul_f32 v[110:111], v[110:111], v[160:161]
	v_lshlrev_b32_e32 v160, 16, v151
	v_and_b32_e32 v204, 0xffff0000, v151
	v_lshlrev_b32_e32 v151, 16, v152
	v_and_b32_e32 v162, 0xffff0000, v152
	v_rcp_f32_e32 v152, v3
	v_add_f32_e32 v3, v126, v154
	v_mul_f32_e32 v3, 0xbfb8aa3b, v3
	v_exp_f32_e32 v3, v3
	v_lshlrev_b32_e32 v159, 16, v155
	v_and_b32_e32 v161, 0xffff0000, v155
	v_and_b32_e32 v155, 0xffff0000, v156
	v_lshlrev_b32_e32 v156, 16, v150
	v_add_f32_e32 v3, 1.0, v3
	v_lshlrev_b32_e32 v164, 16, v157
	v_and_b32_e32 v165, 0xffff0000, v157
	v_and_b32_e32 v157, 0xffff0000, v150
	v_add_f32_e32 v150, v146, v156
	v_rcp_f32_e32 v156, v3
	v_add_f32_e32 v3, v143, v158
	v_mul_f32_e32 v3, 0xbfb8aa3b, v3
	v_exp_f32_e32 v3, v3
	v_lshlrev_b32_e32 v205, 16, v153
	v_and_b32_e32 v206, 0xffff0000, v153
	v_add_f32_e32 v151, v130, v151
	v_add_f32_e32 v3, 1.0, v3
	v_rcp_f32_e32 v153, v3
	v_add_f32_e32 v3, v127, v155
	v_add_f32_e32 v155, v131, v162
	v_add_co_u32_e32 v162, vcc, s26, v192
	v_mul_f32_e32 v3, 0xbfb8aa3b, v3
	s_nop 0
	v_addc_co_u32_e32 v163, vcc, 0, v193, vcc
	global_load_dwordx4 v[228:231], v[162:163], off
	v_exp_f32_e32 v3, v3
	v_mul_f32_e32 v151, 0xbfb8aa3b, v151
	s_mov_b32 s26, 0x202000
	v_exp_f32_e32 v154, v151
	v_add_f32_e32 v3, 1.0, v3
	v_add_f32_e32 v151, v147, v157
	v_rcp_f32_e32 v157, v3
	v_add_f32_e32 v3, v144, v159
	v_add_co_u32_e32 v162, vcc, s26, v192
	v_mul_f32_e32 v3, 0xbfb8aa3b, v3
	s_nop 0
	v_addc_co_u32_e32 v163, vcc, 0, v193, vcc
	v_exp_f32_e32 v3, v3
	global_load_dwordx4 v[232:235], v[162:163], off
	v_add_f32_e32 v158, v148, v160
	v_add_f32_e32 v161, v145, v161
	v_add_f32_e32 v3, 1.0, v3
	v_rcp_f32_e32 v160, v3
	v_add_f32_e32 v3, v128, v164
	v_mul_f32_e32 v3, 0xbfb8aa3b, v3
	v_exp_f32_e32 v3, v3
	v_mul_f32_e32 v161, 0xbfb8aa3b, v161
	v_add_f32_e32 v159, v132, v205
	v_exp_f32_e32 v161, v161
	v_mul_f32_e32 v159, 0xbfb8aa3b, v159
; __device__ __forceinline__ void unpack8(const u32x4 w, float (&v)[8]) { v[0] = bf_lo(w.x); v[1] = bf_hi(w.x); v[2] = bf_lo(w.y); v[3] = bf_hi(w.y); v[4] = bf_lo(w.z); v[5] = bf_hi(w.z); v[6] = bf_lo(w.w); v[7] = bf_hi(w.w); }
;     __device__ __forceinline__ void after(int te, f32x4 (&acc)[2][2][4][2], const Unit& u, int wr, int wc, int fr, int fq) const {
;     ...
;                     for (int m = 0; m < 4; ++m) { const size_t r = (size_t)(row0 + ai * HALF + m * 16); gs[m] = *(const u32x4*)(proj + r * LDP + PGS + c); ga[m] = *(const u32x4*)(proj + r * LDP + PGA + c); }
; #pragma unroll
;                     for (int m = 0; m < 4; ++m) { float vs[8], va[8]; unpack8(gs[m], vs); unpack8(ga[m], va);
; #pragma unroll
;                         for (int e = 0; e < 4; ++e) {
;                             acc[ai][bj][m][0][e] *= (1.f + __expf(-(va[e] + a0[e]))) * __builtin_amdgcn_rcpf(1.f + __expf(-(vs[e] + s0[e])));
;                             acc[ai][bj][m][1][e] *= (1.f + __expf(-(va[4 + e] + a1[e]))) * __builtin_amdgcn_rcpf(1.f + __expf(-(vs[4 + e] + s1[e]))); } }
	v_exp_f32_e32 v162, v159
	v_add_f32_e32 v159, v149, v204
	v_mul_f32_e32 v150, 0xbfb8aa3b, v150
	v_mul_f32_e32 v151, 0xbfb8aa3b, v151
	v_mul_f32_e32 v158, 0xbfb8aa3b, v158
	v_add_f32_e32 v3, 1.0, v3
	v_mul_f32_e32 v159, 0xbfb8aa3b, v159
	v_exp_f32_e32 v150, v150
	v_exp_f32_e32 v151, v151
	v_exp_f32_e32 v158, v158
	v_exp_f32_e32 v159, v159
	v_rcp_f32_e32 v164, v3
	v_add_f32_e32 v3, 1.0, v161
	v_rcp_f32_e32 v161, v3
	v_pk_add_f32 v[158:159], v[158:159], 1.0 op_sel_hi:[1,0]
	v_pk_add_f32 v[150:151], v[150:151], 1.0 op_sel_hi:[1,0]
	v_add_f32_e32 v3, v133, v206
	v_pk_mul_f32 v[150:151], v[150:151], v[152:153]
	v_pk_mul_f32 v[152:153], v[158:159], v[160:161]
	v_mul_f32_e32 v3, 0xbfb8aa3b, v3
	v_pk_mul_f32 v[108:109], v[108:109], v[152:153]
	v_add_f32_e32 v152, v129, v165
	v_mul_f32_e32 v152, 0xbfb8aa3b, v152
	v_exp_f32_e32 v152, v152
	v_exp_f32_e32 v163, v3
	v_mul_f32_e32 v155, 0xbfb8aa3b, v155
	v_exp_f32_e32 v155, v155
	v_add_f32_e32 v3, 1.0, v152
	v_rcp_f32_e32 v165, v3
	s_mov_b64 s[26:27], 0x200000
	v_lshl_add_u64 v[218:219], v[192:193], 0, s[26:27]
	s_mov_b64 s[26:27], 0x202000
	v_pk_mul_f32 v[106:107], v[106:107], v[150:151]
	v_pk_add_f32 v[150:151], v[162:163], 1.0 op_sel_hi:[1,0]
	v_lshl_add_u64 v[216:217], v[192:193], 0, s[26:27]
	s_mov_b64 s[26:27], 0x240000
	v_pk_mul_f32 v[150:151], v[150:151], v[164:165]
	v_lshl_add_u64 v[204:205], v[192:193], 0, s[26:27]
	s_mov_b32 s26, 0x240000
	v_pk_add_f32 v[152:153], v[154:155], 1.0 op_sel_hi:[1,0]
	v_pk_mul_f32 v[104:105], v[104:105], v[150:151]
	v_add_co_u32_e32 v150, vcc, s26, v192
	s_mov_b64 s[26:27], 0x242000
	v_pk_mul_f32 v[152:153], v[152:153], v[156:157]
	v_addc_co_u32_e32 v151, vcc, 0, v193, vcc
	v_lshl_add_u64 v[206:207], v[192:193], 0, s[26:27]
	s_mov_b32 s26, 0x242000
	v_pk_mul_f32 v[102:103], v[102:103], v[152:153]
	v_add_co_u32_e32 v152, vcc, s26, v192
	s_mov_b64 s[26:27], 0x280000
	s_nop 0
	v_addc_co_u32_e32 v153, vcc, 0, v193, vcc
	global_load_dwordx4 v[236:239], v[150:151], off
	global_load_dwordx4 v[240:243], v[152:153], off
	s_waitcnt vmcnt(3)
	v_lshlrev_b32_e32 v3, 16, v228
	v_add_f32_e32 v3, v142, v3
	v_mul_f32_e32 v3, 0xbfb8aa3b, v3
	v_exp_f32_e32 v3, v3
	v_lshlrev_b32_e32 v227, 16, v229
	v_and_b32_e32 v245, 0xffff0000, v229
	v_lshlrev_b32_e32 v229, 16, v230
	v_add_f32_e32 v3, 1.0, v3
	v_and_b32_e32 v246, 0xffff0000, v230
	v_rcp_f32_e32 v230, v3
	v_add_f32_e32 v3, v126, v229
	v_mul_f32_e32 v3, 0xbfb8aa3b, v3
	v_exp_f32_e32 v3, v3
	v_lshl_add_u64 v[208:209], v[192:193], 0, s[26:27]
	s_mov_b32 s26, 0x280000
	v_add_co_u32_e32 v150, vcc, s26, v192
	s_mov_b64 s[26:27], 0x282000
	s_nop 0
	v_addc_co_u32_e32 v151, vcc, 0, v193, vcc
	v_lshl_add_u64 v[210:211], v[192:193], 0, s[26:27]
	s_mov_b32 s26, 0x282000
	v_add_co_u32_e32 v152, vcc, s26, v192
	v_and_b32_e32 v225, 0xffff0000, v228
	v_add_f32_e32 v3, 1.0, v3
	v_addc_co_u32_e32 v153, vcc, 0, v193, vcc
	global_load_dwordx4 v[162:165], v[150:151], off
	global_load_dwordx4 v[158:161], v[152:153], off
	v_lshlrev_b32_e32 v247, 16, v231
	v_and_b32_e32 v251, 0xffff0000, v231
	s_waitcnt vmcnt(4)
	v_lshlrev_b32_e32 v228, 16, v232
	v_and_b32_e32 v231, 0xffff0000, v232
	v_lshlrev_b32_e32 v248, 16, v233
	v_and_b32_e32 v249, 0xffff0000, v233
	v_lshlrev_b32_e32 v232, 16, v234
	v_and_b32_e32 v233, 0xffff0000, v234
	v_rcp_f32_e32 v234, v3
	v_add_f32_e32 v3, v143, v225
	v_mul_f32_e32 v3, 0xbfb8aa3b, v3
	v_exp_f32_e32 v3, v3
	v_add_f32_e32 v225, v147, v231
	v_lshlrev_b32_e32 v250, 16, v235
	v_and_b32_e32 v253, 0xffff0000, v235
	v_add_f32_e32 v3, 1.0, v3
	v_rcp_f32_e32 v231, v3
	v_add_f32_e32 v3, v127, v246
	v_mul_f32_e32 v3, 0xbfb8aa3b, v3
	v_exp_f32_e32 v3, v3
	v_add_f32_e32 v229, v130, v232
	v_mul_f32_e32 v229, 0xbfb8aa3b, v229
	v_mul_f32_e32 v225, 0xbfb8aa3b, v225
	v_add_f32_e32 v3, 1.0, v3
	v_rcp_f32_e32 v235, v3
	v_add_f32_e32 v3, v144, v227
	v_mul_f32_e32 v3, 0xbfb8aa3b, v3
	v_exp_f32_e32 v3, v3
	v_exp_f32_e32 v232, v229
	v_exp_f32_e32 v229, v225
	v_add_f32_e32 v225, v131, v233
	v_mul_f32_e32 v225, 0xbfb8aa3b, v225
	v_exp_f32_e32 v233, v225
	v_add_f32_e32 v225, v148, v248
	v_mul_f32_e32 v225, 0xbfb8aa3b, v225
	v_add_f32_e32 v3, 1.0, v3
	v_exp_f32_e32 v246, v225
	v_rcp_f32_e32 v248, v3
	v_add_f32_e32 v3, v128, v247
	v_add_f32_e32 v225, v132, v250
	v_mul_f32_e32 v3, 0xbfb8aa3b, v3
	v_mul_f32_e32 v225, 0xbfb8aa3b, v225
	v_add_f32_e32 v227, v145, v245
	v_exp_f32_e32 v3, v3
	v_exp_f32_e32 v250, v225
	v_add_f32_e32 v225, v149, v249
	v_mul_f32_e32 v227, 0xbfb8aa3b, v227
	v_exp_f32_e32 v227, v227
	v_mul_f32_e32 v225, 0xbfb8aa3b, v225
	v_exp_f32_e32 v247, v225
	v_add_f32_e32 v225, v129, v251
	v_mul_f32_e32 v225, 0xbfb8aa3b, v225
	v_add_f32_e32 v3, 1.0, v3
	v_exp_f32_e32 v225, v225
	v_rcp_f32_e32 v252, v3
	v_add_f32_e32 v3, 1.0, v227
	v_add_f32_e32 v228, v146, v228
	v_rcp_f32_e32 v249, v3
	v_add_f32_e32 v3, v133, v253
	v_mul_f32_e32 v228, 0xbfb8aa3b, v228
	v_mul_f32_e32 v3, 0xbfb8aa3b, v3
	v_exp_f32_e32 v228, v228
	v_exp_f32_e32 v251, v3
	v_add_f32_e32 v3, 1.0, v225
	v_rcp_f32_e32 v253, v3
	s_waitcnt vmcnt(3)
; __device__ __forceinline__ void unpack8(const u32x4 w, float (&v)[8]) { v[0] = bf_lo(w.x); v[1] = bf_hi(w.x); v[2] = bf_lo(w.y); v[3] = bf_hi(w.y); v[4] = bf_lo(w.z); v[5] = bf_hi(w.z); v[6] = bf_lo(w.w); v[7] = bf_hi(w.w); }
;     __device__ __forceinline__ void after(int te, f32x4 (&acc)[2][2][4][2], const Unit& u, int wr, int wc, int fr, int fq) const {
;     ...
;                     for (int m = 0; m < 4; ++m) { const size_t r = (size_t)(row0 + ai * HALF + m * 16); gs[m] = *(const u32x4*)(proj + r * LDP + PGS + c); ga[m] = *(const u32x4*)(proj + r * LDP + PGA + c); }
; #pragma unroll
;                     for (int m = 0; m < 4; ++m) { float vs[8], va[8]; unpack8(gs[m], vs); unpack8(ga[m], va);
; #pragma unroll
;                         for (int e = 0; e < 4; ++e) {
;                             acc[ai][bj][m][0][e] *= (1.f + __expf(-(va[e] + a0[e]))) * __builtin_amdgcn_rcpf(1.f + __expf(-(vs[e] + s0[e])));
;                             acc[ai][bj][m][1][e] *= (1.f + __expf(-(va[4 + e] + a1[e]))) * __builtin_amdgcn_rcpf(1.f + __expf(-(vs[4 + e] + s1[e]))); } }
	v_lshlrev_b32_e32 v3, 16, v236
	v_add_f32_e32 v3, v142, v3
	v_mul_f32_e32 v3, 0xbfb8aa3b, v3
	v_pk_add_f32 v[228:229], v[228:229], 1.0 op_sel_hi:[1,0]
	v_exp_f32_e32 v3, v3
	v_pk_add_f32 v[246:247], v[246:247], 1.0 op_sel_hi:[1,0]
	v_pk_mul_f32 v[228:229], v[228:229], v[230:231]
	v_pk_mul_f32 v[230:231], v[246:247], v[248:249]
	v_pk_mul_f32 v[98:99], v[98:99], v[228:229]
	v_pk_add_f32 v[228:229], v[250:251], 1.0 op_sel_hi:[1,0]
	v_pk_mul_f32 v[100:101], v[100:101], v[230:231]
	v_pk_add_f32 v[230:231], v[232:233], 1.0 op_sel_hi:[1,0]
	v_pk_mul_f32 v[228:229], v[228:229], v[252:253]
	v_pk_mul_f32 v[230:231], v[230:231], v[234:235]
	v_pk_mul_f32 v[96:97], v[96:97], v[228:229]
	v_lshlrev_b32_e32 v229, 16, v238
	v_add_f32_e32 v3, 1.0, v3
	v_pk_mul_f32 v[94:95], v[94:95], v[230:231]
	v_rcp_f32_e32 v230, v3
	v_add_f32_e32 v3, v126, v229
	v_mul_f32_e32 v3, 0xbfb8aa3b, v3
	v_exp_f32_e32 v3, v3
	v_and_b32_e32 v225, 0xffff0000, v236
	s_mov_b64 s[26:27], 0x2c0000
	v_lshl_add_u64 v[212:213], v[192:193], 0, s[26:27]
	v_add_f32_e32 v3, 1.0, v3
	v_rcp_f32_e32 v234, v3
	v_add_f32_e32 v3, v143, v225
	v_mul_f32_e32 v3, 0xbfb8aa3b, v3
	v_exp_f32_e32 v3, v3
	s_mov_b32 s26, 0x2c0000
	v_add_co_u32_e32 v150, vcc, s26, v192
	s_mov_b64 s[26:27], 0x2c2000
	s_nop 0
	v_addc_co_u32_e32 v151, vcc, 0, v193, vcc
	v_lshl_add_u64 v[214:215], v[192:193], 0, s[26:27]
	s_mov_b32 s26, 0x2c2000
	v_and_b32_e32 v233, 0xffff0000, v238
	s_waitcnt vmcnt(2)
	v_and_b32_e32 v231, 0xffff0000, v240
	v_add_f32_e32 v3, 1.0, v3
	v_add_co_u32_e32 v152, vcc, s26, v192
	v_add_f32_e32 v225, v147, v231
	v_rcp_f32_e32 v231, v3
	v_add_f32_e32 v3, v127, v233
	v_addc_co_u32_e32 v153, vcc, 0, v193, vcc
	v_mul_f32_e32 v3, 0xbfb8aa3b, v3
	global_load_dwordx4 v[154:157], v[150:151], off
	s_nop 0
	global_load_dwordx4 v[150:153], v[152:153], off
	v_exp_f32_e32 v3, v3
	v_lshlrev_b32_e32 v232, 16, v242
	v_add_f32_e32 v229, v130, v232
	v_lshlrev_b32_e32 v227, 16, v237
	v_and_b32_e32 v235, 0xffff0000, v242
	v_mul_f32_e32 v229, 0xbfb8aa3b, v229
	v_mul_f32_e32 v225, 0xbfb8aa3b, v225
	v_add_f32_e32 v3, 1.0, v3
	v_exp_f32_e32 v232, v229
	v_exp_f32_e32 v229, v225
	v_add_f32_e32 v225, v131, v235
	v_rcp_f32_e32 v235, v3
	v_add_f32_e32 v3, v144, v227
	v_mul_f32_e32 v3, 0xbfb8aa3b, v3
	v_exp_f32_e32 v3, v3
	v_lshlrev_b32_e32 v236, 16, v241
	v_mul_f32_e32 v225, 0xbfb8aa3b, v225
	v_exp_f32_e32 v233, v225
	v_add_f32_e32 v225, v148, v236
	v_lshlrev_b32_e32 v245, 16, v239
	v_lshlrev_b32_e32 v228, 16, v240
	v_lshlrev_b32_e32 v240, 16, v243
	v_mul_f32_e32 v225, 0xbfb8aa3b, v225
	v_add_f32_e32 v3, 1.0, v3
	v_and_b32_e32 v237, 0xffff0000, v237
	v_exp_f32_e32 v236, v225
	v_rcp_f32_e32 v238, v3
	v_add_f32_e32 v3, v128, v245
	v_add_f32_e32 v225, v132, v240
	v_and_b32_e32 v246, 0xffff0000, v239
	v_and_b32_e32 v239, 0xffff0000, v241
	v_mul_f32_e32 v3, 0xbfb8aa3b, v3
	v_mul_f32_e32 v225, 0xbfb8aa3b, v225
	v_add_f32_e32 v227, v145, v237
	v_exp_f32_e32 v3, v3
	v_exp_f32_e32 v240, v225
	v_add_f32_e32 v225, v149, v239
	v_mul_f32_e32 v227, 0xbfb8aa3b, v227
	v_exp_f32_e32 v227, v227
	v_mul_f32_e32 v225, 0xbfb8aa3b, v225
	v_exp_f32_e32 v237, v225
	v_add_f32_e32 v225, v129, v246
	v_mul_f32_e32 v225, 0xbfb8aa3b, v225
	v_add_f32_e32 v3, 1.0, v3
	v_exp_f32_e32 v225, v225
	v_and_b32_e32 v241, 0xffff0000, v243
	v_rcp_f32_e32 v242, v3
	v_add_f32_e32 v3, 1.0, v227
	v_rcp_f32_e32 v239, v3
	v_add_f32_e32 v3, v133, v241
	v_add_f32_e32 v228, v146, v228
	v_mul_f32_e32 v3, 0xbfb8aa3b, v3
	v_mul_f32_e32 v228, 0xbfb8aa3b, v228
	v_exp_f32_e32 v241, v3
	v_add_f32_e32 v3, 1.0, v225
	v_exp_f32_e32 v228, v228
	v_rcp_f32_e32 v243, v3
	s_waitcnt vmcnt(3)
	v_lshlrev_b32_e32 v3, 16, v162
	v_add_f32_e32 v3, v142, v3
	v_mul_f32_e32 v3, 0xbfb8aa3b, v3
	v_exp_f32_e32 v3, v3
	v_pk_add_f32 v[236:237], v[236:237], 1.0 op_sel_hi:[1,0]
	v_pk_add_f32 v[228:229], v[228:229], 1.0 op_sel_hi:[1,0]
	v_and_b32_e32 v225, 0xffff0000, v162
	v_pk_mul_f32 v[228:229], v[228:229], v[230:231]
	v_pk_mul_f32 v[230:231], v[236:237], v[238:239]
	v_pk_mul_f32 v[90:91], v[90:91], v[228:229]
	v_pk_mul_f32 v[92:93], v[92:93], v[230:231]
	v_pk_add_f32 v[228:229], v[240:241], 1.0 op_sel_hi:[1,0]
	v_pk_add_f32 v[230:231], v[232:233], 1.0 op_sel_hi:[1,0]
	v_pk_mul_f32 v[228:229], v[228:229], v[242:243]
	v_pk_mul_f32 v[230:231], v[230:231], v[234:235]
	v_lshlrev_b32_e32 v162, 16, v164
	v_add_f32_e32 v3, 1.0, v3
	v_pk_mul_f32 v[88:89], v[88:89], v[228:229]
	v_pk_mul_f32 v[86:87], v[86:87], v[230:231]
	s_waitcnt vmcnt(2)
; __device__ __forceinline__ void unpack8(const u32x4 w, float (&v)[8]) { v[0] = bf_lo(w.x); v[1] = bf_hi(w.x); v[2] = bf_lo(w.y); v[3] = bf_hi(w.y); v[4] = bf_lo(w.z); v[5] = bf_hi(w.z); v[6] = bf_lo(w.w); v[7] = bf_hi(w.w); }
;     __device__ __forceinline__ void after(int te, f32x4 (&acc)[2][2][4][2], const Unit& u, int wr, int wc, int fr, int fq) const {
;     ...
;             for (int bj = 0; bj < 2; ++bj) { const int c = col0 + bj * HALF;
;                 const f32x4 s0 = *(const f32x4*)(gb + c), s1 = *(const f32x4*)(gb + c + 4), a0 = *(const f32x4*)(gb + D_MODEL + c), a1 = *(const f32x4*)(gb + D_MODEL + c + 4);
; #pragma unroll
;                 for (int ai = 0; ai < 2; ++ai) {
;                     u32x4 gs[4], ga[4];
; #pragma unroll
;                     for (int m = 0; m < 4; ++m) { const size_t r = (size_t)(row0 + ai * HALF + m * 16); gs[m] = *(const u32x4*)(proj + r * LDP + PGS + c); ga[m] = *(const u32x4*)(proj + r * LDP + PGA + c); }
; #pragma unroll
;                     for (int m = 0; m < 4; ++m) { float vs[8], va[8]; unpack8(gs[m], vs); unpack8(ga[m], va);
; #pragma unroll
;                         for (int e = 0; e < 4; ++e) {
;                             acc[ai][bj][m][0][e] *= (1.f + __expf(-(va[e] + a0[e]))) * __builtin_amdgcn_rcpf(1.f + __expf(-(vs[e] + s0[e])));
;                             acc[ai][bj][m][1][e] *= (1.f + __expf(-(va[4 + e] + a1[e]))) * __builtin_amdgcn_rcpf(1.f + __expf(-(vs[4 + e] + s1[e]))); } }
	v_lshlrev_b32_e32 v228, 16, v159
	v_and_b32_e32 v234, 0xffff0000, v159
	v_lshlrev_b32_e32 v159, 16, v160
	v_and_b32_e32 v230, 0xffff0000, v160
	v_rcp_f32_e32 v160, v3
	v_add_f32_e32 v3, v126, v162
	v_mul_f32_e32 v3, 0xbfb8aa3b, v3
	v_exp_f32_e32 v3, v3
	v_lshlrev_b32_e32 v227, 16, v163
	v_and_b32_e32 v229, 0xffff0000, v163
	v_and_b32_e32 v163, 0xffff0000, v164
	v_lshlrev_b32_e32 v164, 16, v158
	v_add_f32_e32 v3, 1.0, v3
	v_lshlrev_b32_e32 v231, 16, v165
	v_and_b32_e32 v233, 0xffff0000, v165
	v_and_b32_e32 v165, 0xffff0000, v158
	v_add_f32_e32 v158, v146, v164
	v_rcp_f32_e32 v164, v3
	v_add_f32_e32 v3, v143, v225
	v_mul_f32_e32 v3, 0xbfb8aa3b, v3
	v_exp_f32_e32 v3, v3
	v_lshlrev_b32_e32 v232, 16, v161
	v_and_b32_e32 v235, 0xffff0000, v161
	v_add_f32_e32 v159, v130, v159
	v_add_f32_e32 v3, 1.0, v3
	v_rcp_f32_e32 v161, v3
	v_add_f32_e32 v3, v127, v163
	v_mul_f32_e32 v3, 0xbfb8aa3b, v3
	v_exp_f32_e32 v3, v3
	v_mul_f32_e32 v159, 0xbfb8aa3b, v159
	v_exp_f32_e32 v162, v159
	v_add_f32_e32 v159, v147, v165
	v_add_f32_e32 v3, 1.0, v3
	v_rcp_f32_e32 v165, v3
	v_add_f32_e32 v3, v144, v227
	v_mul_f32_e32 v3, 0xbfb8aa3b, v3
	v_exp_f32_e32 v3, v3
	v_add_f32_e32 v163, v131, v230
	v_add_f32_e32 v225, v148, v228
	v_add_f32_e32 v227, v145, v229
	v_add_f32_e32 v3, 1.0, v3
	v_rcp_f32_e32 v230, v3
	v_add_f32_e32 v3, v128, v231
	v_mul_f32_e32 v3, 0xbfb8aa3b, v3
	v_mul_f32_e32 v225, 0xbfb8aa3b, v225
	v_exp_f32_e32 v3, v3
	v_mul_f32_e32 v227, 0xbfb8aa3b, v227
	v_exp_f32_e32 v228, v225
	v_add_f32_e32 v225, v132, v232
	v_exp_f32_e32 v227, v227
	v_mul_f32_e32 v225, 0xbfb8aa3b, v225
	v_exp_f32_e32 v232, v225
	v_add_f32_e32 v225, v149, v234
	v_mul_f32_e32 v158, 0xbfb8aa3b, v158
	v_mul_f32_e32 v159, 0xbfb8aa3b, v159
	v_add_f32_e32 v3, 1.0, v3
	v_mul_f32_e32 v225, 0xbfb8aa3b, v225
	v_exp_f32_e32 v158, v158
	v_exp_f32_e32 v159, v159
	v_exp_f32_e32 v229, v225
	v_rcp_f32_e32 v234, v3
	v_add_f32_e32 v3, 1.0, v227
	v_rcp_f32_e32 v231, v3
	v_pk_add_f32 v[228:229], v[228:229], 1.0 op_sel_hi:[1,0]
	v_pk_add_f32 v[158:159], v[158:159], 1.0 op_sel_hi:[1,0]
	v_add_f32_e32 v3, v133, v235
	v_pk_mul_f32 v[158:159], v[158:159], v[160:161]
	v_pk_mul_f32 v[160:161], v[228:229], v[230:231]
	v_mul_f32_e32 v3, 0xbfb8aa3b, v3
	v_pk_mul_f32 v[84:85], v[84:85], v[160:161]
	v_add_f32_e32 v160, v129, v233
	v_mul_f32_e32 v160, 0xbfb8aa3b, v160
	v_exp_f32_e32 v160, v160
	v_exp_f32_e32 v233, v3
	s_waitcnt vmcnt(1)
	v_lshlrev_b32_e32 v225, 16, v155
	v_and_b32_e32 v227, 0xffff0000, v155
	v_add_f32_e32 v3, 1.0, v160
	v_rcp_f32_e32 v235, v3
	v_lshlrev_b32_e32 v3, 16, v154
	v_add_f32_e32 v3, v142, v3
	v_mul_f32_e32 v3, 0xbfb8aa3b, v3
	v_exp_f32_e32 v3, v3
	v_lshlrev_b32_e32 v155, 16, v156
	v_and_b32_e32 v236, 0xffff0000, v156
	s_waitcnt vmcnt(0)
	v_lshlrev_b32_e32 v156, 16, v150
	v_add_f32_e32 v3, 1.0, v3
	v_mul_f32_e32 v163, 0xbfb8aa3b, v163
	v_add_f32_e32 v142, v146, v156
	v_rcp_f32_e32 v146, v3
	v_add_f32_e32 v3, v126, v155
	v_exp_f32_e32 v163, v163
	v_mul_f32_e32 v3, 0xbfb8aa3b, v3
	v_exp_f32_e32 v3, v3
	v_pk_mul_f32 v[82:83], v[82:83], v[158:159]
	v_pk_add_f32 v[158:159], v[232:233], 1.0 op_sel_hi:[1,0]
	v_pk_add_f32 v[160:161], v[162:163], 1.0 op_sel_hi:[1,0]
	v_pk_mul_f32 v[158:159], v[158:159], v[234:235]
	v_pk_mul_f32 v[160:161], v[160:161], v[164:165]
	v_and_b32_e32 v150, 0xffff0000, v150
	v_lshlrev_b32_e32 v239, 16, v151
	v_and_b32_e32 v240, 0xffff0000, v151
	v_lshlrev_b32_e32 v151, 16, v152
	global_load_dwordx4 v[228:231], v[192:193], off offset:256
	global_load_dwordx4 v[232:235], v[202:203], off offset:256
	v_add_f32_e32 v3, 1.0, v3
	v_pk_mul_f32 v[80:81], v[80:81], v[158:159]
	v_pk_mul_f32 v[78:79], v[78:79], v[160:161]
	v_and_b32_e32 v241, 0xffff0000, v152
	v_lshlrev_b32_e32 v242, 16, v153
	v_and_b32_e32 v243, 0xffff0000, v153
	v_add_f32_e32 v126, v130, v151
	v_rcp_f32_e32 v130, v3
	v_add_f32_e32 v3, v147, v150
	global_load_dwordx4 v[150:153], v[196:197], off offset:528
	global_load_dwordx4 v[158:161], v[196:197], off offset:512
	v_and_b32_e32 v154, 0xffff0000, v154
	v_lshlrev_b32_e32 v237, 16, v157
	v_and_b32_e32 v238, 0xffff0000, v157
	v_add_f32_e32 v143, v143, v154
	global_load_dwordx4 v[154:157], v[198:199], off offset:528
	global_load_dwordx4 v[162:165], v[198:199], off offset:512
	v_mul_f32_e32 v143, 0xbfb8aa3b, v143
	v_exp_f32_e32 v147, v143
	v_mul_f32_e32 v3, 0xbfb8aa3b, v3
	v_exp_f32_e32 v143, v3
	v_add_f32_e32 v145, v145, v227
	v_add_f32_e32 v3, 1.0, v147
	v_rcp_f32_e32 v147, v3
	v_add_f32_e32 v3, v127, v236
	v_mul_f32_e32 v3, 0xbfb8aa3b, v3
	v_exp_f32_e32 v3, v3
	v_add_f32_e32 v127, v131, v241
	v_mul_f32_e32 v145, 0xbfb8aa3b, v145
	v_add_f32_e32 v129, v129, v238
	v_add_f32_e32 v3, 1.0, v3
	v_rcp_f32_e32 v131, v3
	v_add_f32_e32 v3, v144, v225
	v_mul_f32_e32 v3, 0xbfb8aa3b, v3
	v_exp_f32_e32 v3, v3
	v_add_f32_e32 v144, v148, v239
	v_mul_f32_e32 v129, 0xbfb8aa3b, v129
	v_mul_f32_e32 v142, 0xbfb8aa3b, v142
	v_add_f32_e32 v3, 1.0, v3
	v_rcp_f32_e32 v148, v3
	v_add_f32_e32 v3, v128, v237
	v_mul_f32_e32 v3, 0xbfb8aa3b, v3
	v_exp_f32_e32 v3, v3
	v_add_f32_e32 v128, v132, v242
	v_add_f32_e32 v132, v149, v240
	v_exp_f32_e32 v149, v145
	v_add_f32_e32 v3, 1.0, v3
	v_mul_f32_e32 v132, 0xbfb8aa3b, v132
	v_exp_f32_e32 v145, v132
	v_rcp_f32_e32 v132, v3
	v_add_f32_e32 v3, 1.0, v149
	v_rcp_f32_e32 v149, v3
	v_add_f32_e32 v3, v133, v243
	v_exp_f32_e32 v133, v129
	v_mul_f32_e32 v126, 0xbfb8aa3b, v126
	v_mul_f32_e32 v127, 0xbfb8aa3b, v127
	v_mul_f32_e32 v144, 0xbfb8aa3b, v144
	v_mul_f32_e32 v128, 0xbfb8aa3b, v128
	v_mul_f32_e32 v3, 0xbfb8aa3b, v3
	v_exp_f32_e32 v142, v142
	v_exp_f32_e32 v126, v126
	v_exp_f32_e32 v127, v127
	v_exp_f32_e32 v144, v144
	v_exp_f32_e32 v128, v128
	v_exp_f32_e32 v129, v3
	v_add_f32_e32 v3, 1.0, v133
	v_rcp_f32_e32 v133, v3
	v_pk_add_f32 v[144:145], v[144:145], 1.0 op_sel_hi:[1,0]
	v_pk_add_f32 v[142:143], v[142:143], 1.0 op_sel_hi:[1,0]
	v_pk_add_f32 v[128:129], v[128:129], 1.0 op_sel_hi:[1,0]
	v_pk_add_f32 v[126:127], v[126:127], 1.0 op_sel_hi:[1,0]
	v_pk_mul_f32 v[142:143], v[142:143], v[146:147]
	v_pk_mul_f32 v[144:145], v[144:145], v[148:149]
	v_pk_mul_f32 v[126:127], v[126:127], v[130:131]
	v_pk_mul_f32 v[128:129], v[128:129], v[132:133]
	v_pk_mul_f32 v[76:77], v[76:77], v[144:145]
	v_pk_mul_f32 v[74:75], v[74:75], v[142:143]
	v_pk_mul_f32 v[72:73], v[72:73], v[128:129]
	v_pk_mul_f32 v[70:71], v[70:71], v[126:127]
	global_load_dwordx4 v[196:199], v[4:5], off offset:256
	global_load_dwordx4 v[236:239], v[186:187], off offset:256
	global_load_dwordx4 v[146:149], v[188:189], off offset:256
	global_load_dwordx4 v[142:145], v[190:191], off offset:256
	global_load_dwordx4 v[130:133], v[194:195], off offset:256
	global_load_dwordx4 v[126:129], v[200:201], off offset:256
	s_waitcnt vmcnt(11)
; __device__ __forceinline__ void unpack8(const u32x4 w, float (&v)[8]) { v[0] = bf_lo(w.x); v[1] = bf_hi(w.x); v[2] = bf_lo(w.y); v[3] = bf_hi(w.y); v[4] = bf_lo(w.z); v[5] = bf_hi(w.z); v[6] = bf_lo(w.w); v[7] = bf_hi(w.w); }
;     __device__ __forceinline__ void after(int te, f32x4 (&acc)[2][2][4][2], const Unit& u, int wr, int wc, int fr, int fq) const {
;     ...
;                     for (int m = 0; m < 4; ++m) { float vs[8], va[8]; unpack8(gs[m], vs); unpack8(ga[m], va);
; #pragma unroll
;                         for (int e = 0; e < 4; ++e) {
;                             acc[ai][bj][m][0][e] *= (1.f + __expf(-(va[e] + a0[e]))) * __builtin_amdgcn_rcpf(1.f + __expf(-(vs[e] + s0[e])));
;                             acc[ai][bj][m][1][e] *= (1.f + __expf(-(va[4 + e] + a1[e]))) * __builtin_amdgcn_rcpf(1.f + __expf(-(vs[4 + e] + s1[e]))); } }
	v_lshlrev_b32_e32 v3, 16, v228
	v_lshlrev_b32_e32 v187, 16, v230
	v_and_b32_e32 v5, 0xffff0000, v228
	s_waitcnt vmcnt(10)
	v_lshlrev_b32_e32 v188, 16, v234
	v_and_b32_e32 v189, 0xffff0000, v230
	v_lshlrev_b32_e32 v192, 16, v229
	v_and_b32_e32 v191, 0xffff0000, v232
	v_lshlrev_b32_e32 v195, 16, v231
	v_lshlrev_b32_e32 v194, 16, v233
	v_and_b32_e32 v193, 0xffff0000, v229
	v_lshlrev_b32_e32 v203, 16, v235
	s_waitcnt vmcnt(8)
	v_add_f32_e32 v3, v158, v3
	v_mul_f32_e32 v3, 0xbfb8aa3b, v3
	v_exp_f32_e32 v3, v3
	v_add_f32_e32 v193, v161, v193
	v_mul_f32_e32 v193, 0xbfb8aa3b, v193
	v_lshlrev_b32_e32 v4, 16, v232
	v_add_f32_e32 v3, 1.0, v3
	v_rcp_f32_e32 v186, v3
	v_add_f32_e32 v3, v150, v187
	v_mul_f32_e32 v3, 0xbfb8aa3b, v3
	v_exp_f32_e32 v3, v3
	s_waitcnt vmcnt(7)
	v_add_f32_e32 v187, v154, v188
	v_mul_f32_e32 v187, 0xbfb8aa3b, v187
	v_exp_f32_e32 v188, v187
	v_add_f32_e32 v3, 1.0, v3
	v_rcp_f32_e32 v190, v3
	v_add_f32_e32 v3, v159, v5
	v_mul_f32_e32 v3, 0xbfb8aa3b, v3
	v_exp_f32_e32 v3, v3
	s_waitcnt vmcnt(6)
	v_add_f32_e32 v5, v163, v191
	v_and_b32_e32 v202, 0xffff0000, v233
	v_and_b32_e32 v200, 0xffff0000, v234
	v_add_f32_e32 v3, 1.0, v3
	v_rcp_f32_e32 v187, v3
	v_add_f32_e32 v3, v151, v189
	v_mul_f32_e32 v3, 0xbfb8aa3b, v3
	v_exp_f32_e32 v3, v3
	v_add_f32_e32 v4, v162, v4
	v_add_f32_e32 v189, v155, v200
	v_mul_f32_e32 v4, 0xbfb8aa3b, v4
	v_add_f32_e32 v3, 1.0, v3
	v_rcp_f32_e32 v191, v3
	v_add_f32_e32 v3, v160, v192
	v_mul_f32_e32 v3, 0xbfb8aa3b, v3
	v_exp_f32_e32 v3, v3
	v_add_f32_e32 v192, v164, v194
	v_mul_f32_e32 v5, 0xbfb8aa3b, v5
	v_mul_f32_e32 v192, 0xbfb8aa3b, v192
	v_add_f32_e32 v3, 1.0, v3
	v_rcp_f32_e32 v194, v3
	v_add_f32_e32 v3, v152, v195
	v_mul_f32_e32 v3, 0xbfb8aa3b, v3
	v_exp_f32_e32 v3, v3
	v_add_f32_e32 v195, v156, v203
	v_exp_f32_e32 v203, v193
	v_mul_f32_e32 v195, 0xbfb8aa3b, v195
	v_exp_f32_e32 v200, v195
	v_add_f32_e32 v195, v165, v202
	v_add_f32_e32 v3, 1.0, v3
	v_mul_f32_e32 v193, 0xbfb8aa3b, v195
	v_exp_f32_e32 v4, v4
	v_exp_f32_e32 v5, v5
	v_exp_f32_e32 v192, v192
	v_exp_f32_e32 v193, v193
	v_rcp_f32_e32 v202, v3
	v_add_f32_e32 v3, 1.0, v203
	v_rcp_f32_e32 v195, v3
	v_pk_add_f32 v[192:193], v[192:193], 1.0 op_sel_hi:[1,0]
	v_pk_add_f32 v[4:5], v[4:5], 1.0 op_sel_hi:[1,0]
	v_and_b32_e32 v201, 0xffff0000, v231
	v_pk_mul_f32 v[4:5], v[4:5], v[186:187]
	v_pk_mul_f32 v[186:187], v[192:193], v[194:195]
	v_and_b32_e32 v225, 0xffff0000, v235
	v_pk_mul_f32 v[68:69], v[68:69], v[186:187]
	v_add_f32_e32 v186, v153, v201
	v_mul_f32_e32 v186, 0xbfb8aa3b, v186
	v_exp_f32_e32 v186, v186
	v_add_f32_e32 v3, v157, v225
	v_mul_f32_e32 v3, 0xbfb8aa3b, v3
	v_exp_f32_e32 v201, v3
	v_add_f32_e32 v3, 1.0, v186
	v_mul_f32_e32 v189, 0xbfb8aa3b, v189
	v_rcp_f32_e32 v203, v3
	s_waitcnt vmcnt(5)
	v_lshlrev_b32_e32 v3, 16, v196
	v_exp_f32_e32 v189, v189
	v_add_f32_e32 v3, v158, v3
	v_mul_f32_e32 v3, 0xbfb8aa3b, v3
	v_exp_f32_e32 v3, v3
	v_pk_add_f32 v[186:187], v[188:189], 1.0 op_sel_hi:[1,0]
	v_pk_mul_f32 v[66:67], v[66:67], v[4:5]
	v_pk_mul_f32 v[186:187], v[186:187], v[190:191]
	v_add_f32_e32 v3, 1.0, v3
	v_pk_mul_f32 v[62:63], v[62:63], v[186:187]
	v_lshlrev_b32_e32 v187, 16, v198
	v_rcp_f32_e32 v186, v3
	v_add_f32_e32 v3, v150, v187
	v_mul_f32_e32 v3, 0xbfb8aa3b, v3
	v_exp_f32_e32 v3, v3
	v_pk_add_f32 v[4:5], v[200:201], 1.0 op_sel_hi:[1,0]
	s_waitcnt vmcnt(4)
	v_lshlrev_b32_e32 v188, 16, v238
	v_pk_mul_f32 v[4:5], v[4:5], v[202:203]
	v_add_f32_e32 v3, 1.0, v3
	v_pk_mul_f32 v[64:65], v[64:65], v[4:5]
	v_and_b32_e32 v5, 0xffff0000, v196
	v_rcp_f32_e32 v190, v3
	v_add_f32_e32 v3, v159, v5
	v_mul_f32_e32 v3, 0xbfb8aa3b, v3
	v_exp_f32_e32 v3, v3
	v_add_f32_e32 v187, v154, v188
	v_and_b32_e32 v189, 0xffff0000, v198
	v_mul_f32_e32 v187, 0xbfb8aa3b, v187
	v_add_f32_e32 v3, 1.0, v3
	v_exp_f32_e32 v188, v187
	v_rcp_f32_e32 v187, v3
	v_add_f32_e32 v3, v151, v189
	v_mul_f32_e32 v3, 0xbfb8aa3b, v3
	v_exp_f32_e32 v3, v3
	v_lshlrev_b32_e32 v192, 16, v197
	v_and_b32_e32 v191, 0xffff0000, v236
	v_add_f32_e32 v5, v163, v191
	v_add_f32_e32 v3, 1.0, v3
	v_rcp_f32_e32 v191, v3
	v_add_f32_e32 v3, v160, v192
	v_mul_f32_e32 v3, 0xbfb8aa3b, v3
	v_exp_f32_e32 v3, v3
	v_lshlrev_b32_e32 v195, 16, v199
	v_lshlrev_b32_e32 v194, 16, v237
	v_and_b32_e32 v193, 0xffff0000, v197
	v_add_f32_e32 v3, 1.0, v3
	v_add_f32_e32 v192, v164, v194
	v_rcp_f32_e32 v194, v3
	v_add_f32_e32 v3, v152, v195
	v_mul_f32_e32 v3, 0xbfb8aa3b, v3
	v_add_f32_e32 v193, v161, v193
	v_and_b32_e32 v197, 0xffff0000, v199
	v_lshlrev_b32_e32 v199, 16, v239
	v_exp_f32_e32 v3, v3
	v_mul_f32_e32 v193, 0xbfb8aa3b, v193
	v_add_f32_e32 v195, v156, v199
	v_exp_f32_e32 v199, v193
	v_lshlrev_b32_e32 v4, 16, v236
	v_and_b32_e32 v198, 0xffff0000, v237
	v_and_b32_e32 v196, 0xffff0000, v238
	v_mul_f32_e32 v195, 0xbfb8aa3b, v195
	v_add_f32_e32 v4, v162, v4
	v_add_f32_e32 v189, v155, v196
	v_exp_f32_e32 v196, v195
	v_add_f32_e32 v195, v165, v198
	v_mul_f32_e32 v4, 0xbfb8aa3b, v4
	v_mul_f32_e32 v5, 0xbfb8aa3b, v5
	v_mul_f32_e32 v192, 0xbfb8aa3b, v192
	v_add_f32_e32 v3, 1.0, v3
	v_mul_f32_e32 v193, 0xbfb8aa3b, v195
	v_exp_f32_e32 v4, v4
	v_exp_f32_e32 v5, v5
	v_exp_f32_e32 v192, v192
	v_exp_f32_e32 v193, v193
	v_rcp_f32_e32 v198, v3
	v_add_f32_e32 v3, 1.0, v199
	v_rcp_f32_e32 v195, v3
	v_pk_add_f32 v[192:193], v[192:193], 1.0 op_sel_hi:[1,0]
	v_pk_add_f32 v[4:5], v[4:5], 1.0 op_sel_hi:[1,0]
	v_and_b32_e32 v200, 0xffff0000, v239
	v_pk_mul_f32 v[4:5], v[4:5], v[186:187]
	v_pk_mul_f32 v[186:187], v[192:193], v[194:195]
	v_add_f32_e32 v3, v157, v200
	v_pk_mul_f32 v[60:61], v[60:61], v[186:187]
	v_add_f32_e32 v186, v153, v197
	v_mul_f32_e32 v186, 0xbfb8aa3b, v186
	v_exp_f32_e32 v186, v186
	v_mul_f32_e32 v3, 0xbfb8aa3b, v3
	v_exp_f32_e32 v197, v3
	v_mul_f32_e32 v189, 0xbfb8aa3b, v189
	v_add_f32_e32 v3, 1.0, v186
	v_rcp_f32_e32 v199, v3
	s_waitcnt vmcnt(3)
; __device__ __forceinline__ void unpack8(const u32x4 w, float (&v)[8]) { v[0] = bf_lo(w.x); v[1] = bf_hi(w.x); v[2] = bf_lo(w.y); v[3] = bf_hi(w.y); v[4] = bf_lo(w.z); v[5] = bf_hi(w.z); v[6] = bf_lo(w.w); v[7] = bf_hi(w.w); }
;     __device__ __forceinline__ void after(int te, f32x4 (&acc)[2][2][4][2], const Unit& u, int wr, int wc, int fr, int fq) const {
;     ...
;                     for (int m = 0; m < 4; ++m) { const size_t r = (size_t)(row0 + ai * HALF + m * 16); gs[m] = *(const u32x4*)(proj + r * LDP + PGS + c); ga[m] = *(const u32x4*)(proj + r * LDP + PGA + c); }
; #pragma unroll
;                     for (int m = 0; m < 4; ++m) { float vs[8], va[8]; unpack8(gs[m], vs); unpack8(ga[m], va);
; #pragma unroll
;                         for (int e = 0; e < 4; ++e) {
;                             acc[ai][bj][m][0][e] *= (1.f + __expf(-(va[e] + a0[e]))) * __builtin_amdgcn_rcpf(1.f + __expf(-(vs[e] + s0[e])));
;                             acc[ai][bj][m][1][e] *= (1.f + __expf(-(va[4 + e] + a1[e]))) * __builtin_amdgcn_rcpf(1.f + __expf(-(vs[4 + e] + s1[e]))); } }
	v_lshlrev_b32_e32 v3, 16, v146
	v_add_f32_e32 v3, v158, v3
	v_exp_f32_e32 v189, v189
	v_mul_f32_e32 v3, 0xbfb8aa3b, v3
	v_exp_f32_e32 v3, v3
	v_pk_mul_f32 v[58:59], v[58:59], v[4:5]
	v_pk_add_f32 v[4:5], v[196:197], 1.0 op_sel_hi:[1,0]
	v_pk_add_f32 v[186:187], v[188:189], 1.0 op_sel_hi:[1,0]
	v_pk_mul_f32 v[4:5], v[4:5], v[198:199]
	v_pk_mul_f32 v[186:187], v[186:187], v[190:191]
	v_pk_mul_f32 v[56:57], v[56:57], v[4:5]
	v_and_b32_e32 v5, 0xffff0000, v146
	v_lshlrev_b32_e32 v146, 16, v148
	v_add_f32_e32 v3, 1.0, v3
	v_pk_mul_f32 v[54:55], v[54:55], v[186:187]
	v_lshlrev_b32_e32 v186, 16, v147
	v_and_b32_e32 v187, 0xffff0000, v147
	v_and_b32_e32 v147, 0xffff0000, v148
	s_waitcnt vmcnt(2)
	v_lshlrev_b32_e32 v4, 16, v142
	v_and_b32_e32 v148, 0xffff0000, v142
	v_rcp_f32_e32 v142, v3
	v_add_f32_e32 v3, v150, v146
	v_mul_f32_e32 v3, 0xbfb8aa3b, v3
	v_exp_f32_e32 v3, v3
	v_lshlrev_b32_e32 v188, 16, v149
	v_and_b32_e32 v189, 0xffff0000, v149
	v_lshlrev_b32_e32 v149, 16, v143
	v_add_f32_e32 v3, 1.0, v3
	v_rcp_f32_e32 v146, v3
	v_add_f32_e32 v3, v159, v5
	v_mul_f32_e32 v3, 0xbfb8aa3b, v3
	v_exp_f32_e32 v3, v3
	v_and_b32_e32 v190, 0xffff0000, v143
	v_lshlrev_b32_e32 v143, 16, v144
	v_add_f32_e32 v143, v154, v143
	v_mul_f32_e32 v143, 0xbfb8aa3b, v143
	v_add_f32_e32 v3, 1.0, v3
	v_and_b32_e32 v191, 0xffff0000, v144
	v_exp_f32_e32 v144, v143
	v_rcp_f32_e32 v143, v3
	v_add_f32_e32 v3, v151, v147
	v_mul_f32_e32 v3, 0xbfb8aa3b, v3
	v_exp_f32_e32 v3, v3
	v_add_f32_e32 v187, v161, v187
	v_lshlrev_b32_e32 v192, 16, v145
	v_mul_f32_e32 v187, 0xbfb8aa3b, v187
	v_add_f32_e32 v3, 1.0, v3
	v_rcp_f32_e32 v147, v3
	v_add_f32_e32 v3, v160, v186
	v_mul_f32_e32 v3, 0xbfb8aa3b, v3
	v_exp_f32_e32 v3, v3
	v_add_f32_e32 v5, v163, v148
	v_add_f32_e32 v148, v164, v149
	v_add_f32_e32 v149, v156, v192
	v_add_f32_e32 v3, 1.0, v3
	v_rcp_f32_e32 v186, v3
	v_add_f32_e32 v3, v152, v188
	v_mul_f32_e32 v3, 0xbfb8aa3b, v3
	v_exp_f32_e32 v3, v3
	v_exp_f32_e32 v187, v187
	v_mul_f32_e32 v149, 0xbfb8aa3b, v149
	v_add_f32_e32 v4, v162, v4
	v_exp_f32_e32 v188, v149
	v_add_f32_e32 v149, v165, v190
	v_mul_f32_e32 v4, 0xbfb8aa3b, v4
	v_mul_f32_e32 v5, 0xbfb8aa3b, v5
	v_mul_f32_e32 v148, 0xbfb8aa3b, v148
	v_add_f32_e32 v3, 1.0, v3
	v_mul_f32_e32 v149, 0xbfb8aa3b, v149
	v_exp_f32_e32 v4, v4
	v_exp_f32_e32 v5, v5
	v_exp_f32_e32 v148, v148
	v_exp_f32_e32 v149, v149
	v_rcp_f32_e32 v190, v3
	v_add_f32_e32 v3, 1.0, v187
	v_rcp_f32_e32 v187, v3
	v_pk_add_f32 v[148:149], v[148:149], 1.0 op_sel_hi:[1,0]
	v_pk_add_f32 v[4:5], v[4:5], 1.0 op_sel_hi:[1,0]
	v_and_b32_e32 v193, 0xffff0000, v145
	v_pk_mul_f32 v[4:5], v[4:5], v[142:143]
	v_pk_mul_f32 v[142:143], v[148:149], v[186:187]
	v_add_f32_e32 v3, v157, v193
	v_pk_mul_f32 v[52:53], v[52:53], v[142:143]
	v_add_f32_e32 v142, v153, v189
	v_mul_f32_e32 v142, 0xbfb8aa3b, v142
	v_mul_f32_e32 v3, 0xbfb8aa3b, v3
	v_exp_f32_e32 v142, v142
	v_exp_f32_e32 v189, v3
	v_pk_mul_f32 v[50:51], v[50:51], v[4:5]
	v_add_f32_e32 v3, 1.0, v142
	v_pk_add_f32 v[4:5], v[188:189], 1.0 op_sel_hi:[1,0]
	global_load_dwordx4 v[186:189], v[218:219], off offset:256
	v_add_f32_e32 v145, v155, v191
	v_rcp_f32_e32 v191, v3
	s_waitcnt vmcnt(2)
	v_lshlrev_b32_e32 v3, 16, v130
	v_mul_f32_e32 v145, 0xbfb8aa3b, v145
	v_add_f32_e32 v3, v158, v3
	v_exp_f32_e32 v145, v145
	v_mul_f32_e32 v3, 0xbfb8aa3b, v3
	v_exp_f32_e32 v3, v3
	v_pk_mul_f32 v[4:5], v[4:5], v[190:191]
	v_pk_add_f32 v[142:143], v[144:145], 1.0 op_sel_hi:[1,0]
	v_pk_mul_f32 v[48:49], v[48:49], v[4:5]
	v_pk_mul_f32 v[142:143], v[142:143], v[146:147]
	v_and_b32_e32 v5, 0xffff0000, v130
	v_lshlrev_b32_e32 v130, 16, v132
	v_add_f32_e32 v3, 1.0, v3
	v_pk_mul_f32 v[46:47], v[46:47], v[142:143]
	v_lshlrev_b32_e32 v142, 16, v131
	v_and_b32_e32 v143, 0xffff0000, v131
	v_and_b32_e32 v131, 0xffff0000, v132
	s_waitcnt vmcnt(1)
	v_lshlrev_b32_e32 v4, 16, v126
	v_and_b32_e32 v132, 0xffff0000, v126
	v_rcp_f32_e32 v126, v3
	v_add_f32_e32 v3, v150, v130
	v_mul_f32_e32 v3, 0xbfb8aa3b, v3
	v_exp_f32_e32 v3, v3
	global_load_dwordx4 v[190:193], v[216:217], off offset:256
	v_lshlrev_b32_e32 v144, 16, v133
	v_and_b32_e32 v145, 0xffff0000, v133
	v_add_f32_e32 v3, 1.0, v3
	v_rcp_f32_e32 v130, v3
	v_add_f32_e32 v3, v159, v5
	v_mul_f32_e32 v3, 0xbfb8aa3b, v3
	v_exp_f32_e32 v3, v3
	v_lshlrev_b32_e32 v133, 16, v127
	v_and_b32_e32 v146, 0xffff0000, v127
	v_lshlrev_b32_e32 v127, 16, v128
	v_add_f32_e32 v127, v154, v127
	v_mul_f32_e32 v127, 0xbfb8aa3b, v127
	v_add_f32_e32 v3, 1.0, v3
	v_and_b32_e32 v147, 0xffff0000, v128
	v_exp_f32_e32 v128, v127
	v_rcp_f32_e32 v127, v3
	v_add_f32_e32 v3, v151, v131
	v_mul_f32_e32 v3, 0xbfb8aa3b, v3
	v_exp_f32_e32 v3, v3
	v_add_f32_e32 v143, v161, v143
	v_lshlrev_b32_e32 v148, 16, v129
	v_mul_f32_e32 v143, 0xbfb8aa3b, v143
	v_add_f32_e32 v3, 1.0, v3
	v_rcp_f32_e32 v131, v3
	v_add_f32_e32 v3, v160, v142
	v_mul_f32_e32 v3, 0xbfb8aa3b, v3
	v_exp_f32_e32 v3, v3
	v_add_f32_e32 v5, v163, v132
	v_add_f32_e32 v132, v164, v133
	v_add_f32_e32 v133, v156, v148
	v_add_f32_e32 v3, 1.0, v3
	v_rcp_f32_e32 v142, v3
	v_add_f32_e32 v3, v152, v144
	v_mul_f32_e32 v3, 0xbfb8aa3b, v3
	v_exp_f32_e32 v3, v3
	v_exp_f32_e32 v143, v143
	v_mul_f32_e32 v133, 0xbfb8aa3b, v133
	v_add_f32_e32 v4, v162, v4
	v_exp_f32_e32 v144, v133
	v_add_f32_e32 v133, v165, v146
	v_mul_f32_e32 v4, 0xbfb8aa3b, v4
	v_mul_f32_e32 v5, 0xbfb8aa3b, v5
	v_mul_f32_e32 v132, 0xbfb8aa3b, v132
	v_add_f32_e32 v3, 1.0, v3
	v_mul_f32_e32 v133, 0xbfb8aa3b, v133
	v_exp_f32_e32 v4, v4
	v_exp_f32_e32 v5, v5
	v_exp_f32_e32 v132, v132
	v_exp_f32_e32 v133, v133
	v_rcp_f32_e32 v146, v3
	v_add_f32_e32 v3, 1.0, v143
	v_rcp_f32_e32 v143, v3
	v_pk_add_f32 v[132:133], v[132:133], 1.0 op_sel_hi:[1,0]
	v_pk_add_f32 v[4:5], v[4:5], 1.0 op_sel_hi:[1,0]
	v_and_b32_e32 v149, 0xffff0000, v129
	v_pk_mul_f32 v[4:5], v[4:5], v[126:127]
	v_pk_mul_f32 v[126:127], v[132:133], v[142:143]
	v_add_f32_e32 v129, v155, v147
	v_pk_mul_f32 v[44:45], v[44:45], v[126:127]
	v_add_f32_e32 v126, v153, v145
	v_mul_f32_e32 v126, 0xbfb8aa3b, v126
	v_exp_f32_e32 v126, v126
	v_mul_f32_e32 v129, 0xbfb8aa3b, v129
	v_add_f32_e32 v3, v157, v149
	v_exp_f32_e32 v129, v129
	v_mul_f32_e32 v3, 0xbfb8aa3b, v3
	v_exp_f32_e32 v145, v3
	v_add_f32_e32 v3, 1.0, v126
	v_rcp_f32_e32 v147, v3
	v_pk_add_f32 v[126:127], v[128:129], 1.0 op_sel_hi:[1,0]
	v_pk_mul_f32 v[42:43], v[42:43], v[4:5]
	v_pk_add_f32 v[4:5], v[144:145], 1.0 op_sel_hi:[1,0]
	v_pk_mul_f32 v[126:127], v[126:127], v[130:131]
	v_pk_mul_f32 v[4:5], v[4:5], v[146:147]
	v_pk_mul_f32 v[38:39], v[38:39], v[126:127]
	global_load_dwordx4 v[194:197], v[204:205], off offset:256
	global_load_dwordx4 v[198:201], v[206:207], off offset:256
	global_load_dwordx4 v[146:149], v[208:209], off offset:256
	global_load_dwordx4 v[142:145], v[210:211], off offset:256
	global_load_dwordx4 v[130:133], v[212:213], off offset:256
	global_load_dwordx4 v[126:129], v[214:215], off offset:256
	s_waitcnt vmcnt(7)
; __device__ __forceinline__ void unpack8(const u32x4 w, float (&v)[8]) { v[0] = bf_lo(w.x); v[1] = bf_hi(w.x); v[2] = bf_lo(w.y); v[3] = bf_hi(w.y); v[4] = bf_lo(w.z); v[5] = bf_hi(w.z); v[6] = bf_lo(w.w); v[7] = bf_hi(w.w); }
;     __device__ __forceinline__ void after(int te, f32x4 (&acc)[2][2][4][2], const Unit& u, int wr, int wc, int fr, int fq) const {
;     ...
;                     for (int m = 0; m < 4; ++m) { float vs[8], va[8]; unpack8(gs[m], vs); unpack8(ga[m], va);
; #pragma unroll
;                         for (int e = 0; e < 4; ++e) {
;                             acc[ai][bj][m][0][e] *= (1.f + __expf(-(va[e] + a0[e]))) * __builtin_amdgcn_rcpf(1.f + __expf(-(vs[e] + s0[e])));
;                             acc[ai][bj][m][1][e] *= (1.f + __expf(-(va[4 + e] + a1[e]))) * __builtin_amdgcn_rcpf(1.f + __expf(-(vs[4 + e] + s1[e]))); } }
	v_lshlrev_b32_e32 v3, 16, v186
	v_add_f32_e32 v3, v158, v3
	v_mul_f32_e32 v3, 0xbfb8aa3b, v3
	v_exp_f32_e32 v3, v3
	v_lshlrev_b32_e32 v202, 16, v187
	v_and_b32_e32 v203, 0xffff0000, v187
	v_lshlrev_b32_e32 v187, 16, v188
	v_add_f32_e32 v3, 1.0, v3
	v_pk_mul_f32 v[40:41], v[40:41], v[4:5]
	v_and_b32_e32 v5, 0xffff0000, v186
	v_rcp_f32_e32 v186, v3
	v_add_f32_e32 v3, v150, v187
	v_mul_f32_e32 v3, 0xbfb8aa3b, v3
	v_exp_f32_e32 v3, v3
	v_lshlrev_b32_e32 v205, 16, v189
	v_and_b32_e32 v207, 0xffff0000, v189
	s_waitcnt vmcnt(6)
	v_lshlrev_b32_e32 v4, 16, v190
	v_add_f32_e32 v3, 1.0, v3
	v_and_b32_e32 v189, 0xffff0000, v190
	v_rcp_f32_e32 v190, v3
	v_add_f32_e32 v3, v159, v5
	v_mul_f32_e32 v3, 0xbfb8aa3b, v3
	v_exp_f32_e32 v3, v3
	v_and_b32_e32 v204, 0xffff0000, v188
	v_lshlrev_b32_e32 v188, 16, v192
	v_add_f32_e32 v187, v154, v188
	v_mul_f32_e32 v187, 0xbfb8aa3b, v187
	v_add_f32_e32 v3, 1.0, v3
	v_exp_f32_e32 v188, v187
	v_rcp_f32_e32 v187, v3
	v_add_f32_e32 v3, v151, v204
	v_mul_f32_e32 v3, 0xbfb8aa3b, v3
	v_exp_f32_e32 v3, v3
	v_lshlrev_b32_e32 v206, 16, v191
	v_and_b32_e32 v208, 0xffff0000, v191
	v_and_b32_e32 v191, 0xffff0000, v192
	v_add_f32_e32 v3, 1.0, v3
	v_add_f32_e32 v5, v163, v189
	v_add_f32_e32 v189, v155, v191
	v_rcp_f32_e32 v191, v3
	v_add_f32_e32 v3, v160, v202
	v_mul_f32_e32 v3, 0xbfb8aa3b, v3
	v_exp_f32_e32 v3, v3
	v_add_f32_e32 v203, v161, v203
	v_lshlrev_b32_e32 v209, 16, v193
	v_mul_f32_e32 v203, 0xbfb8aa3b, v203
	v_add_f32_e32 v3, 1.0, v3
	v_rcp_f32_e32 v202, v3
	v_add_f32_e32 v3, v152, v205
	v_mul_f32_e32 v3, 0xbfb8aa3b, v3
	v_exp_f32_e32 v3, v3
	v_and_b32_e32 v210, 0xffff0000, v193
	v_add_f32_e32 v193, v156, v209
	v_exp_f32_e32 v203, v203
	v_mul_f32_e32 v193, 0xbfb8aa3b, v193
	v_add_f32_e32 v4, v162, v4
	v_add_f32_e32 v192, v164, v206
	v_exp_f32_e32 v204, v193
	v_add_f32_e32 v193, v165, v208
	v_mul_f32_e32 v4, 0xbfb8aa3b, v4
	v_mul_f32_e32 v5, 0xbfb8aa3b, v5
	v_mul_f32_e32 v192, 0xbfb8aa3b, v192
	v_add_f32_e32 v3, 1.0, v3
	v_mul_f32_e32 v193, 0xbfb8aa3b, v193
	v_exp_f32_e32 v4, v4
	v_exp_f32_e32 v5, v5
	v_exp_f32_e32 v192, v192
	v_exp_f32_e32 v193, v193
	v_rcp_f32_e32 v206, v3
	v_add_f32_e32 v3, 1.0, v203
	v_rcp_f32_e32 v203, v3
	v_pk_add_f32 v[192:193], v[192:193], 1.0 op_sel_hi:[1,0]
	v_pk_add_f32 v[4:5], v[4:5], 1.0 op_sel_hi:[1,0]
	v_add_f32_e32 v3, v157, v210
	v_pk_mul_f32 v[4:5], v[4:5], v[186:187]
	v_pk_mul_f32 v[186:187], v[192:193], v[202:203]
	v_mul_f32_e32 v3, 0xbfb8aa3b, v3
	v_pk_mul_f32 v[36:37], v[36:37], v[186:187]
	v_add_f32_e32 v186, v153, v207
	v_mul_f32_e32 v186, 0xbfb8aa3b, v186
	v_exp_f32_e32 v186, v186
	v_exp_f32_e32 v205, v3
	v_mul_f32_e32 v189, 0xbfb8aa3b, v189
	v_exp_f32_e32 v189, v189
	v_add_f32_e32 v3, 1.0, v186
	v_rcp_f32_e32 v207, v3
	s_waitcnt vmcnt(5)
	v_lshlrev_b32_e32 v3, 16, v194
	v_add_f32_e32 v3, v158, v3
	v_mul_f32_e32 v3, 0xbfb8aa3b, v3
	v_exp_f32_e32 v3, v3
	v_pk_add_f32 v[186:187], v[188:189], 1.0 op_sel_hi:[1,0]
	v_pk_mul_f32 v[34:35], v[34:35], v[4:5]
	v_pk_mul_f32 v[186:187], v[186:187], v[190:191]
	v_add_f32_e32 v3, 1.0, v3
	v_pk_mul_f32 v[30:31], v[30:31], v[186:187]
	v_lshlrev_b32_e32 v187, 16, v196
	v_rcp_f32_e32 v186, v3
	v_add_f32_e32 v3, v150, v187
	v_mul_f32_e32 v3, 0xbfb8aa3b, v3
	v_exp_f32_e32 v3, v3
	v_pk_add_f32 v[4:5], v[204:205], 1.0 op_sel_hi:[1,0]
	s_waitcnt vmcnt(4)
	v_lshlrev_b32_e32 v188, 16, v200
	v_pk_mul_f32 v[4:5], v[4:5], v[206:207]
	v_add_f32_e32 v3, 1.0, v3
	v_pk_mul_f32 v[32:33], v[32:33], v[4:5]
	v_and_b32_e32 v5, 0xffff0000, v194
	v_rcp_f32_e32 v190, v3
	v_add_f32_e32 v3, v159, v5
	v_mul_f32_e32 v3, 0xbfb8aa3b, v3
	v_exp_f32_e32 v3, v3
	v_add_f32_e32 v187, v154, v188
	v_and_b32_e32 v189, 0xffff0000, v196
	v_mul_f32_e32 v187, 0xbfb8aa3b, v187
	v_add_f32_e32 v3, 1.0, v3
	v_exp_f32_e32 v188, v187
	v_rcp_f32_e32 v187, v3
	v_add_f32_e32 v3, v151, v189
	v_mul_f32_e32 v3, 0xbfb8aa3b, v3
	v_exp_f32_e32 v3, v3
	v_lshlrev_b32_e32 v192, 16, v195
	v_and_b32_e32 v191, 0xffff0000, v198
	v_add_f32_e32 v5, v163, v191
	v_add_f32_e32 v3, 1.0, v3
	v_rcp_f32_e32 v191, v3
	v_add_f32_e32 v3, v160, v192
	v_mul_f32_e32 v3, 0xbfb8aa3b, v3
	v_exp_f32_e32 v3, v3
	v_and_b32_e32 v193, 0xffff0000, v195
	v_lshlrev_b32_e32 v195, 16, v197
	v_lshlrev_b32_e32 v194, 16, v199
	v_add_f32_e32 v3, 1.0, v3
	v_add_f32_e32 v192, v164, v194
	v_rcp_f32_e32 v194, v3
	v_add_f32_e32 v3, v152, v195
	v_mul_f32_e32 v3, 0xbfb8aa3b, v3
	v_add_f32_e32 v193, v161, v193
	v_lshlrev_b32_e32 v4, 16, v198
	v_and_b32_e32 v198, 0xffff0000, v199
	v_lshlrev_b32_e32 v199, 16, v201
	v_exp_f32_e32 v3, v3
	v_mul_f32_e32 v193, 0xbfb8aa3b, v193
	v_add_f32_e32 v195, v156, v199
	v_exp_f32_e32 v199, v193
	v_and_b32_e32 v196, 0xffff0000, v200
	v_mul_f32_e32 v195, 0xbfb8aa3b, v195
	v_add_f32_e32 v4, v162, v4
	v_add_f32_e32 v189, v155, v196
	v_exp_f32_e32 v196, v195
	v_add_f32_e32 v195, v165, v198
	v_mul_f32_e32 v4, 0xbfb8aa3b, v4
	v_mul_f32_e32 v5, 0xbfb8aa3b, v5
	v_mul_f32_e32 v192, 0xbfb8aa3b, v192
	v_add_f32_e32 v3, 1.0, v3
	v_mul_f32_e32 v193, 0xbfb8aa3b, v195
	v_exp_f32_e32 v4, v4
	v_exp_f32_e32 v5, v5
	v_exp_f32_e32 v192, v192
	v_exp_f32_e32 v193, v193
	v_rcp_f32_e32 v198, v3
	v_add_f32_e32 v3, 1.0, v199
	v_rcp_f32_e32 v195, v3
	v_pk_add_f32 v[192:193], v[192:193], 1.0 op_sel_hi:[1,0]
	v_pk_add_f32 v[4:5], v[4:5], 1.0 op_sel_hi:[1,0]
	v_and_b32_e32 v197, 0xffff0000, v197
	v_pk_mul_f32 v[4:5], v[4:5], v[186:187]
	v_pk_mul_f32 v[186:187], v[192:193], v[194:195]
	v_and_b32_e32 v200, 0xffff0000, v201
	v_pk_mul_f32 v[28:29], v[28:29], v[186:187]
	v_add_f32_e32 v186, v153, v197
	v_mul_f32_e32 v186, 0xbfb8aa3b, v186
	v_exp_f32_e32 v186, v186
	v_add_f32_e32 v3, v157, v200
	v_mul_f32_e32 v3, 0xbfb8aa3b, v3
	v_exp_f32_e32 v197, v3
	v_add_f32_e32 v3, 1.0, v186
	v_rcp_f32_e32 v199, v3
	s_waitcnt vmcnt(3)
; __device__ __forceinline__ void unpack8(const u32x4 w, float (&v)[8]) { v[0] = bf_lo(w.x); v[1] = bf_hi(w.x); v[2] = bf_lo(w.y); v[3] = bf_hi(w.y); v[4] = bf_lo(w.z); v[5] = bf_hi(w.z); v[6] = bf_lo(w.w); v[7] = bf_hi(w.w); }
;     __device__ __forceinline__ void after(int te, f32x4 (&acc)[2][2][4][2], const Unit& u, int wr, int wc, int fr, int fq) const {
;     ...
;                     for (int m = 0; m < 4; ++m) { float vs[8], va[8]; unpack8(gs[m], vs); unpack8(ga[m], va);
; #pragma unroll
;                         for (int e = 0; e < 4; ++e) {
;                             acc[ai][bj][m][0][e] *= (1.f + __expf(-(va[e] + a0[e]))) * __builtin_amdgcn_rcpf(1.f + __expf(-(vs[e] + s0[e])));
;                             acc[ai][bj][m][1][e] *= (1.f + __expf(-(va[4 + e] + a1[e]))) * __builtin_amdgcn_rcpf(1.f + __expf(-(vs[4 + e] + s1[e]))); } }
;                     asm volatile("" ::: "memory");
;                 } }
	v_lshlrev_b32_e32 v3, 16, v146
	v_mul_f32_e32 v189, 0xbfb8aa3b, v189
	v_add_f32_e32 v3, v158, v3
	v_exp_f32_e32 v189, v189
	v_mul_f32_e32 v3, 0xbfb8aa3b, v3
	v_exp_f32_e32 v3, v3
	v_pk_mul_f32 v[26:27], v[26:27], v[4:5]
	v_pk_add_f32 v[4:5], v[196:197], 1.0 op_sel_hi:[1,0]
	v_pk_add_f32 v[186:187], v[188:189], 1.0 op_sel_hi:[1,0]
	v_pk_mul_f32 v[4:5], v[4:5], v[198:199]
	v_pk_mul_f32 v[186:187], v[186:187], v[190:191]
	v_pk_mul_f32 v[24:25], v[24:25], v[4:5]
	v_and_b32_e32 v5, 0xffff0000, v146
	v_lshlrev_b32_e32 v146, 16, v148
	v_add_f32_e32 v3, 1.0, v3
	v_pk_mul_f32 v[22:23], v[22:23], v[186:187]
	v_lshlrev_b32_e32 v186, 16, v147
	v_and_b32_e32 v187, 0xffff0000, v147
	v_and_b32_e32 v147, 0xffff0000, v148
	s_waitcnt vmcnt(2)
	v_lshlrev_b32_e32 v4, 16, v142
	v_and_b32_e32 v148, 0xffff0000, v142
	v_rcp_f32_e32 v142, v3
	v_add_f32_e32 v3, v150, v146
	v_mul_f32_e32 v3, 0xbfb8aa3b, v3
	v_exp_f32_e32 v3, v3
	v_lshlrev_b32_e32 v188, 16, v149
	v_and_b32_e32 v189, 0xffff0000, v149
	v_lshlrev_b32_e32 v149, 16, v143
	v_add_f32_e32 v3, 1.0, v3
	v_rcp_f32_e32 v146, v3
	v_add_f32_e32 v3, v159, v5
	v_mul_f32_e32 v3, 0xbfb8aa3b, v3
	v_exp_f32_e32 v3, v3
	v_and_b32_e32 v190, 0xffff0000, v143
	v_lshlrev_b32_e32 v143, 16, v144
	v_add_f32_e32 v143, v154, v143
	v_mul_f32_e32 v143, 0xbfb8aa3b, v143
	v_add_f32_e32 v3, 1.0, v3
	v_and_b32_e32 v191, 0xffff0000, v144
	v_exp_f32_e32 v144, v143
	v_rcp_f32_e32 v143, v3
	v_add_f32_e32 v3, v151, v147
	v_mul_f32_e32 v3, 0xbfb8aa3b, v3
	v_exp_f32_e32 v3, v3
	v_add_f32_e32 v187, v161, v187
	v_lshlrev_b32_e32 v192, 16, v145
	v_mul_f32_e32 v187, 0xbfb8aa3b, v187
	v_add_f32_e32 v3, 1.0, v3
	v_rcp_f32_e32 v147, v3
	v_add_f32_e32 v3, v160, v186
	v_mul_f32_e32 v3, 0xbfb8aa3b, v3
	v_exp_f32_e32 v3, v3
	v_add_f32_e32 v5, v163, v148
	v_add_f32_e32 v148, v164, v149
	v_add_f32_e32 v149, v156, v192
	v_add_f32_e32 v3, 1.0, v3
	v_rcp_f32_e32 v186, v3
	v_add_f32_e32 v3, v152, v188
	v_mul_f32_e32 v3, 0xbfb8aa3b, v3
	v_exp_f32_e32 v3, v3
	v_exp_f32_e32 v187, v187
	v_mul_f32_e32 v149, 0xbfb8aa3b, v149
	v_add_f32_e32 v4, v162, v4
	v_exp_f32_e32 v188, v149
	v_add_f32_e32 v149, v165, v190
	v_mul_f32_e32 v4, 0xbfb8aa3b, v4
	v_mul_f32_e32 v5, 0xbfb8aa3b, v5
	v_mul_f32_e32 v148, 0xbfb8aa3b, v148
	v_add_f32_e32 v3, 1.0, v3
	v_mul_f32_e32 v149, 0xbfb8aa3b, v149
	v_exp_f32_e32 v4, v4
	v_exp_f32_e32 v5, v5
	v_exp_f32_e32 v148, v148
	v_exp_f32_e32 v149, v149
	v_rcp_f32_e32 v190, v3
	v_add_f32_e32 v3, 1.0, v187
	v_rcp_f32_e32 v187, v3
	v_pk_add_f32 v[148:149], v[148:149], 1.0 op_sel_hi:[1,0]
	v_pk_add_f32 v[4:5], v[4:5], 1.0 op_sel_hi:[1,0]
	v_and_b32_e32 v193, 0xffff0000, v145
	v_pk_mul_f32 v[4:5], v[4:5], v[142:143]
	v_pk_mul_f32 v[142:143], v[148:149], v[186:187]
	v_add_f32_e32 v3, v157, v193
	v_pk_mul_f32 v[20:21], v[20:21], v[142:143]
	v_add_f32_e32 v142, v153, v189
	v_mul_f32_e32 v142, 0xbfb8aa3b, v142
	v_exp_f32_e32 v142, v142
	v_mul_f32_e32 v3, 0xbfb8aa3b, v3
	v_exp_f32_e32 v189, v3
	v_add_f32_e32 v145, v155, v191
	v_add_f32_e32 v3, 1.0, v142
	v_rcp_f32_e32 v191, v3
	s_waitcnt vmcnt(1)
	v_lshlrev_b32_e32 v3, 16, v130
	v_mul_f32_e32 v145, 0xbfb8aa3b, v145
	v_add_f32_e32 v3, v158, v3
	v_exp_f32_e32 v145, v145
	v_mul_f32_e32 v3, 0xbfb8aa3b, v3
	v_exp_f32_e32 v3, v3
	v_pk_mul_f32 v[18:19], v[18:19], v[4:5]
	v_pk_add_f32 v[4:5], v[188:189], 1.0 op_sel_hi:[1,0]
	v_pk_add_f32 v[142:143], v[144:145], 1.0 op_sel_hi:[1,0]
	v_pk_mul_f32 v[4:5], v[4:5], v[190:191]
	v_pk_mul_f32 v[142:143], v[142:143], v[146:147]
	v_pk_mul_f32 v[16:17], v[16:17], v[4:5]
	v_and_b32_e32 v5, 0xffff0000, v130
	v_lshlrev_b32_e32 v130, 16, v132
	v_add_f32_e32 v3, 1.0, v3
	v_pk_mul_f32 v[14:15], v[14:15], v[142:143]
	v_lshlrev_b32_e32 v142, 16, v131
	v_and_b32_e32 v143, 0xffff0000, v131
	v_and_b32_e32 v131, 0xffff0000, v132
	s_waitcnt vmcnt(0)
	v_lshlrev_b32_e32 v4, 16, v126
	v_and_b32_e32 v132, 0xffff0000, v126
	v_rcp_f32_e32 v126, v3
	v_add_f32_e32 v3, v150, v130
	v_mul_f32_e32 v3, 0xbfb8aa3b, v3
	v_exp_f32_e32 v3, v3
	v_lshlrev_b32_e32 v144, 16, v133
	v_and_b32_e32 v145, 0xffff0000, v133
	v_lshlrev_b32_e32 v133, 16, v127
	v_add_f32_e32 v3, 1.0, v3
	v_rcp_f32_e32 v130, v3
	v_add_f32_e32 v3, v159, v5
	v_mul_f32_e32 v3, 0xbfb8aa3b, v3
	v_exp_f32_e32 v3, v3
	v_and_b32_e32 v146, 0xffff0000, v127
	v_lshlrev_b32_e32 v127, 16, v128
	v_add_f32_e32 v127, v154, v127
	v_mul_f32_e32 v127, 0xbfb8aa3b, v127
	v_add_f32_e32 v3, 1.0, v3
	v_and_b32_e32 v147, 0xffff0000, v128
	v_exp_f32_e32 v128, v127
	v_rcp_f32_e32 v127, v3
	v_add_f32_e32 v3, v151, v131
	v_mul_f32_e32 v3, 0xbfb8aa3b, v3
	v_exp_f32_e32 v3, v3
	v_add_f32_e32 v143, v161, v143
	v_lshlrev_b32_e32 v148, 16, v129
	v_mul_f32_e32 v143, 0xbfb8aa3b, v143
	v_add_f32_e32 v3, 1.0, v3
	v_rcp_f32_e32 v131, v3
	v_add_f32_e32 v3, v160, v142
	v_mul_f32_e32 v3, 0xbfb8aa3b, v3
	v_exp_f32_e32 v3, v3
	v_add_f32_e32 v5, v163, v132
	v_add_f32_e32 v132, v164, v133
	v_add_f32_e32 v133, v156, v148
	v_add_f32_e32 v3, 1.0, v3
	v_rcp_f32_e32 v142, v3
	v_add_f32_e32 v3, v152, v144
	v_mul_f32_e32 v3, 0xbfb8aa3b, v3
	v_exp_f32_e32 v3, v3
	v_exp_f32_e32 v143, v143
	v_mul_f32_e32 v133, 0xbfb8aa3b, v133
	v_add_f32_e32 v4, v162, v4
	v_exp_f32_e32 v144, v133
	v_add_f32_e32 v133, v165, v146
	v_mul_f32_e32 v4, 0xbfb8aa3b, v4
	v_mul_f32_e32 v5, 0xbfb8aa3b, v5
	v_mul_f32_e32 v132, 0xbfb8aa3b, v132
	v_add_f32_e32 v3, 1.0, v3
	v_mul_f32_e32 v133, 0xbfb8aa3b, v133
	v_exp_f32_e32 v4, v4
	v_exp_f32_e32 v5, v5
	v_exp_f32_e32 v132, v132
	v_exp_f32_e32 v133, v133
	v_rcp_f32_e32 v146, v3
	v_add_f32_e32 v3, 1.0, v143
	v_rcp_f32_e32 v143, v3
	v_pk_add_f32 v[132:133], v[132:133], 1.0 op_sel_hi:[1,0]
	v_pk_add_f32 v[4:5], v[4:5], 1.0 op_sel_hi:[1,0]
	v_and_b32_e32 v149, 0xffff0000, v129
	v_pk_mul_f32 v[4:5], v[4:5], v[126:127]
	v_pk_mul_f32 v[126:127], v[132:133], v[142:143]
	v_add_f32_e32 v129, v155, v147
	v_pk_mul_f32 v[12:13], v[12:13], v[126:127]
	v_add_f32_e32 v126, v153, v145
	v_mul_f32_e32 v126, 0xbfb8aa3b, v126
	v_exp_f32_e32 v126, v126
	v_add_f32_e32 v3, v157, v149
	v_mul_f32_e32 v129, 0xbfb8aa3b, v129
	v_mul_f32_e32 v3, 0xbfb8aa3b, v3
	v_exp_f32_e32 v129, v129
	v_exp_f32_e32 v145, v3
	v_add_f32_e32 v3, 1.0, v126
	v_rcp_f32_e32 v147, v3
	v_pk_mul_f32 v[10:11], v[10:11], v[4:5]
	v_pk_add_f32 v[4:5], v[144:145], 1.0 op_sel_hi:[1,0]
	v_pk_add_f32 v[126:127], v[128:129], 1.0 op_sel_hi:[1,0]
	v_pk_mul_f32 v[4:5], v[4:5], v[146:147]
	v_pk_mul_f32 v[126:127], v[126:127], v[130:131]
	v_pk_mul_f32 v[8:9], v[8:9], v[4:5]
	v_pk_mul_f32 v[6:7], v[6:7], v[126:127]

; #define PG8_STAGE(bufoff, gbase, voff) do { _Pragma("unroll") for (int _i = 0; _i < 2; ++_i) \
;         __builtin_amdgcn_global_load_lds((const unsigned*)((const char*)(gbase) + (voff)[_i]), (LAS unsigned*)(lds + (bufoff) + ldsw + _i * 8192), 16, 0, 0); } while (0)
; #define PG8_LDA(dst, b, h) do { _Pragma("unroll") for (int m = 0; m < 4; ++m) _Pragma("unroll") for (int k = 0; k < 2; ++k) dst[m][k] = *(const LAS bf16x8*)(lds + PG8_SA(b, h) + aoff + m * 2048 + k * 1024); } while (0)
; #define PG8_LDB(dst, b, h) do { _Pragma("unroll") for (int n = 0; n < 2; ++n) _Pragma("unroll") for (int k = 0; k < 2; ++k) dst[n][k] = *(const LAS bf16x8*)(lds + PG8_SB(b, h) + boff + n * 2048 + k * 1024); } while (0)
; #define PG8_MMA(ai, bj, At, Bt) do { __builtin_amdgcn_s_setprio(1); _Pragma("unroll") for (int m = 0; m < 4; ++m) _Pragma("unroll") for (int n = 0; n < 2; ++n) _Pragma("unroll") for (int k = 0; k < 2; ++k) \
;         acc[ai][bj][m][n] = __builtin_amdgcn_mfma_f32_16x16x32_bf16(Bt[n][k], At[m][k], acc[ai][bj][m][n], 0, 0, 0); __builtin_amdgcn_s_setprio(0); } while (0)
; #define PG8_WAIT_V(n) asm volatile("s_waitcnt vmcnt(" #n ")" ::: "memory")
; #define PG8_WAIT_L(n) asm volatile("s_waitcnt lgkmcnt(" #n ")" ::: "memory")
; #define PG8_BAR __builtin_amdgcn_s_barrier()
; template <class Epi, class Sched, bool ALIGN_EPI, class Hook = NoHook>
; __device__ __forceinline__ void gemm_phase(LAS unsigned char* lds, const Gemm g, const Sched& S, const Epi& E, const Hook& H = Hook()) {
;     ...
;             const bool last = (t == nt - 2);
;             const char* a1 = cA + (size_t)(t + 1) * kstep;
;             const char* a2 = last ? nA : cA + (size_t)(t + 2) * kstep; const char* b2 = last ? nB : cB + (size_t)(t + 2) * kstep;
;             const char* a3 = a2 + kstep; const char* b3 = b2 + kstep;
;             if (last && has_next) S.a_ready(nxt);
;             PG8_LDB(B0, 0, 0); PG8_LDB(B1, 0, 1); PG8_SCHED; PG8_LDA(At, 0, 0); PG8_STAGE(PG8_SA(1, 1), a1 + hA, voffA);
;             PG8_WAIT_V(8); PG8_WAIT_L(0); PG8_BAR; PG8_MMA(0, 0, At, B0); PG8_MMA(0, 1, At, B1); PG8_BAR; PG8_SCHED;
;             PG8_LDA(At, 0, 1); PG8_STAGE(PG8_SB(0, 0), b2, voffB); PG8_STAGE(PG8_SB(0, 1), b2 + hB, voffB); PG8_STAGE(PG8_SA(0, 0), a2, voffA);
;             PG8_WAIT_V(8); PG8_WAIT_L(0); PG8_BAR; PG8_MMA(1, 0, At, B0); PG8_MMA(1, 1, At, B1); PG8_BAR; PG8_SCHED;
.LBB0_850:
	ds_read_b128 v[146:149], v1
	ds_read_b128 v[150:153], v1 offset:1024
	s_add_u32 s20, s6, 0x87c00080
	s_addc_u32 s21, s7, -1
	s_cmp_lg_u32 s42, 60
	s_cselect_b32 s20, s20, 0
	s_cselect_b32 s21, s21, 0
	s_add_u32 s22, s2, s20
	s_addc_u32 s23, s3, s21
	s_add_u32 s20, s14, s20
	s_addc_u32 s21, s15, s21
	s_mov_b32 m0, s43
	ds_read_b128 v[154:157], v1 offset:2048
	ds_read_b128 v[158:161], v1 offset:3072
	ds_read_b128 v[162:165], v142
	ds_read_b128 v[166:169], v142 offset:1024
	ds_read_b128 v[170:173], v142 offset:2048
	ds_read_b128 v[174:177], v142 offset:3072
	v_lshl_add_u64 v[178:179], v[138:139], 0, s[6:7]
	global_load_lds_dwordx4 v[178:179], off
	ds_read_b128 v[186:189], v143
	ds_read_b128 v[190:193], v143 offset:1024
	ds_read_b128 v[194:197], v143 offset:2048
	ds_read_b128 v[198:201], v143 offset:3072
	ds_read_b128 v[202:205], v143 offset:4096
	ds_read_b128 v[206:209], v143 offset:5120
	ds_read_b128 v[210:213], v143 offset:6144
	ds_read_b128 v[214:217], v143 offset:7168
	v_lshl_add_u64 v[178:179], v[140:141], 0, s[6:7]
	s_mov_b32 m0, s44
	s_nop 0
	global_load_lds_dwordx4 v[178:179], off
	s_waitcnt vmcnt(8)
	s_waitcnt lgkmcnt(0)
	s_barrier
	s_setprio 1
	s_waitcnt lgkmcnt(0)
	v_mfma_f32_16x16x32_bf16 v[54:57], v[146:149], v[186:189], v[54:57]
	v_mfma_f32_16x16x32_bf16 v[34:37], v[154:157], v[186:189], v[34:37]
	v_mfma_f32_16x16x32_bf16 v[42:45], v[146:149], v[194:197], v[42:45]
	v_mfma_f32_16x16x32_bf16 v[30:33], v[154:157], v[194:197], v[30:33]
	v_mfma_f32_16x16x32_bf16 v[62:65], v[146:149], v[202:205], v[62:65]
	v_mfma_f32_16x16x32_bf16 v[50:53], v[154:157], v[202:205], v[50:53]
	v_mfma_f32_16x16x32_bf16 v[78:81], v[146:149], v[210:213], v[78:81]
	v_mfma_f32_16x16x32_bf16 v[70:73], v[154:157], v[210:213], v[70:73]
	v_mfma_f32_16x16x32_bf16 v[54:57], v[150:153], v[190:193], v[54:57]
	v_mfma_f32_16x16x32_bf16 v[34:37], v[158:161], v[190:193], v[34:37]
	v_mfma_f32_16x16x32_bf16 v[42:45], v[150:153], v[198:201], v[42:45]
	v_mfma_f32_16x16x32_bf16 v[30:33], v[158:161], v[198:201], v[30:33]
	v_mfma_f32_16x16x32_bf16 v[62:65], v[150:153], v[206:209], v[62:65]
	v_mfma_f32_16x16x32_bf16 v[50:53], v[158:161], v[206:209], v[50:53]
	v_mfma_f32_16x16x32_bf16 v[78:81], v[150:153], v[214:217], v[78:81]
	v_mfma_f32_16x16x32_bf16 v[70:73], v[158:161], v[214:217], v[70:73]
	s_setprio 0
	s_setprio 1
	v_mfma_f32_16x16x32_bf16 v[10:13], v[162:165], v[186:189], v[10:13]
	v_mfma_f32_16x16x32_bf16 v[2:5], v[170:173], v[186:189], v[2:5]
	v_mfma_f32_16x16x32_bf16 v[14:17], v[162:165], v[194:197], v[14:17]
	v_mfma_f32_16x16x32_bf16 v[6:9], v[170:173], v[194:197], v[6:9]
	v_mfma_f32_16x16x32_bf16 v[22:25], v[162:165], v[202:205], v[22:25]
	v_mfma_f32_16x16x32_bf16 v[18:21], v[170:173], v[202:205], v[18:21]
	v_mfma_f32_16x16x32_bf16 v[38:41], v[162:165], v[210:213], v[38:41]
	v_mfma_f32_16x16x32_bf16 v[26:29], v[170:173], v[210:213], v[26:29]
	v_mfma_f32_16x16x32_bf16 v[10:13], v[166:169], v[190:193], v[10:13]
	v_mfma_f32_16x16x32_bf16 v[2:5], v[174:177], v[190:193], v[2:5]
	v_mfma_f32_16x16x32_bf16 v[14:17], v[166:169], v[198:201], v[14:17]
	v_mfma_f32_16x16x32_bf16 v[6:9], v[174:177], v[198:201], v[6:9]
	v_mfma_f32_16x16x32_bf16 v[22:25], v[166:169], v[206:209], v[22:25]
	v_mfma_f32_16x16x32_bf16 v[18:21], v[174:177], v[206:209], v[18:21]
	v_mfma_f32_16x16x32_bf16 v[38:41], v[166:169], v[214:217], v[38:41]
	v_mfma_f32_16x16x32_bf16 v[26:29], v[174:177], v[214:217], v[26:29]
	s_setprio 0
	s_barrier
	s_mov_b32 m0, s45
	s_add_u32 s54, s20, 0x100000
	ds_read_b128 v[186:189], v143 offset:16384
	ds_read_b128 v[190:193], v143 offset:17408
	global_load_lds_dwordx4 v132, s[20:21]
	ds_read_b128 v[194:197], v143 offset:18432
	s_mov_b32 m0, s46
	s_addc_u32 s55, s21, 0
	global_load_lds_dwordx4 v136, s[20:21]
	ds_read_b128 v[198:201], v143 offset:19456
	s_mov_b32 m0, s47
	s_nop 0
	global_load_lds_dwordx4 v132, s[54:55]
	ds_read_b128 v[202:205], v143 offset:20480
	s_mov_b32 m0, s48
	s_nop 0
	global_load_lds_dwordx4 v136, s[54:55]
	ds_read_b128 v[206:209], v143 offset:21504
	s_add_u32 s58, s22, s4
	s_addc_u32 s59, s23, s5
	s_mov_b32 m0, s28
	s_nop 0
	global_load_lds_dwordx4 v130, s[22:23]
	ds_read_b128 v[210:213], v143 offset:22528
	s_mov_b32 m0, s29
	s_nop 0
	global_load_lds_dwordx4 v134, s[22:23]
	ds_read_b128 v[214:217], v143 offset:23552
	s_waitcnt vmcnt(8)
	s_waitcnt lgkmcnt(0)
	s_barrier
	s_setprio 1
	s_waitcnt lgkmcnt(0)
	v_mfma_f32_16x16x32_bf16 v[94:97], v[146:149], v[186:189], v[94:97]
	v_mfma_f32_16x16x32_bf16 v[86:89], v[154:157], v[186:189], v[86:89]
	v_mfma_f32_16x16x32_bf16 v[102:105], v[146:149], v[194:197], v[102:105]
	v_mfma_f32_16x16x32_bf16 v[98:101], v[154:157], v[194:197], v[98:101]
	v_mfma_f32_16x16x32_bf16 v[110:113], v[146:149], v[202:205], v[110:113]
	v_mfma_f32_16x16x32_bf16 v[106:109], v[154:157], v[202:205], v[106:109]
	v_mfma_f32_16x16x32_bf16 v[126:129], v[146:149], v[210:213], v[126:129]
	v_mfma_f32_16x16x32_bf16 v[122:125], v[154:157], v[210:213], v[122:125]
	v_mfma_f32_16x16x32_bf16 v[94:97], v[150:153], v[190:193], v[94:97]
	v_mfma_f32_16x16x32_bf16 v[86:89], v[158:161], v[190:193], v[86:89]
	v_mfma_f32_16x16x32_bf16 v[102:105], v[150:153], v[198:201], v[102:105]
	v_mfma_f32_16x16x32_bf16 v[98:101], v[158:161], v[198:201], v[98:101]
	v_mfma_f32_16x16x32_bf16 v[110:113], v[150:153], v[206:209], v[110:113]
	v_mfma_f32_16x16x32_bf16 v[106:109], v[158:161], v[206:209], v[106:109]
	v_mfma_f32_16x16x32_bf16 v[126:129], v[150:153], v[214:217], v[126:129]
	v_mfma_f32_16x16x32_bf16 v[122:125], v[158:161], v[214:217], v[122:125]
	s_setprio 0
	s_setprio 1
	v_mfma_f32_16x16x32_bf16 v[58:61], v[162:165], v[186:189], v[58:61]
	v_mfma_f32_16x16x32_bf16 v[46:49], v[170:173], v[186:189], v[46:49]
	v_mfma_f32_16x16x32_bf16 v[74:77], v[162:165], v[194:197], v[74:77]
	v_mfma_f32_16x16x32_bf16 v[66:69], v[170:173], v[194:197], v[66:69]
	v_mfma_f32_16x16x32_bf16 v[90:93], v[162:165], v[202:205], v[90:93]
	v_mfma_f32_16x16x32_bf16 v[82:85], v[170:173], v[202:205], v[82:85]
	v_mfma_f32_16x16x32_bf16 v[118:121], v[162:165], v[210:213], v[118:121]
	v_mfma_f32_16x16x32_bf16 v[114:117], v[170:173], v[210:213], v[114:117]
	v_mfma_f32_16x16x32_bf16 v[58:61], v[166:169], v[190:193], v[58:61]
	v_mfma_f32_16x16x32_bf16 v[46:49], v[174:177], v[190:193], v[46:49]
	v_mfma_f32_16x16x32_bf16 v[74:77], v[166:169], v[198:201], v[74:77]
	v_mfma_f32_16x16x32_bf16 v[66:69], v[174:177], v[198:201], v[66:69]
	v_mfma_f32_16x16x32_bf16 v[90:93], v[166:169], v[206:209], v[90:93]
	v_mfma_f32_16x16x32_bf16 v[82:85], v[174:177], v[206:209], v[82:85]
	v_mfma_f32_16x16x32_bf16 v[118:121], v[166:169], v[214:217], v[118:121]
	v_mfma_f32_16x16x32_bf16 v[114:117], v[174:177], v[214:217], v[114:117]
	s_setprio 0
	s_barrier
; #define PG8_STAGE(bufoff, gbase, voff) do { _Pragma("unroll") for (int _i = 0; _i < 2; ++_i) \
;         __builtin_amdgcn_global_load_lds((const unsigned*)((const char*)(gbase) + (voff)[_i]), (LAS unsigned*)(lds + (bufoff) + ldsw + _i * 8192), 16, 0, 0); } while (0)
; #define PG8_LDA(dst, b, h) do { _Pragma("unroll") for (int m = 0; m < 4; ++m) _Pragma("unroll") for (int k = 0; k < 2; ++k) dst[m][k] = *(const LAS bf16x8*)(lds + PG8_SA(b, h) + aoff + m * 2048 + k * 1024); } while (0)
; #define PG8_LDB(dst, b, h) do { _Pragma("unroll") for (int n = 0; n < 2; ++n) _Pragma("unroll") for (int k = 0; k < 2; ++k) dst[n][k] = *(const LAS bf16x8*)(lds + PG8_SB(b, h) + boff + n * 2048 + k * 1024); } while (0)
; #define PG8_MMA(ai, bj, At, Bt) do { __builtin_amdgcn_s_setprio(1); _Pragma("unroll") for (int m = 0; m < 4; ++m) _Pragma("unroll") for (int n = 0; n < 2; ++n) _Pragma("unroll") for (int k = 0; k < 2; ++k) \
;         acc[ai][bj][m][n] = __builtin_amdgcn_mfma_f32_16x16x32_bf16(Bt[n][k], At[m][k], acc[ai][bj][m][n], 0, 0, 0); __builtin_amdgcn_s_setprio(0); } while (0)
; #define PG8_WAIT_V(n) asm volatile("s_waitcnt vmcnt(" #n ")" ::: "memory")
; #define PG8_WAIT_L(n) asm volatile("s_waitcnt lgkmcnt(" #n ")" ::: "memory")
; #define PG8_BAR __builtin_amdgcn_s_barrier()
; #define PG8_SCHED __builtin_amdgcn_sched_barrier(0)
; template <class Epi, class Sched, bool ALIGN_EPI, class Hook = NoHook>
; __device__ __forceinline__ void gemm_phase(LAS unsigned char* lds, const Gemm g, const Sched& S, const Epi& E, const Hook& H = Hook()) {
;     ...
;             PG8_LDB(B0, 1, 0); PG8_LDB(B1, 1, 1); PG8_SCHED; PG8_LDA(At, 1, 0); PG8_STAGE(PG8_SA(0, 1), a2 + hA, voffA);
;             PG8_WAIT_V(8); PG8_WAIT_L(0); PG8_BAR; PG8_MMA(0, 0, At, B0); PG8_MMA(0, 1, At, B1); PG8_BAR; PG8_SCHED;
;             PG8_LDA(At, 1, 1); PG8_STAGE(PG8_SB(1, 0), b3, voffB); PG8_STAGE(PG8_SB(1, 1), b3 + hB, voffB); PG8_STAGE(PG8_SA(1, 0), a3, voffA);
;             PG8_WAIT_V(8); PG8_WAIT_L(0); PG8_BAR; PG8_MMA(1, 0, At, B0); PG8_MMA(1, 1, At, B1); PG8_BAR; PG8_SCHED;
;         }
	ds_read_b128 v[146:149], v144
	ds_read_b128 v[150:153], v144 offset:1024
	s_add_u32 s22, s22, 0x100000
	s_addc_u32 s23, s23, 0
	s_mov_b32 m0, s38
	s_nop 0
	global_load_lds_dwordx4 v130, s[22:23]
	ds_read_b128 v[154:157], v144 offset:2048
	ds_read_b128 v[158:161], v144 offset:3072
	ds_read_b128 v[162:165], v145
	ds_read_b128 v[166:169], v145 offset:1024
	ds_read_b128 v[170:173], v145 offset:2048
	ds_read_b128 v[174:177], v145 offset:3072
	ds_read_b128 v[186:189], v143 offset:32768
	s_mov_b32 m0, s39
	s_nop 0
	global_load_lds_dwordx4 v134, s[22:23]
	ds_read_b128 v[190:193], v143 offset:33792
	ds_read_b128 v[194:197], v143 offset:34816
	ds_read_b128 v[198:201], v143 offset:35840
	ds_read_b128 v[202:205], v143 offset:36864
	ds_read_b128 v[206:209], v143 offset:37888
	ds_read_b128 v[210:213], v143 offset:38912
	ds_read_b128 v[214:217], v143 offset:39936
	s_waitcnt vmcnt(8)
	s_waitcnt lgkmcnt(0)
	s_barrier
	s_setprio 1
	s_waitcnt lgkmcnt(0)
	v_mfma_f32_16x16x32_bf16 v[54:57], v[146:149], v[186:189], v[54:57]
	v_mfma_f32_16x16x32_bf16 v[34:37], v[154:157], v[186:189], v[34:37]
	v_mfma_f32_16x16x32_bf16 v[42:45], v[146:149], v[194:197], v[42:45]
	v_mfma_f32_16x16x32_bf16 v[30:33], v[154:157], v[194:197], v[30:33]
	v_mfma_f32_16x16x32_bf16 v[62:65], v[146:149], v[202:205], v[62:65]
	v_mfma_f32_16x16x32_bf16 v[50:53], v[154:157], v[202:205], v[50:53]
	v_mfma_f32_16x16x32_bf16 v[78:81], v[146:149], v[210:213], v[78:81]
	v_mfma_f32_16x16x32_bf16 v[70:73], v[154:157], v[210:213], v[70:73]
	v_mfma_f32_16x16x32_bf16 v[54:57], v[150:153], v[190:193], v[54:57]
	v_mfma_f32_16x16x32_bf16 v[34:37], v[158:161], v[190:193], v[34:37]
	v_mfma_f32_16x16x32_bf16 v[42:45], v[150:153], v[198:201], v[42:45]
	v_mfma_f32_16x16x32_bf16 v[30:33], v[158:161], v[198:201], v[30:33]
	v_mfma_f32_16x16x32_bf16 v[62:65], v[150:153], v[206:209], v[62:65]
	v_mfma_f32_16x16x32_bf16 v[50:53], v[158:161], v[206:209], v[50:53]
	v_mfma_f32_16x16x32_bf16 v[78:81], v[150:153], v[214:217], v[78:81]
	v_mfma_f32_16x16x32_bf16 v[70:73], v[158:161], v[214:217], v[70:73]
	s_setprio 0
	s_setprio 1
	v_mfma_f32_16x16x32_bf16 v[10:13], v[162:165], v[186:189], v[10:13]
	v_mfma_f32_16x16x32_bf16 v[2:5], v[170:173], v[186:189], v[2:5]
	v_mfma_f32_16x16x32_bf16 v[14:17], v[162:165], v[194:197], v[14:17]
	v_mfma_f32_16x16x32_bf16 v[6:9], v[170:173], v[194:197], v[6:9]
	v_mfma_f32_16x16x32_bf16 v[22:25], v[162:165], v[202:205], v[22:25]
	v_mfma_f32_16x16x32_bf16 v[18:21], v[170:173], v[202:205], v[18:21]
	v_mfma_f32_16x16x32_bf16 v[38:41], v[162:165], v[210:213], v[38:41]
	v_mfma_f32_16x16x32_bf16 v[26:29], v[170:173], v[210:213], v[26:29]
	v_mfma_f32_16x16x32_bf16 v[10:13], v[166:169], v[190:193], v[10:13]
	v_mfma_f32_16x16x32_bf16 v[2:5], v[174:177], v[190:193], v[2:5]
	v_mfma_f32_16x16x32_bf16 v[14:17], v[166:169], v[198:201], v[14:17]
	v_mfma_f32_16x16x32_bf16 v[6:9], v[174:177], v[198:201], v[6:9]
	v_mfma_f32_16x16x32_bf16 v[22:25], v[166:169], v[206:209], v[22:25]
	v_mfma_f32_16x16x32_bf16 v[18:21], v[174:177], v[206:209], v[18:21]
	v_mfma_f32_16x16x32_bf16 v[38:41], v[166:169], v[214:217], v[38:41]
	v_mfma_f32_16x16x32_bf16 v[26:29], v[174:177], v[214:217], v[26:29]
	s_setprio 0
	s_barrier
	s_mov_b32 m0, s49
	s_add_u32 s56, s20, s4
	s_addc_u32 s57, s21, s5
	s_add_u32 s20, s20, 0x100080
	ds_read_b128 v[186:189], v143 offset:49152
	ds_read_b128 v[190:193], v143 offset:50176
	global_load_lds_dwordx4 v132, s[56:57]
	ds_read_b128 v[194:197], v143 offset:51200
	s_mov_b32 m0, s50
	s_addc_u32 s21, s21, 0
	global_load_lds_dwordx4 v136, s[56:57]
	ds_read_b128 v[198:201], v143 offset:52224
	s_mov_b32 m0, s51
	s_nop 0
	global_load_lds_dwordx4 v132, s[20:21]
	ds_read_b128 v[202:205], v143 offset:53248
	s_mov_b32 m0, s52
	s_nop 0
	global_load_lds_dwordx4 v136, s[20:21]
	ds_read_b128 v[206:209], v143 offset:54272
	s_mov_b32 m0, s40
	s_nop 0
	global_load_lds_dwordx4 v130, s[58:59]
	ds_read_b128 v[210:213], v143 offset:55296
	s_mov_b32 m0, s41
	s_nop 0
	global_load_lds_dwordx4 v134, s[58:59]
	ds_read_b128 v[214:217], v143 offset:56320
	s_waitcnt vmcnt(8)
	s_waitcnt lgkmcnt(0)
	s_barrier
	s_setprio 1
	s_waitcnt lgkmcnt(0)
	v_mfma_f32_16x16x32_bf16 v[94:97], v[146:149], v[186:189], v[94:97]
	v_mfma_f32_16x16x32_bf16 v[86:89], v[154:157], v[186:189], v[86:89]
	v_mfma_f32_16x16x32_bf16 v[102:105], v[146:149], v[194:197], v[102:105]
	v_mfma_f32_16x16x32_bf16 v[98:101], v[154:157], v[194:197], v[98:101]
	v_mfma_f32_16x16x32_bf16 v[110:113], v[146:149], v[202:205], v[110:113]
	v_mfma_f32_16x16x32_bf16 v[106:109], v[154:157], v[202:205], v[106:109]
	v_mfma_f32_16x16x32_bf16 v[126:129], v[146:149], v[210:213], v[126:129]
	v_mfma_f32_16x16x32_bf16 v[122:125], v[154:157], v[210:213], v[122:125]
	v_mfma_f32_16x16x32_bf16 v[94:97], v[150:153], v[190:193], v[94:97]
	v_mfma_f32_16x16x32_bf16 v[86:89], v[158:161], v[190:193], v[86:89]
	v_mfma_f32_16x16x32_bf16 v[102:105], v[150:153], v[198:201], v[102:105]
	v_mfma_f32_16x16x32_bf16 v[98:101], v[158:161], v[198:201], v[98:101]
	v_mfma_f32_16x16x32_bf16 v[110:113], v[150:153], v[206:209], v[110:113]
	v_mfma_f32_16x16x32_bf16 v[106:109], v[158:161], v[206:209], v[106:109]
	v_mfma_f32_16x16x32_bf16 v[126:129], v[150:153], v[214:217], v[126:129]
	v_mfma_f32_16x16x32_bf16 v[122:125], v[158:161], v[214:217], v[122:125]
	s_setprio 0
	s_setprio 1
	v_mfma_f32_16x16x32_bf16 v[58:61], v[162:165], v[186:189], v[58:61]
	v_mfma_f32_16x16x32_bf16 v[46:49], v[170:173], v[186:189], v[46:49]
	v_mfma_f32_16x16x32_bf16 v[74:77], v[162:165], v[194:197], v[74:77]
	v_mfma_f32_16x16x32_bf16 v[66:69], v[170:173], v[194:197], v[66:69]
	v_mfma_f32_16x16x32_bf16 v[90:93], v[162:165], v[202:205], v[90:93]
	v_mfma_f32_16x16x32_bf16 v[82:85], v[170:173], v[202:205], v[82:85]
	v_mfma_f32_16x16x32_bf16 v[118:121], v[162:165], v[210:213], v[118:121]
	v_mfma_f32_16x16x32_bf16 v[114:117], v[170:173], v[210:213], v[114:117]
	v_mfma_f32_16x16x32_bf16 v[58:61], v[166:169], v[190:193], v[58:61]
	v_mfma_f32_16x16x32_bf16 v[46:49], v[174:177], v[190:193], v[46:49]
	v_mfma_f32_16x16x32_bf16 v[74:77], v[166:169], v[198:201], v[74:77]
	v_mfma_f32_16x16x32_bf16 v[66:69], v[174:177], v[198:201], v[66:69]
	v_mfma_f32_16x16x32_bf16 v[90:93], v[166:169], v[206:209], v[90:93]
	v_mfma_f32_16x16x32_bf16 v[82:85], v[174:177], v[206:209], v[82:85]
	v_mfma_f32_16x16x32_bf16 v[118:121], v[166:169], v[214:217], v[118:121]
	v_mfma_f32_16x16x32_bf16 v[114:117], v[174:177], v[214:217], v[114:117]
	s_setprio 0
	s_barrier
	s_add_i32 s42, s42, 2
	s_add_u32 s6, s6, 0x100
	s_addc_u32 s7, s7, 0
	s_cmp_gt_u32 s42, 61
	s_cbranch_scc0 .LBB0_850
	s_cmpk_lt_u32 s26, 0x100
	s_cbranch_scc0 .LBB0_853
	s_barrier

; #define PG8_STAGE(bufoff, gbase, voff) do { _Pragma("unroll") for (int _i = 0; _i < 2; ++_i) \
;         __builtin_amdgcn_global_load_lds((const unsigned*)((const char*)(gbase) + (voff)[_i]), (LAS unsigned*)(lds + (bufoff) + ldsw + _i * 8192), 16, 0, 0); } while (0)
; #define PG8_LDA(dst, b, h) do { _Pragma("unroll") for (int m = 0; m < 4; ++m) _Pragma("unroll") for (int k = 0; k < 2; ++k) dst[m][k] = *(const LAS bf16x8*)(lds + PG8_SA(b, h) + aoff + m * 2048 + k * 1024); } while (0)
; #define PG8_LDB(dst, b, h) do { _Pragma("unroll") for (int n = 0; n < 2; ++n) _Pragma("unroll") for (int k = 0; k < 2; ++k) dst[n][k] = *(const LAS bf16x8*)(lds + PG8_SB(b, h) + boff + n * 2048 + k * 1024); } while (0)
; #define PG8_MMA(ai, bj, At, Bt) do { __builtin_amdgcn_s_setprio(1); _Pragma("unroll") for (int m = 0; m < 4; ++m) _Pragma("unroll") for (int n = 0; n < 2; ++n) _Pragma("unroll") for (int k = 0; k < 2; ++k) \
;         acc[ai][bj][m][n] = __builtin_amdgcn_mfma_f32_16x16x32_bf16(Bt[n][k], At[m][k], acc[ai][bj][m][n], 0, 0, 0); __builtin_amdgcn_s_setprio(0); } while (0)
; #define PG8_WAIT_V(n) asm volatile("s_waitcnt vmcnt(" #n ")" ::: "memory")
; #define PG8_WAIT_L(n) asm volatile("s_waitcnt lgkmcnt(" #n ")" ::: "memory")
; #define PG8_BAR __builtin_amdgcn_s_barrier()
; template <class Epi, class Sched, bool ALIGN_EPI, class Hook = NoHook>
; __device__ __forceinline__ void gemm_phase(LAS unsigned char* lds, const Gemm g, const Sched& S, const Epi& E, const Hook& H = Hook()) {
;     ...
;             const bool last = (t == nt - 2);
;             const char* a1 = cA + (size_t)(t + 1) * kstep;
;             const char* a2 = last ? nA : cA + (size_t)(t + 2) * kstep; const char* b2 = last ? nB : cB + (size_t)(t + 2) * kstep;
;             const char* a3 = a2 + kstep; const char* b3 = b2 + kstep;
;             if (last && has_next) S.a_ready(nxt);
;             PG8_LDB(B0, 0, 0); PG8_LDB(B1, 0, 1); PG8_SCHED; PG8_LDA(At, 0, 0); PG8_STAGE(PG8_SA(1, 1), a1 + hA, voffA);
;             PG8_WAIT_V(8); PG8_WAIT_L(0); PG8_BAR; PG8_MMA(0, 0, At, B0); PG8_MMA(0, 1, At, B1); PG8_BAR; PG8_SCHED;
;             PG8_LDA(At, 0, 1); PG8_STAGE(PG8_SB(0, 0), b2, voffB); PG8_STAGE(PG8_SB(0, 1), b2 + hB, voffB); PG8_STAGE(PG8_SA(0, 0), a2, voffA);
;             PG8_WAIT_V(8); PG8_WAIT_L(0); PG8_BAR; PG8_MMA(1, 0, At, B0); PG8_MMA(1, 1, At, B1); PG8_BAR; PG8_SCHED;
.LBB0_896:
	ds_read_b128 v[146:149], v140
	ds_read_b128 v[150:153], v140 offset:1024
	s_add_u32 s10, s6, 0x87c00080
	s_addc_u32 s11, s7, -1
	s_cmp_lg_u32 s18, 60
	s_cselect_b32 s10, s10, 0
	s_cselect_b32 s11, s11, 0
	s_add_u32 s16, s2, s10
	s_addc_u32 s17, s3, s11
	s_add_u32 s10, s14, s10
	s_addc_u32 s11, s15, s11
	s_mov_b32 m0, s19
	ds_read_b128 v[154:157], v140 offset:2048
	ds_read_b128 v[158:161], v140 offset:3072
	ds_read_b128 v[162:165], v141
	ds_read_b128 v[166:169], v141 offset:1024
	ds_read_b128 v[170:173], v141 offset:2048
	ds_read_b128 v[174:177], v141 offset:3072
	v_lshl_add_u64 v[178:179], v[136:137], 0, s[6:7]
	global_load_lds_dwordx4 v[178:179], off
	ds_read_b128 v[186:189], v142
	ds_read_b128 v[190:193], v142 offset:1024
	ds_read_b128 v[194:197], v142 offset:2048
	ds_read_b128 v[198:201], v142 offset:3072
	ds_read_b128 v[202:205], v142 offset:4096
	ds_read_b128 v[206:209], v142 offset:5120
	ds_read_b128 v[210:213], v142 offset:6144
	ds_read_b128 v[214:217], v142 offset:7168
	v_lshl_add_u64 v[178:179], v[138:139], 0, s[6:7]
	s_mov_b32 m0, s31
	s_nop 0
	global_load_lds_dwordx4 v[178:179], off
	s_waitcnt vmcnt(8)
	s_waitcnt lgkmcnt(0)
	s_barrier
	s_setprio 1
	s_waitcnt lgkmcnt(0)
	v_mfma_f32_16x16x32_bf16 v[54:57], v[146:149], v[186:189], v[54:57]
	v_mfma_f32_16x16x32_bf16 v[34:37], v[154:157], v[186:189], v[34:37]
	v_mfma_f32_16x16x32_bf16 v[42:45], v[146:149], v[194:197], v[42:45]
	v_mfma_f32_16x16x32_bf16 v[30:33], v[154:157], v[194:197], v[30:33]
	v_mfma_f32_16x16x32_bf16 v[62:65], v[146:149], v[202:205], v[62:65]
	v_mfma_f32_16x16x32_bf16 v[50:53], v[154:157], v[202:205], v[50:53]
	v_mfma_f32_16x16x32_bf16 v[78:81], v[146:149], v[210:213], v[78:81]
	v_mfma_f32_16x16x32_bf16 v[70:73], v[154:157], v[210:213], v[70:73]
	v_mfma_f32_16x16x32_bf16 v[54:57], v[150:153], v[190:193], v[54:57]
	v_mfma_f32_16x16x32_bf16 v[34:37], v[158:161], v[190:193], v[34:37]
	v_mfma_f32_16x16x32_bf16 v[42:45], v[150:153], v[198:201], v[42:45]
	v_mfma_f32_16x16x32_bf16 v[30:33], v[158:161], v[198:201], v[30:33]
	v_mfma_f32_16x16x32_bf16 v[62:65], v[150:153], v[206:209], v[62:65]
	v_mfma_f32_16x16x32_bf16 v[50:53], v[158:161], v[206:209], v[50:53]
	v_mfma_f32_16x16x32_bf16 v[78:81], v[150:153], v[214:217], v[78:81]
	v_mfma_f32_16x16x32_bf16 v[70:73], v[158:161], v[214:217], v[70:73]
	s_setprio 0
	s_setprio 1
	v_mfma_f32_16x16x32_bf16 v[10:13], v[162:165], v[186:189], v[10:13]
	v_mfma_f32_16x16x32_bf16 v[2:5], v[170:173], v[186:189], v[2:5]
	v_mfma_f32_16x16x32_bf16 v[14:17], v[162:165], v[194:197], v[14:17]
	v_mfma_f32_16x16x32_bf16 v[6:9], v[170:173], v[194:197], v[6:9]
	v_mfma_f32_16x16x32_bf16 v[22:25], v[162:165], v[202:205], v[22:25]
	v_mfma_f32_16x16x32_bf16 v[18:21], v[170:173], v[202:205], v[18:21]
	v_mfma_f32_16x16x32_bf16 v[38:41], v[162:165], v[210:213], v[38:41]
	v_mfma_f32_16x16x32_bf16 v[26:29], v[170:173], v[210:213], v[26:29]
	v_mfma_f32_16x16x32_bf16 v[10:13], v[166:169], v[190:193], v[10:13]
	v_mfma_f32_16x16x32_bf16 v[2:5], v[174:177], v[190:193], v[2:5]
	v_mfma_f32_16x16x32_bf16 v[14:17], v[166:169], v[198:201], v[14:17]
	v_mfma_f32_16x16x32_bf16 v[6:9], v[174:177], v[198:201], v[6:9]
	v_mfma_f32_16x16x32_bf16 v[22:25], v[166:169], v[206:209], v[22:25]
	v_mfma_f32_16x16x32_bf16 v[18:21], v[174:177], v[206:209], v[18:21]
	v_mfma_f32_16x16x32_bf16 v[38:41], v[166:169], v[214:217], v[38:41]
	v_mfma_f32_16x16x32_bf16 v[26:29], v[174:177], v[214:217], v[26:29]
	s_setprio 0
	s_barrier
	s_mov_b32 m0, s33
	s_add_u32 s46, s10, 0x100000
	ds_read_b128 v[186:189], v142 offset:16384
	ds_read_b128 v[190:193], v142 offset:17408
	global_load_lds_dwordx4 v180, s[10:11]
	ds_read_b128 v[194:197], v142 offset:18432
	s_mov_b32 m0, s34
	s_addc_u32 s47, s11, 0
	global_load_lds_dwordx4 v134, s[10:11]
	ds_read_b128 v[198:201], v142 offset:19456
	s_mov_b32 m0, s35
	s_nop 0
	global_load_lds_dwordx4 v180, s[46:47]
	ds_read_b128 v[202:205], v142 offset:20480
	s_mov_b32 m0, s42
	s_nop 0
	global_load_lds_dwordx4 v134, s[46:47]
	ds_read_b128 v[206:209], v142 offset:21504
	s_add_u32 s50, s16, s4
	s_addc_u32 s51, s17, s5
	s_mov_b32 m0, s27
	s_nop 0
	global_load_lds_dwordx4 v130, s[16:17]
	ds_read_b128 v[210:213], v142 offset:22528
	s_mov_b32 m0, s28
	s_nop 0
	global_load_lds_dwordx4 v132, s[16:17]
	ds_read_b128 v[214:217], v142 offset:23552
	s_waitcnt vmcnt(8)
	s_waitcnt lgkmcnt(0)
	s_barrier
	s_setprio 1
	s_waitcnt lgkmcnt(0)
	v_mfma_f32_16x16x32_bf16 v[94:97], v[146:149], v[186:189], v[94:97]
	v_mfma_f32_16x16x32_bf16 v[86:89], v[154:157], v[186:189], v[86:89]
	v_mfma_f32_16x16x32_bf16 v[102:105], v[146:149], v[194:197], v[102:105]
	v_mfma_f32_16x16x32_bf16 v[98:101], v[154:157], v[194:197], v[98:101]
	v_mfma_f32_16x16x32_bf16 v[110:113], v[146:149], v[202:205], v[110:113]
	v_mfma_f32_16x16x32_bf16 v[106:109], v[154:157], v[202:205], v[106:109]
	v_mfma_f32_16x16x32_bf16 v[126:129], v[146:149], v[210:213], v[126:129]
	v_mfma_f32_16x16x32_bf16 v[122:125], v[154:157], v[210:213], v[122:125]
	v_mfma_f32_16x16x32_bf16 v[94:97], v[150:153], v[190:193], v[94:97]
	v_mfma_f32_16x16x32_bf16 v[86:89], v[158:161], v[190:193], v[86:89]
	v_mfma_f32_16x16x32_bf16 v[102:105], v[150:153], v[198:201], v[102:105]
	v_mfma_f32_16x16x32_bf16 v[98:101], v[158:161], v[198:201], v[98:101]
	v_mfma_f32_16x16x32_bf16 v[110:113], v[150:153], v[206:209], v[110:113]
	v_mfma_f32_16x16x32_bf16 v[106:109], v[158:161], v[206:209], v[106:109]
	v_mfma_f32_16x16x32_bf16 v[126:129], v[150:153], v[214:217], v[126:129]
	v_mfma_f32_16x16x32_bf16 v[122:125], v[158:161], v[214:217], v[122:125]
	s_setprio 0
	s_setprio 1
	v_mfma_f32_16x16x32_bf16 v[58:61], v[162:165], v[186:189], v[58:61]
	v_mfma_f32_16x16x32_bf16 v[46:49], v[170:173], v[186:189], v[46:49]
	v_mfma_f32_16x16x32_bf16 v[74:77], v[162:165], v[194:197], v[74:77]
	v_mfma_f32_16x16x32_bf16 v[66:69], v[170:173], v[194:197], v[66:69]
	v_mfma_f32_16x16x32_bf16 v[90:93], v[162:165], v[202:205], v[90:93]
	v_mfma_f32_16x16x32_bf16 v[82:85], v[170:173], v[202:205], v[82:85]
	v_mfma_f32_16x16x32_bf16 v[118:121], v[162:165], v[210:213], v[118:121]
	v_mfma_f32_16x16x32_bf16 v[114:117], v[170:173], v[210:213], v[114:117]
	v_mfma_f32_16x16x32_bf16 v[58:61], v[166:169], v[190:193], v[58:61]
	v_mfma_f32_16x16x32_bf16 v[46:49], v[174:177], v[190:193], v[46:49]
	v_mfma_f32_16x16x32_bf16 v[74:77], v[166:169], v[198:201], v[74:77]
	v_mfma_f32_16x16x32_bf16 v[66:69], v[174:177], v[198:201], v[66:69]
	v_mfma_f32_16x16x32_bf16 v[90:93], v[166:169], v[206:209], v[90:93]
	v_mfma_f32_16x16x32_bf16 v[82:85], v[174:177], v[206:209], v[82:85]
	v_mfma_f32_16x16x32_bf16 v[118:121], v[166:169], v[214:217], v[118:121]
	v_mfma_f32_16x16x32_bf16 v[114:117], v[174:177], v[214:217], v[114:117]
	s_setprio 0
	s_barrier
; #define PG8_STAGE(bufoff, gbase, voff) do { _Pragma("unroll") for (int _i = 0; _i < 2; ++_i) \
;         __builtin_amdgcn_global_load_lds((const unsigned*)((const char*)(gbase) + (voff)[_i]), (LAS unsigned*)(lds + (bufoff) + ldsw + _i * 8192), 16, 0, 0); } while (0)
; #define PG8_LDA(dst, b, h) do { _Pragma("unroll") for (int m = 0; m < 4; ++m) _Pragma("unroll") for (int k = 0; k < 2; ++k) dst[m][k] = *(const LAS bf16x8*)(lds + PG8_SA(b, h) + aoff + m * 2048 + k * 1024); } while (0)
; #define PG8_LDB(dst, b, h) do { _Pragma("unroll") for (int n = 0; n < 2; ++n) _Pragma("unroll") for (int k = 0; k < 2; ++k) dst[n][k] = *(const LAS bf16x8*)(lds + PG8_SB(b, h) + boff + n * 2048 + k * 1024); } while (0)
; #define PG8_MMA(ai, bj, At, Bt) do { __builtin_amdgcn_s_setprio(1); _Pragma("unroll") for (int m = 0; m < 4; ++m) _Pragma("unroll") for (int n = 0; n < 2; ++n) _Pragma("unroll") for (int k = 0; k < 2; ++k) \
;         acc[ai][bj][m][n] = __builtin_amdgcn_mfma_f32_16x16x32_bf16(Bt[n][k], At[m][k], acc[ai][bj][m][n], 0, 0, 0); __builtin_amdgcn_s_setprio(0); } while (0)
; #define PG8_WAIT_V(n) asm volatile("s_waitcnt vmcnt(" #n ")" ::: "memory")
; #define PG8_WAIT_L(n) asm volatile("s_waitcnt lgkmcnt(" #n ")" ::: "memory")
; #define PG8_BAR __builtin_amdgcn_s_barrier()
; #define PG8_SCHED __builtin_amdgcn_sched_barrier(0)
; template <class Epi, class Sched, bool ALIGN_EPI, class Hook = NoHook>
; __device__ __forceinline__ void gemm_phase(LAS unsigned char* lds, const Gemm g, const Sched& S, const Epi& E, const Hook& H = Hook()) {
;     ...
;             PG8_LDB(B0, 1, 0); PG8_LDB(B1, 1, 1); PG8_SCHED; PG8_LDA(At, 1, 0); PG8_STAGE(PG8_SA(0, 1), a2 + hA, voffA);
;             PG8_WAIT_V(8); PG8_WAIT_L(0); PG8_BAR; PG8_MMA(0, 0, At, B0); PG8_MMA(0, 1, At, B1); PG8_BAR; PG8_SCHED;
;             PG8_LDA(At, 1, 1); PG8_STAGE(PG8_SB(1, 0), b3, voffB); PG8_STAGE(PG8_SB(1, 1), b3 + hB, voffB); PG8_STAGE(PG8_SA(1, 0), a3, voffA);
;             PG8_WAIT_V(8); PG8_WAIT_L(0); PG8_BAR; PG8_MMA(1, 0, At, B0); PG8_MMA(1, 1, At, B1); PG8_BAR; PG8_SCHED;
;         }
	ds_read_b128 v[146:149], v143
	ds_read_b128 v[150:153], v143 offset:1024
	s_add_u32 s16, s16, 0x100000
	s_addc_u32 s17, s17, 0
	s_mov_b32 m0, s29
	s_nop 0
	global_load_lds_dwordx4 v130, s[16:17]
	ds_read_b128 v[154:157], v143 offset:2048
	ds_read_b128 v[158:161], v143 offset:3072
	ds_read_b128 v[162:165], v144
	ds_read_b128 v[166:169], v144 offset:1024
	ds_read_b128 v[170:173], v144 offset:2048
	ds_read_b128 v[174:177], v144 offset:3072
	ds_read_b128 v[186:189], v142 offset:32768
	s_mov_b32 m0, s39
	s_nop 0
	global_load_lds_dwordx4 v132, s[16:17]
	ds_read_b128 v[190:193], v142 offset:33792
	ds_read_b128 v[194:197], v142 offset:34816
	ds_read_b128 v[198:201], v142 offset:35840
	ds_read_b128 v[202:205], v142 offset:36864
	ds_read_b128 v[206:209], v142 offset:37888
	ds_read_b128 v[210:213], v142 offset:38912
	ds_read_b128 v[214:217], v142 offset:39936
	s_waitcnt vmcnt(8)
	s_waitcnt lgkmcnt(0)
	s_barrier
	s_setprio 1
	s_waitcnt lgkmcnt(0)
	v_mfma_f32_16x16x32_bf16 v[54:57], v[146:149], v[186:189], v[54:57]
	v_mfma_f32_16x16x32_bf16 v[34:37], v[154:157], v[186:189], v[34:37]
	v_mfma_f32_16x16x32_bf16 v[42:45], v[146:149], v[194:197], v[42:45]
	v_mfma_f32_16x16x32_bf16 v[30:33], v[154:157], v[194:197], v[30:33]
	v_mfma_f32_16x16x32_bf16 v[62:65], v[146:149], v[202:205], v[62:65]
	v_mfma_f32_16x16x32_bf16 v[50:53], v[154:157], v[202:205], v[50:53]
	v_mfma_f32_16x16x32_bf16 v[78:81], v[146:149], v[210:213], v[78:81]
	v_mfma_f32_16x16x32_bf16 v[70:73], v[154:157], v[210:213], v[70:73]
	v_mfma_f32_16x16x32_bf16 v[54:57], v[150:153], v[190:193], v[54:57]
	v_mfma_f32_16x16x32_bf16 v[34:37], v[158:161], v[190:193], v[34:37]
	v_mfma_f32_16x16x32_bf16 v[42:45], v[150:153], v[198:201], v[42:45]
	v_mfma_f32_16x16x32_bf16 v[30:33], v[158:161], v[198:201], v[30:33]
	v_mfma_f32_16x16x32_bf16 v[62:65], v[150:153], v[206:209], v[62:65]
	v_mfma_f32_16x16x32_bf16 v[50:53], v[158:161], v[206:209], v[50:53]
	v_mfma_f32_16x16x32_bf16 v[78:81], v[150:153], v[214:217], v[78:81]
	v_mfma_f32_16x16x32_bf16 v[70:73], v[158:161], v[214:217], v[70:73]
	s_setprio 0
	s_setprio 1
	v_mfma_f32_16x16x32_bf16 v[10:13], v[162:165], v[186:189], v[10:13]
	v_mfma_f32_16x16x32_bf16 v[2:5], v[170:173], v[186:189], v[2:5]
	v_mfma_f32_16x16x32_bf16 v[14:17], v[162:165], v[194:197], v[14:17]
	v_mfma_f32_16x16x32_bf16 v[6:9], v[170:173], v[194:197], v[6:9]
	v_mfma_f32_16x16x32_bf16 v[22:25], v[162:165], v[202:205], v[22:25]
	v_mfma_f32_16x16x32_bf16 v[18:21], v[170:173], v[202:205], v[18:21]
	v_mfma_f32_16x16x32_bf16 v[38:41], v[162:165], v[210:213], v[38:41]
	v_mfma_f32_16x16x32_bf16 v[26:29], v[170:173], v[210:213], v[26:29]
	v_mfma_f32_16x16x32_bf16 v[10:13], v[166:169], v[190:193], v[10:13]
	v_mfma_f32_16x16x32_bf16 v[2:5], v[174:177], v[190:193], v[2:5]
	v_mfma_f32_16x16x32_bf16 v[14:17], v[166:169], v[198:201], v[14:17]
	v_mfma_f32_16x16x32_bf16 v[6:9], v[174:177], v[198:201], v[6:9]
	v_mfma_f32_16x16x32_bf16 v[22:25], v[166:169], v[206:209], v[22:25]
	v_mfma_f32_16x16x32_bf16 v[18:21], v[174:177], v[206:209], v[18:21]
	v_mfma_f32_16x16x32_bf16 v[38:41], v[166:169], v[214:217], v[38:41]
	v_mfma_f32_16x16x32_bf16 v[26:29], v[174:177], v[214:217], v[26:29]
	s_setprio 0
	s_barrier
	s_mov_b32 m0, s36
	s_add_u32 s48, s10, s4
	s_addc_u32 s49, s11, s5
	s_add_u32 s10, s10, 0x100080
	ds_read_b128 v[186:189], v142 offset:49152
	ds_read_b128 v[190:193], v142 offset:50176
	global_load_lds_dwordx4 v180, s[48:49]
	ds_read_b128 v[194:197], v142 offset:51200
	s_mov_b32 m0, s43
	s_addc_u32 s11, s11, 0
	global_load_lds_dwordx4 v134, s[48:49]
	ds_read_b128 v[198:201], v142 offset:52224
	s_mov_b32 m0, s37
	s_nop 0
	global_load_lds_dwordx4 v180, s[10:11]
	ds_read_b128 v[202:205], v142 offset:53248
	s_mov_b32 m0, s44
	s_nop 0
	global_load_lds_dwordx4 v134, s[10:11]
	ds_read_b128 v[206:209], v142 offset:54272
	s_mov_b32 m0, s40
	s_nop 0
	global_load_lds_dwordx4 v130, s[50:51]
	ds_read_b128 v[210:213], v142 offset:55296
	s_mov_b32 m0, s41
	s_nop 0
	global_load_lds_dwordx4 v132, s[50:51]
	ds_read_b128 v[214:217], v142 offset:56320
	s_waitcnt vmcnt(8)
	s_waitcnt lgkmcnt(0)
	s_barrier
	s_setprio 1
	s_waitcnt lgkmcnt(0)
	v_mfma_f32_16x16x32_bf16 v[94:97], v[146:149], v[186:189], v[94:97]
	v_mfma_f32_16x16x32_bf16 v[86:89], v[154:157], v[186:189], v[86:89]
	v_mfma_f32_16x16x32_bf16 v[102:105], v[146:149], v[194:197], v[102:105]
	v_mfma_f32_16x16x32_bf16 v[98:101], v[154:157], v[194:197], v[98:101]
	v_mfma_f32_16x16x32_bf16 v[110:113], v[146:149], v[202:205], v[110:113]
	v_mfma_f32_16x16x32_bf16 v[106:109], v[154:157], v[202:205], v[106:109]
	v_mfma_f32_16x16x32_bf16 v[126:129], v[146:149], v[210:213], v[126:129]
	v_mfma_f32_16x16x32_bf16 v[122:125], v[154:157], v[210:213], v[122:125]
	v_mfma_f32_16x16x32_bf16 v[94:97], v[150:153], v[190:193], v[94:97]
	v_mfma_f32_16x16x32_bf16 v[86:89], v[158:161], v[190:193], v[86:89]
	v_mfma_f32_16x16x32_bf16 v[102:105], v[150:153], v[198:201], v[102:105]
	v_mfma_f32_16x16x32_bf16 v[98:101], v[158:161], v[198:201], v[98:101]
	v_mfma_f32_16x16x32_bf16 v[110:113], v[150:153], v[206:209], v[110:113]
	v_mfma_f32_16x16x32_bf16 v[106:109], v[158:161], v[206:209], v[106:109]
	v_mfma_f32_16x16x32_bf16 v[126:129], v[150:153], v[214:217], v[126:129]
	v_mfma_f32_16x16x32_bf16 v[122:125], v[158:161], v[214:217], v[122:125]
	s_setprio 0
	s_setprio 1
	v_mfma_f32_16x16x32_bf16 v[58:61], v[162:165], v[186:189], v[58:61]
	v_mfma_f32_16x16x32_bf16 v[46:49], v[170:173], v[186:189], v[46:49]
	v_mfma_f32_16x16x32_bf16 v[74:77], v[162:165], v[194:197], v[74:77]
	v_mfma_f32_16x16x32_bf16 v[66:69], v[170:173], v[194:197], v[66:69]
	v_mfma_f32_16x16x32_bf16 v[90:93], v[162:165], v[202:205], v[90:93]
	v_mfma_f32_16x16x32_bf16 v[82:85], v[170:173], v[202:205], v[82:85]
	v_mfma_f32_16x16x32_bf16 v[118:121], v[162:165], v[210:213], v[118:121]
	v_mfma_f32_16x16x32_bf16 v[114:117], v[170:173], v[210:213], v[114:117]
	v_mfma_f32_16x16x32_bf16 v[58:61], v[166:169], v[190:193], v[58:61]
	v_mfma_f32_16x16x32_bf16 v[46:49], v[174:177], v[190:193], v[46:49]
	v_mfma_f32_16x16x32_bf16 v[74:77], v[166:169], v[198:201], v[74:77]
	v_mfma_f32_16x16x32_bf16 v[66:69], v[174:177], v[198:201], v[66:69]
	v_mfma_f32_16x16x32_bf16 v[90:93], v[166:169], v[206:209], v[90:93]
	v_mfma_f32_16x16x32_bf16 v[82:85], v[174:177], v[206:209], v[82:85]
	v_mfma_f32_16x16x32_bf16 v[118:121], v[166:169], v[214:217], v[118:121]
	v_mfma_f32_16x16x32_bf16 v[114:117], v[174:177], v[214:217], v[114:117]
	s_setprio 0
	s_barrier
	s_add_i32 s18, s18, 2
	s_add_u32 s6, s6, 0x100
	s_addc_u32 s7, s7, 0
	s_cmp_gt_u32 s18, 61
	s_cbranch_scc0 .LBB0_896
	s_cmpk_lt_u32 s22, 0x100
	s_cbranch_scc0 .LBB0_899
	s_barrier

; #define PG8_STAGE(bufoff, gbase, voff) do { _Pragma("unroll") for (int _i = 0; _i < 2; ++_i) \
;         __builtin_amdgcn_global_load_lds((const unsigned*)((const char*)(gbase) + (voff)[_i]), (LAS unsigned*)(lds + (bufoff) + ldsw + _i * 8192), 16, 0, 0); } while (0)
; #define PG8_LDA(dst, b, h) do { _Pragma("unroll") for (int m = 0; m < 4; ++m) _Pragma("unroll") for (int k = 0; k < 2; ++k) dst[m][k] = *(const LAS bf16x8*)(lds + PG8_SA(b, h) + aoff + m * 2048 + k * 1024); } while (0)
; #define PG8_LDB(dst, b, h) do { _Pragma("unroll") for (int n = 0; n < 2; ++n) _Pragma("unroll") for (int k = 0; k < 2; ++k) dst[n][k] = *(const LAS bf16x8*)(lds + PG8_SB(b, h) + boff + n * 2048 + k * 1024); } while (0)
; #define PG8_MMA(ai, bj, At, Bt) do { __builtin_amdgcn_s_setprio(1); _Pragma("unroll") for (int m = 0; m < 4; ++m) _Pragma("unroll") for (int n = 0; n < 2; ++n) _Pragma("unroll") for (int k = 0; k < 2; ++k) \
;         acc[ai][bj][m][n] = __builtin_amdgcn_mfma_f32_16x16x32_bf16(Bt[n][k], At[m][k], acc[ai][bj][m][n], 0, 0, 0); __builtin_amdgcn_s_setprio(0); } while (0)
; #define PG8_WAIT_V(n) asm volatile("s_waitcnt vmcnt(" #n ")" ::: "memory")
; #define PG8_WAIT_L(n) asm volatile("s_waitcnt lgkmcnt(" #n ")" ::: "memory")
; #define PG8_BAR __builtin_amdgcn_s_barrier()
; template <class Epi, class Sched, bool ALIGN_EPI, class Hook = NoHook>
; __device__ __forceinline__ void gemm_phase(LAS unsigned char* lds, const Gemm g, const Sched& S, const Epi& E, const Hook& H = Hook()) {
;     ...
;             const bool last = (t == nt - 2);
;             const char* a1 = cA + (size_t)(t + 1) * kstep;
;             const char* a2 = last ? nA : cA + (size_t)(t + 2) * kstep; const char* b2 = last ? nB : cB + (size_t)(t + 2) * kstep;
;             const char* a3 = a2 + kstep; const char* b3 = b2 + kstep;
;             if (last && has_next) S.a_ready(nxt);
;             PG8_LDB(B0, 0, 0); PG8_LDB(B1, 0, 1); PG8_SCHED; PG8_LDA(At, 0, 0); PG8_STAGE(PG8_SA(1, 1), a1 + hA, voffA);
;             PG8_WAIT_V(8); PG8_WAIT_L(0); PG8_BAR; PG8_MMA(0, 0, At, B0); PG8_MMA(0, 1, At, B1); PG8_BAR; PG8_SCHED;
;             PG8_LDA(At, 0, 1); PG8_STAGE(PG8_SB(0, 0), b2, voffB); PG8_STAGE(PG8_SB(0, 1), b2 + hB, voffB); PG8_STAGE(PG8_SA(0, 0), a2, voffA);
;             PG8_WAIT_V(8); PG8_WAIT_L(0); PG8_BAR; PG8_MMA(1, 0, At, B0); PG8_MMA(1, 1, At, B1); PG8_BAR; PG8_SCHED;
.LBB0_1001:
	ds_read_b128 v[106:109], v246
	ds_read_b128 v[110:113], v246 offset:1024
	s_add_u32 s42, s6, 0x100
	s_addc_u32 s43, s7, 0
	s_cmp_eq_u32 s70, 60
	s_cselect_b32 s47, s35, s43
	s_cselect_b32 s46, s66, s42
	s_cselect_b32 s45, s31, s69
	s_cselect_b32 s44, s67, s68
	s_add_i32 m0, s51, 0xc000
	s_nop 0
	global_load_lds_dwordx4 v236, s[6:7]
	ds_read_b128 v[114:117], v246 offset:2048
	ds_read_b128 v[118:121], v246 offset:3072
	ds_read_b128 v[122:125], v247
	ds_read_b128 v[126:129], v247 offset:1024
	ds_read_b128 v[130:133], v247 offset:2048
	ds_read_b128 v[134:137], v247 offset:3072
	ds_read_b128 v[138:141], v248
	s_add_i32 m0, s51, 0xe000
	s_nop 0
	global_load_lds_dwordx4 v238, s[6:7]
	ds_read_b128 v[142:145], v248 offset:1024
	ds_read_b128 v[146:149], v248 offset:2048
	ds_read_b128 v[150:153], v248 offset:3072
	ds_read_b128 v[154:157], v248 offset:4096
	ds_read_b128 v[158:161], v248 offset:5120
	ds_read_b128 v[162:165], v248 offset:6144
	ds_read_b128 v[170:173], v248 offset:7168
	s_waitcnt vmcnt(8)
	s_waitcnt lgkmcnt(0)
	s_barrier
	s_setprio 1
	s_waitcnt lgkmcnt(0)
	v_mfma_f32_16x16x32_bf16 v[190:193], v[106:109], v[138:141], v[190:193]
	v_mfma_f32_16x16x32_bf16 v[178:181], v[114:117], v[138:141], v[178:181]
	v_mfma_f32_16x16x32_bf16 v[182:185], v[106:109], v[146:149], v[182:185]
	v_mfma_f32_16x16x32_bf16 v[98:101], v[114:117], v[146:149], v[98:101]
	v_mfma_f32_16x16x32_bf16 v[102:105], v[106:109], v[154:157], v[102:105]
	v_mfma_f32_16x16x32_bf16 v[86:89], v[114:117], v[154:157], v[86:89]
	v_mfma_f32_16x16x32_bf16 v[78:81], v[106:109], v[162:165], v[78:81]
	v_mfma_f32_16x16x32_bf16 v[70:73], v[114:117], v[162:165], v[70:73]
	v_mfma_f32_16x16x32_bf16 v[190:193], v[110:113], v[142:145], v[190:193]
	v_mfma_f32_16x16x32_bf16 v[178:181], v[118:121], v[142:145], v[178:181]
	v_mfma_f32_16x16x32_bf16 v[182:185], v[110:113], v[150:153], v[182:185]
	v_mfma_f32_16x16x32_bf16 v[98:101], v[118:121], v[150:153], v[98:101]
	v_mfma_f32_16x16x32_bf16 v[102:105], v[110:113], v[158:161], v[102:105]
	v_mfma_f32_16x16x32_bf16 v[86:89], v[118:121], v[158:161], v[86:89]
	v_mfma_f32_16x16x32_bf16 v[78:81], v[110:113], v[170:173], v[78:81]
	v_mfma_f32_16x16x32_bf16 v[70:73], v[118:121], v[170:173], v[70:73]
	s_setprio 0
	s_setprio 1
	v_mfma_f32_16x16x32_bf16 v[186:189], v[122:125], v[138:141], v[186:189]
	v_mfma_f32_16x16x32_bf16 v[138:141], v[130:133], v[138:141], v[174:177]
	v_mfma_f32_16x16x32_bf16 v[94:97], v[130:133], v[146:149], v[94:97]
	v_mfma_f32_16x16x32_bf16 v[90:93], v[122:125], v[154:157], v[90:93]
	v_mfma_f32_16x16x32_bf16 v[82:85], v[130:133], v[154:157], v[82:85]
	v_mfma_f32_16x16x32_bf16 v[74:77], v[122:125], v[162:165], v[74:77]
	v_mfma_f32_16x16x32_bf16 v[66:69], v[130:133], v[162:165], v[66:69]
	v_mfma_f32_16x16x32_bf16 v[186:189], v[126:129], v[142:145], v[186:189]
	v_mfma_f32_16x16x32_bf16 v[138:141], v[134:137], v[142:145], v[138:141]
	v_mfma_f32_16x16x32_bf16 v[142:145], v[122:125], v[146:149], v[166:169]
	v_mfma_f32_16x16x32_bf16 v[94:97], v[134:137], v[150:153], v[94:97]
	v_mfma_f32_16x16x32_bf16 v[90:93], v[126:129], v[158:161], v[90:93]
	v_mfma_f32_16x16x32_bf16 v[82:85], v[134:137], v[158:161], v[82:85]
	v_mfma_f32_16x16x32_bf16 v[74:77], v[126:129], v[170:173], v[74:77]
	v_mfma_f32_16x16x32_bf16 v[66:69], v[134:137], v[170:173], v[66:69]
	v_mfma_f32_16x16x32_bf16 v[142:145], v[126:129], v[150:153], v[142:145]
	s_setprio 0
	s_barrier
	s_add_i32 s6, s63, s29
	s_mov_b32 m0, s6
	ds_read_b128 v[146:149], v248 offset:16384
	ds_read_b128 v[150:153], v248 offset:17408
	global_load_lds_dwordx4 v232, s[44:45]
	ds_read_b128 v[154:157], v248 offset:18432
	s_add_i32 m0, s6, 0x2000
	s_add_u32 s6, s44, 0x100000
	s_addc_u32 s7, s45, 0
	s_add_i32 s71, s64, s29
	global_load_lds_dwordx4 v228, s[44:45]
	ds_read_b128 v[158:161], v248 offset:19456
	s_mov_b32 m0, s71
	s_nop 0
	global_load_lds_dwordx4 v232, s[6:7]
	ds_read_b128 v[162:165], v248 offset:20480
	s_add_i32 m0, s71, 0x2000
	s_nop 0
	global_load_lds_dwordx4 v228, s[6:7]
	ds_read_b128 v[166:169], v248 offset:21504
	s_mov_b32 m0, s51
	s_nop 0
	global_load_lds_dwordx4 v234, s[46:47]
	ds_read_b128 v[170:173], v248 offset:22528
	s_mov_b32 m0, s52
	s_nop 0
	global_load_lds_dwordx4 v230, s[46:47]
	ds_read_b128 v[174:177], v248 offset:23552
	s_waitcnt vmcnt(8)
	s_waitcnt lgkmcnt(0)
	s_barrier
	s_setprio 1
	s_waitcnt lgkmcnt(0)
	v_mfma_f32_16x16x32_bf16 v[62:65], v[106:109], v[146:149], v[62:65]
	v_mfma_f32_16x16x32_bf16 v[54:57], v[114:117], v[146:149], v[54:57]
	v_mfma_f32_16x16x32_bf16 v[46:49], v[106:109], v[154:157], v[46:49]
	v_mfma_f32_16x16x32_bf16 v[22:25], v[114:117], v[154:157], v[22:25]
	v_mfma_f32_16x16x32_bf16 v[42:45], v[106:109], v[162:165], v[42:45]
	v_mfma_f32_16x16x32_bf16 v[10:13], v[114:117], v[162:165], v[10:13]
	v_mfma_f32_16x16x32_bf16 v[38:41], v[106:109], v[170:173], v[38:41]
	v_mfma_f32_16x16x32_bf16 v[14:17], v[114:117], v[170:173], v[14:17]
	v_mfma_f32_16x16x32_bf16 v[62:65], v[110:113], v[150:153], v[62:65]
	v_mfma_f32_16x16x32_bf16 v[54:57], v[118:121], v[150:153], v[54:57]
	v_mfma_f32_16x16x32_bf16 v[46:49], v[110:113], v[158:161], v[46:49]
	v_mfma_f32_16x16x32_bf16 v[22:25], v[118:121], v[158:161], v[22:25]
	v_mfma_f32_16x16x32_bf16 v[42:45], v[110:113], v[166:169], v[42:45]
	v_mfma_f32_16x16x32_bf16 v[10:13], v[118:121], v[166:169], v[10:13]
	v_mfma_f32_16x16x32_bf16 v[38:41], v[110:113], v[174:177], v[38:41]
	v_mfma_f32_16x16x32_bf16 v[14:17], v[118:121], v[174:177], v[14:17]
	s_setprio 0
	s_setprio 1
	v_mfma_f32_16x16x32_bf16 v[58:61], v[122:125], v[146:149], v[58:61]
	v_mfma_f32_16x16x32_bf16 v[50:53], v[130:133], v[146:149], v[50:53]
	v_mfma_f32_16x16x32_bf16 v[34:37], v[122:125], v[154:157], v[34:37]
	v_mfma_f32_16x16x32_bf16 v[18:21], v[130:133], v[154:157], v[18:21]
	v_mfma_f32_16x16x32_bf16 v[30:33], v[122:125], v[162:165], v[30:33]
	v_mfma_f32_16x16x32_bf16 v[2:5], v[130:133], v[162:165], v[2:5]
	v_mfma_f32_16x16x32_bf16 v[26:29], v[122:125], v[170:173], v[26:29]
	v_mfma_f32_16x16x32_bf16 v[6:9], v[130:133], v[170:173], v[6:9]
	v_mfma_f32_16x16x32_bf16 v[58:61], v[126:129], v[150:153], v[58:61]
	v_mfma_f32_16x16x32_bf16 v[50:53], v[134:137], v[150:153], v[50:53]
	v_mfma_f32_16x16x32_bf16 v[34:37], v[126:129], v[158:161], v[34:37]
	v_mfma_f32_16x16x32_bf16 v[18:21], v[134:137], v[158:161], v[18:21]
	v_mfma_f32_16x16x32_bf16 v[30:33], v[126:129], v[166:169], v[30:33]
	v_mfma_f32_16x16x32_bf16 v[2:5], v[134:137], v[166:169], v[2:5]
	v_mfma_f32_16x16x32_bf16 v[26:29], v[126:129], v[174:177], v[26:29]
	v_mfma_f32_16x16x32_bf16 v[6:9], v[134:137], v[174:177], v[6:9]
	s_setprio 0
	s_barrier
; #define PG8_STAGE(bufoff, gbase, voff) do { _Pragma("unroll") for (int _i = 0; _i < 2; ++_i) \
;         __builtin_amdgcn_global_load_lds((const unsigned*)((const char*)(gbase) + (voff)[_i]), (LAS unsigned*)(lds + (bufoff) + ldsw + _i * 8192), 16, 0, 0); } while (0)
; #define PG8_LDA(dst, b, h) do { _Pragma("unroll") for (int m = 0; m < 4; ++m) _Pragma("unroll") for (int k = 0; k < 2; ++k) dst[m][k] = *(const LAS bf16x8*)(lds + PG8_SA(b, h) + aoff + m * 2048 + k * 1024); } while (0)
; #define PG8_LDB(dst, b, h) do { _Pragma("unroll") for (int n = 0; n < 2; ++n) _Pragma("unroll") for (int k = 0; k < 2; ++k) dst[n][k] = *(const LAS bf16x8*)(lds + PG8_SB(b, h) + boff + n * 2048 + k * 1024); } while (0)
; #define PG8_MMA(ai, bj, At, Bt) do { __builtin_amdgcn_s_setprio(1); _Pragma("unroll") for (int m = 0; m < 4; ++m) _Pragma("unroll") for (int n = 0; n < 2; ++n) _Pragma("unroll") for (int k = 0; k < 2; ++k) \
;         acc[ai][bj][m][n] = __builtin_amdgcn_mfma_f32_16x16x32_bf16(Bt[n][k], At[m][k], acc[ai][bj][m][n], 0, 0, 0); __builtin_amdgcn_s_setprio(0); } while (0)
; #define PG8_WAIT_V(n) asm volatile("s_waitcnt vmcnt(" #n ")" ::: "memory")
; #define PG8_WAIT_L(n) asm volatile("s_waitcnt lgkmcnt(" #n ")" ::: "memory")
; #define PG8_BAR __builtin_amdgcn_s_barrier()
; #define PG8_SCHED __builtin_amdgcn_sched_barrier(0)
; template <class Epi, class Sched, bool ALIGN_EPI, class Hook = NoHook>
; __device__ __forceinline__ void gemm_phase(LAS unsigned char* lds, const Gemm g, const Sched& S, const Epi& E, const Hook& H = Hook()) {
;     ...
;             PG8_LDB(B0, 1, 0); PG8_LDB(B1, 1, 1); PG8_SCHED; PG8_LDA(At, 1, 0); PG8_STAGE(PG8_SA(0, 1), a2 + hA, voffA);
;             PG8_WAIT_V(8); PG8_WAIT_L(0); PG8_BAR; PG8_MMA(0, 0, At, B0); PG8_MMA(0, 1, At, B1); PG8_BAR; PG8_SCHED;
;             PG8_LDA(At, 1, 1); PG8_STAGE(PG8_SB(1, 0), b3, voffB); PG8_STAGE(PG8_SB(1, 1), b3 + hB, voffB); PG8_STAGE(PG8_SA(1, 0), a3, voffA);
;             PG8_WAIT_V(8); PG8_WAIT_L(0); PG8_BAR; PG8_MMA(1, 0, At, B0); PG8_MMA(1, 1, At, B1); PG8_BAR; PG8_SCHED;
;         }
	s_add_i32 s71, 0, 0x18000
	s_add_i32 s72, 0, 0x1c000
	v_add_u32_e32 v118, s71, v245
	v_add_u32_e32 v134, s72, v245
	ds_read_b128 v[106:109], v118
	ds_read_b128 v[110:113], v118 offset:1024
	s_add_u32 s6, s46, 0x8000
	s_addc_u32 s7, s47, 0
	s_mov_b32 m0, s53
	s_nop 0
	global_load_lds_dwordx4 v234, s[6:7]
	ds_read_b128 v[114:117], v118 offset:2048
	ds_read_b128 v[118:121], v118 offset:3072
	ds_read_b128 v[122:125], v134
	ds_read_b128 v[126:129], v134 offset:1024
	ds_read_b128 v[130:133], v134 offset:2048
	ds_read_b128 v[134:137], v134 offset:3072
	ds_read_b128 v[146:149], v248 offset:32768
	s_mov_b32 m0, s54
	s_nop 0
	global_load_lds_dwordx4 v230, s[6:7]
	ds_read_b128 v[150:153], v248 offset:33792
	ds_read_b128 v[154:157], v248 offset:34816
	ds_read_b128 v[158:161], v248 offset:35840
	ds_read_b128 v[162:165], v248 offset:36864
	ds_read_b128 v[170:173], v248 offset:37888
	ds_read_b128 v[194:197], v248 offset:38912
	ds_read_b128 v[198:201], v248 offset:39936
	s_waitcnt vmcnt(8)
	s_waitcnt lgkmcnt(0)
	s_barrier
	s_setprio 1
	s_waitcnt lgkmcnt(0)
	v_mfma_f32_16x16x32_bf16 v[166:169], v[106:109], v[146:149], v[190:193]
	v_mfma_f32_16x16x32_bf16 v[190:193], v[110:113], v[150:153], v[166:169]
	v_mfma_f32_16x16x32_bf16 v[166:169], v[114:117], v[146:149], v[178:181]
	v_mfma_f32_16x16x32_bf16 v[178:181], v[118:121], v[150:153], v[166:169]
	v_mfma_f32_16x16x32_bf16 v[166:169], v[106:109], v[154:157], v[182:185]
	v_mfma_f32_16x16x32_bf16 v[98:101], v[114:117], v[154:157], v[98:101]
	v_mfma_f32_16x16x32_bf16 v[102:105], v[106:109], v[162:165], v[102:105]
	v_mfma_f32_16x16x32_bf16 v[86:89], v[114:117], v[162:165], v[86:89]
	v_mfma_f32_16x16x32_bf16 v[78:81], v[106:109], v[194:197], v[78:81]
	v_mfma_f32_16x16x32_bf16 v[70:73], v[114:117], v[194:197], v[70:73]
	v_mfma_f32_16x16x32_bf16 v[182:185], v[110:113], v[158:161], v[166:169]
	v_mfma_f32_16x16x32_bf16 v[98:101], v[118:121], v[158:161], v[98:101]
	v_mfma_f32_16x16x32_bf16 v[102:105], v[110:113], v[170:173], v[102:105]
	v_mfma_f32_16x16x32_bf16 v[86:89], v[118:121], v[170:173], v[86:89]
	v_mfma_f32_16x16x32_bf16 v[78:81], v[110:113], v[198:201], v[78:81]
	v_mfma_f32_16x16x32_bf16 v[70:73], v[118:121], v[198:201], v[70:73]
	s_setprio 0
	s_setprio 1
	v_mfma_f32_16x16x32_bf16 v[138:141], v[130:133], v[146:149], v[138:141]
	v_mfma_f32_16x16x32_bf16 v[166:169], v[122:125], v[146:149], v[186:189]
	v_mfma_f32_16x16x32_bf16 v[174:177], v[134:137], v[150:153], v[138:141]
	v_mfma_f32_16x16x32_bf16 v[138:141], v[122:125], v[154:157], v[142:145]
	v_mfma_f32_16x16x32_bf16 v[94:97], v[130:133], v[154:157], v[94:97]
	v_mfma_f32_16x16x32_bf16 v[90:93], v[122:125], v[162:165], v[90:93]
	v_mfma_f32_16x16x32_bf16 v[82:85], v[130:133], v[162:165], v[82:85]
	v_mfma_f32_16x16x32_bf16 v[74:77], v[122:125], v[194:197], v[74:77]
	v_mfma_f32_16x16x32_bf16 v[66:69], v[130:133], v[194:197], v[66:69]
	v_mfma_f32_16x16x32_bf16 v[186:189], v[126:129], v[150:153], v[166:169]
	v_mfma_f32_16x16x32_bf16 v[166:169], v[126:129], v[158:161], v[138:141]
	v_mfma_f32_16x16x32_bf16 v[94:97], v[134:137], v[158:161], v[94:97]
	v_mfma_f32_16x16x32_bf16 v[90:93], v[126:129], v[170:173], v[90:93]
	v_mfma_f32_16x16x32_bf16 v[82:85], v[134:137], v[170:173], v[82:85]
	v_mfma_f32_16x16x32_bf16 v[74:77], v[126:129], v[198:201], v[74:77]
	v_mfma_f32_16x16x32_bf16 v[66:69], v[134:137], v[198:201], v[66:69]
	s_setprio 0
	s_barrier
	s_add_i32 s6, s71, s29
	s_add_u32 s74, s44, s14
	s_addc_u32 s75, s45, s15
	s_mov_b32 m0, s6
	ds_read_b128 v[138:141], v248 offset:49152
	ds_read_b128 v[142:145], v248 offset:50176
	global_load_lds_dwordx4 v232, s[74:75]
	ds_read_b128 v[146:149], v248 offset:51200
	s_add_i32 m0, s6, 0x2000
	s_add_u32 s6, s44, 0x100080
	s_addc_u32 s7, s45, 0
	s_add_i32 s44, s72, s29
	global_load_lds_dwordx4 v228, s[74:75]
	ds_read_b128 v[150:153], v248 offset:52224
	s_mov_b32 m0, s44
	s_nop 0
	global_load_lds_dwordx4 v232, s[6:7]
	ds_read_b128 v[154:157], v248 offset:53248
	s_add_i32 m0, s44, 0x2000
	s_nop 0
	global_load_lds_dwordx4 v228, s[6:7]
	ds_read_b128 v[158:161], v248 offset:54272
	s_add_u32 s78, s46, s14
	s_addc_u32 s79, s47, s15
	s_mov_b32 m0, s57
	s_nop 0
	global_load_lds_dwordx4 v234, s[78:79]
	ds_read_b128 v[162:165], v248 offset:55296
	s_mov_b32 m0, s58
	s_nop 0
	global_load_lds_dwordx4 v230, s[78:79]
	ds_read_b128 v[170:173], v248 offset:56320
	s_waitcnt vmcnt(8)
	s_waitcnt lgkmcnt(0)
	s_barrier
	s_setprio 1
	s_waitcnt lgkmcnt(0)
	v_mfma_f32_16x16x32_bf16 v[62:65], v[106:109], v[138:141], v[62:65]
	v_mfma_f32_16x16x32_bf16 v[54:57], v[114:117], v[138:141], v[54:57]
	v_mfma_f32_16x16x32_bf16 v[46:49], v[106:109], v[146:149], v[46:49]
	v_mfma_f32_16x16x32_bf16 v[22:25], v[114:117], v[146:149], v[22:25]
	v_mfma_f32_16x16x32_bf16 v[42:45], v[106:109], v[154:157], v[42:45]
	v_mfma_f32_16x16x32_bf16 v[10:13], v[114:117], v[154:157], v[10:13]
	v_mfma_f32_16x16x32_bf16 v[38:41], v[106:109], v[162:165], v[38:41]
	v_mfma_f32_16x16x32_bf16 v[14:17], v[114:117], v[162:165], v[14:17]
	v_mfma_f32_16x16x32_bf16 v[62:65], v[110:113], v[142:145], v[62:65]
	v_mfma_f32_16x16x32_bf16 v[54:57], v[118:121], v[142:145], v[54:57]
	v_mfma_f32_16x16x32_bf16 v[46:49], v[110:113], v[150:153], v[46:49]
	v_mfma_f32_16x16x32_bf16 v[22:25], v[118:121], v[150:153], v[22:25]
	v_mfma_f32_16x16x32_bf16 v[42:45], v[110:113], v[158:161], v[42:45]
	v_mfma_f32_16x16x32_bf16 v[10:13], v[118:121], v[158:161], v[10:13]
	v_mfma_f32_16x16x32_bf16 v[38:41], v[110:113], v[170:173], v[38:41]
	v_mfma_f32_16x16x32_bf16 v[14:17], v[118:121], v[170:173], v[14:17]
	s_setprio 0
	s_setprio 1
	v_mfma_f32_16x16x32_bf16 v[58:61], v[122:125], v[138:141], v[58:61]
	v_mfma_f32_16x16x32_bf16 v[50:53], v[130:133], v[138:141], v[50:53]
	v_mfma_f32_16x16x32_bf16 v[34:37], v[122:125], v[146:149], v[34:37]
	v_mfma_f32_16x16x32_bf16 v[18:21], v[130:133], v[146:149], v[18:21]
	v_mfma_f32_16x16x32_bf16 v[30:33], v[122:125], v[154:157], v[30:33]
	v_mfma_f32_16x16x32_bf16 v[2:5], v[130:133], v[154:157], v[2:5]
	v_mfma_f32_16x16x32_bf16 v[26:29], v[122:125], v[162:165], v[26:29]
	v_mfma_f32_16x16x32_bf16 v[6:9], v[130:133], v[162:165], v[6:9]
	v_mfma_f32_16x16x32_bf16 v[58:61], v[126:129], v[142:145], v[58:61]
	v_mfma_f32_16x16x32_bf16 v[50:53], v[134:137], v[142:145], v[50:53]
	v_mfma_f32_16x16x32_bf16 v[34:37], v[126:129], v[150:153], v[34:37]
	v_mfma_f32_16x16x32_bf16 v[18:21], v[134:137], v[150:153], v[18:21]
	v_mfma_f32_16x16x32_bf16 v[30:33], v[126:129], v[158:161], v[30:33]
	v_mfma_f32_16x16x32_bf16 v[2:5], v[134:137], v[158:161], v[2:5]
	v_mfma_f32_16x16x32_bf16 v[26:29], v[126:129], v[170:173], v[26:29]
	v_mfma_f32_16x16x32_bf16 v[6:9], v[134:137], v[170:173], v[6:9]
	s_setprio 0
	s_barrier
	s_add_i32 s70, s70, 2
	s_add_u32 s68, s68, 0x100
	s_addc_u32 s69, s69, 0
	s_cmp_gt_u32 s70, 61
	s_mov_b64 s[6:7], s[42:43]
	s_cbranch_scc0 .LBB0_1001
	s_and_b64 vcc, exec, s[2:3]
	s_cbranch_vccz .LBB0_1004
	s_barrier

; #define PG8_STAGE(bufoff, gbase, voff) do { _Pragma("unroll") for (int _i = 0; _i < 2; ++_i) \
;         __builtin_amdgcn_global_load_lds((const unsigned*)((const char*)(gbase) + (voff)[_i]), (LAS unsigned*)(lds + (bufoff) + ldsw + _i * 8192), 16, 0, 0); } while (0)
; #define PG8_LDA(dst, b, h) do { _Pragma("unroll") for (int m = 0; m < 4; ++m) _Pragma("unroll") for (int k = 0; k < 2; ++k) dst[m][k] = *(const LAS bf16x8*)(lds + PG8_SA(b, h) + aoff + m * 2048 + k * 1024); } while (0)
; #define PG8_LDB(dst, b, h) do { _Pragma("unroll") for (int n = 0; n < 2; ++n) _Pragma("unroll") for (int k = 0; k < 2; ++k) dst[n][k] = *(const LAS bf16x8*)(lds + PG8_SB(b, h) + boff + n * 2048 + k * 1024); } while (0)
; #define PG8_MMA(ai, bj, At, Bt) do { __builtin_amdgcn_s_setprio(1); _Pragma("unroll") for (int m = 0; m < 4; ++m) _Pragma("unroll") for (int n = 0; n < 2; ++n) _Pragma("unroll") for (int k = 0; k < 2; ++k) \
;         acc[ai][bj][m][n] = __builtin_amdgcn_mfma_f32_16x16x32_bf16(Bt[n][k], At[m][k], acc[ai][bj][m][n], 0, 0, 0); __builtin_amdgcn_s_setprio(0); } while (0)
; #define PG8_WAIT_V(n) asm volatile("s_waitcnt vmcnt(" #n ")" ::: "memory")
; #define PG8_WAIT_L(n) asm volatile("s_waitcnt lgkmcnt(" #n ")" ::: "memory")
; #define PG8_BAR __builtin_amdgcn_s_barrier()
; template <class Epi, class Sched, bool ALIGN_EPI, class Hook = NoHook>
; __device__ __forceinline__ void gemm_phase(LAS unsigned char* lds, const Gemm g, const Sched& S, const Epi& E, const Hook& H = Hook()) {
;     ...
;             const bool last = (t == nt - 2);
;             const char* a1 = cA + (size_t)(t + 1) * kstep;
;             const char* a2 = last ? nA : cA + (size_t)(t + 2) * kstep; const char* b2 = last ? nB : cB + (size_t)(t + 2) * kstep;
;             const char* a3 = a2 + kstep; const char* b3 = b2 + kstep;
;             if (last && has_next) S.a_ready(nxt);
;             PG8_LDB(B0, 0, 0); PG8_LDB(B1, 0, 1); PG8_SCHED; PG8_LDA(At, 0, 0); PG8_STAGE(PG8_SA(1, 1), a1 + hA, voffA);
;             PG8_WAIT_V(8); PG8_WAIT_L(0); PG8_BAR; PG8_MMA(0, 0, At, B0); PG8_MMA(0, 1, At, B1); PG8_BAR; PG8_SCHED;
;             PG8_LDA(At, 0, 1); PG8_STAGE(PG8_SB(0, 0), b2, voffB); PG8_STAGE(PG8_SB(0, 1), b2 + hB, voffB); PG8_STAGE(PG8_SA(0, 0), a2, voffA);
;             PG8_WAIT_V(8); PG8_WAIT_L(0); PG8_BAR; PG8_MMA(1, 0, At, B0); PG8_MMA(1, 1, At, B1); PG8_BAR; PG8_SCHED;
.LBB0_1360:
	ds_read_b128 v[146:149], v1
	ds_read_b128 v[150:153], v1 offset:1024
	s_add_u32 s14, s4, 0xbb050080
	s_addc_u32 s15, s5, -1
	s_cmpk_lg_i32 s41, 0xa8
	s_cselect_b32 s14, s14, 0
	s_cselect_b32 s15, s15, 0
	s_add_u32 s20, s0, s14
	s_addc_u32 s21, s1, s15
	s_add_u32 s14, s12, s14
	s_addc_u32 s15, s13, s15
	s_mov_b32 m0, s42
	ds_read_b128 v[154:157], v1 offset:2048
	ds_read_b128 v[158:161], v1 offset:3072
	ds_read_b128 v[164:167], v142
	ds_read_b128 v[170:173], v142 offset:1024
	ds_read_b128 v[174:177], v142 offset:2048
	ds_read_b128 v[178:181], v142 offset:3072
	v_lshl_add_u64 v[214:215], v[138:139], 0, s[4:5]
	global_load_lds_dwordx4 v[214:215], off
	ds_read_b128 v[182:185], v143
	ds_read_b128 v[186:189], v143 offset:1024
	ds_read_b128 v[190:193], v143 offset:2048
	ds_read_b128 v[194:197], v143 offset:3072
	ds_read_b128 v[198:201], v143 offset:4096
	ds_read_b128 v[202:205], v143 offset:5120
	ds_read_b128 v[206:209], v143 offset:6144
	ds_read_b128 v[210:213], v143 offset:7168
	v_lshl_add_u64 v[214:215], v[140:141], 0, s[4:5]
	s_mov_b32 m0, s43
	s_nop 0
	global_load_lds_dwordx4 v[214:215], off
	s_waitcnt vmcnt(8)
	s_waitcnt lgkmcnt(0)
	s_barrier
	s_setprio 1
	s_waitcnt lgkmcnt(0)
	v_mfma_f32_16x16x32_bf16 v[82:85], v[146:149], v[182:185], v[82:85]
	v_mfma_f32_16x16x32_bf16 v[54:57], v[154:157], v[182:185], v[54:57]
	v_mfma_f32_16x16x32_bf16 v[58:61], v[146:149], v[190:193], v[58:61]
	v_mfma_f32_16x16x32_bf16 v[42:45], v[154:157], v[190:193], v[42:45]
	v_mfma_f32_16x16x32_bf16 v[70:73], v[146:149], v[198:201], v[70:73]
	v_mfma_f32_16x16x32_bf16 v[50:53], v[154:157], v[198:201], v[50:53]
	v_mfma_f32_16x16x32_bf16 v[86:89], v[146:149], v[206:209], v[86:89]
	v_mfma_f32_16x16x32_bf16 v[74:77], v[154:157], v[206:209], v[74:77]
	v_mfma_f32_16x16x32_bf16 v[82:85], v[150:153], v[186:189], v[82:85]
	v_mfma_f32_16x16x32_bf16 v[54:57], v[158:161], v[186:189], v[54:57]
	v_mfma_f32_16x16x32_bf16 v[58:61], v[150:153], v[194:197], v[58:61]
	v_mfma_f32_16x16x32_bf16 v[42:45], v[158:161], v[194:197], v[42:45]
	v_mfma_f32_16x16x32_bf16 v[70:73], v[150:153], v[202:205], v[70:73]
	v_mfma_f32_16x16x32_bf16 v[50:53], v[158:161], v[202:205], v[50:53]
	v_mfma_f32_16x16x32_bf16 v[86:89], v[150:153], v[210:213], v[86:89]
	v_mfma_f32_16x16x32_bf16 v[74:77], v[158:161], v[210:213], v[74:77]
	s_setprio 0
	s_setprio 1
	v_mfma_f32_16x16x32_bf16 v[14:17], v[164:167], v[182:185], v[14:17]
	v_mfma_f32_16x16x32_bf16 v[2:5], v[174:177], v[182:185], v[2:5]
	v_mfma_f32_16x16x32_bf16 v[18:21], v[164:167], v[190:193], v[18:21]
	v_mfma_f32_16x16x32_bf16 v[6:9], v[174:177], v[190:193], v[6:9]
	v_mfma_f32_16x16x32_bf16 v[22:25], v[164:167], v[198:201], v[22:25]
	v_mfma_f32_16x16x32_bf16 v[10:13], v[174:177], v[198:201], v[10:13]
	v_mfma_f32_16x16x32_bf16 v[30:33], v[164:167], v[206:209], v[30:33]
	v_mfma_f32_16x16x32_bf16 v[26:29], v[174:177], v[206:209], v[26:29]
	v_mfma_f32_16x16x32_bf16 v[14:17], v[170:173], v[186:189], v[14:17]
	v_mfma_f32_16x16x32_bf16 v[2:5], v[178:181], v[186:189], v[2:5]
	v_mfma_f32_16x16x32_bf16 v[18:21], v[170:173], v[194:197], v[18:21]
	v_mfma_f32_16x16x32_bf16 v[6:9], v[178:181], v[194:197], v[6:9]
	v_mfma_f32_16x16x32_bf16 v[22:25], v[170:173], v[202:205], v[22:25]
	v_mfma_f32_16x16x32_bf16 v[10:13], v[178:181], v[202:205], v[10:13]
	v_mfma_f32_16x16x32_bf16 v[30:33], v[170:173], v[210:213], v[30:33]
	v_mfma_f32_16x16x32_bf16 v[26:29], v[178:181], v[210:213], v[26:29]
	s_setprio 0
	s_barrier
	s_mov_b32 m0, s44
	s_add_u32 s52, s14, 0x2b0000
	ds_read_b128 v[182:185], v143 offset:16384
	ds_read_b128 v[186:189], v143 offset:17408
	global_load_lds_dwordx4 v132, s[14:15]
	ds_read_b128 v[190:193], v143 offset:18432
	s_mov_b32 m0, s45
	s_addc_u32 s53, s15, 0
	global_load_lds_dwordx4 v136, s[14:15]
	ds_read_b128 v[194:197], v143 offset:19456
	s_mov_b32 m0, s46
	s_nop 0
	global_load_lds_dwordx4 v132, s[52:53]
	ds_read_b128 v[198:201], v143 offset:20480
	s_mov_b32 m0, s47
	s_nop 0
	global_load_lds_dwordx4 v136, s[52:53]
	ds_read_b128 v[202:205], v143 offset:21504
	s_add_u32 s56, s20, s2
	s_addc_u32 s57, s21, s3
	s_mov_b32 m0, s25
	s_nop 0
	global_load_lds_dwordx4 v130, s[20:21]
	ds_read_b128 v[206:209], v143 offset:22528
	s_mov_b32 m0, s27
	s_nop 0
	global_load_lds_dwordx4 v134, s[20:21]
	ds_read_b128 v[210:213], v143 offset:23552
	s_waitcnt vmcnt(8)
	s_waitcnt lgkmcnt(0)
	s_barrier
	s_setprio 1
	s_waitcnt lgkmcnt(0)
	v_mfma_f32_16x16x32_bf16 v[94:97], v[146:149], v[182:185], v[94:97]
	v_mfma_f32_16x16x32_bf16 v[90:93], v[154:157], v[182:185], v[90:93]
	v_mfma_f32_16x16x32_bf16 v[106:109], v[146:149], v[190:193], v[106:109]
	v_mfma_f32_16x16x32_bf16 v[98:101], v[154:157], v[190:193], v[98:101]
	v_mfma_f32_16x16x32_bf16 v[110:113], v[146:149], v[198:201], v[110:113]
	v_mfma_f32_16x16x32_bf16 v[102:105], v[154:157], v[198:201], v[102:105]
	v_mfma_f32_16x16x32_bf16 v[126:129], v[146:149], v[206:209], v[126:129]
	v_mfma_f32_16x16x32_bf16 v[122:125], v[154:157], v[206:209], v[122:125]
	v_mfma_f32_16x16x32_bf16 v[94:97], v[150:153], v[186:189], v[94:97]
	v_mfma_f32_16x16x32_bf16 v[90:93], v[158:161], v[186:189], v[90:93]
	v_mfma_f32_16x16x32_bf16 v[106:109], v[150:153], v[194:197], v[106:109]
	v_mfma_f32_16x16x32_bf16 v[98:101], v[158:161], v[194:197], v[98:101]
	v_mfma_f32_16x16x32_bf16 v[110:113], v[150:153], v[202:205], v[110:113]
	v_mfma_f32_16x16x32_bf16 v[102:105], v[158:161], v[202:205], v[102:105]
	v_mfma_f32_16x16x32_bf16 v[126:129], v[150:153], v[210:213], v[126:129]
	v_mfma_f32_16x16x32_bf16 v[122:125], v[158:161], v[210:213], v[122:125]
	s_setprio 0
	s_setprio 1
	v_mfma_f32_16x16x32_bf16 v[38:41], v[164:167], v[182:185], v[38:41]
	v_mfma_f32_16x16x32_bf16 v[34:37], v[174:177], v[182:185], v[34:37]
	v_mfma_f32_16x16x32_bf16 v[66:69], v[164:167], v[190:193], v[66:69]
	v_mfma_f32_16x16x32_bf16 v[46:49], v[174:177], v[190:193], v[46:49]
	v_mfma_f32_16x16x32_bf16 v[78:81], v[164:167], v[198:201], v[78:81]
	v_mfma_f32_16x16x32_bf16 v[62:65], v[174:177], v[198:201], v[62:65]
	v_mfma_f32_16x16x32_bf16 v[118:121], v[164:167], v[206:209], v[118:121]
	v_mfma_f32_16x16x32_bf16 v[114:117], v[174:177], v[206:209], v[114:117]
	v_mfma_f32_16x16x32_bf16 v[38:41], v[170:173], v[186:189], v[38:41]
	v_mfma_f32_16x16x32_bf16 v[34:37], v[178:181], v[186:189], v[34:37]
	v_mfma_f32_16x16x32_bf16 v[66:69], v[170:173], v[194:197], v[66:69]
	v_mfma_f32_16x16x32_bf16 v[46:49], v[178:181], v[194:197], v[46:49]
	v_mfma_f32_16x16x32_bf16 v[78:81], v[170:173], v[202:205], v[78:81]
	v_mfma_f32_16x16x32_bf16 v[62:65], v[178:181], v[202:205], v[62:65]
	v_mfma_f32_16x16x32_bf16 v[118:121], v[170:173], v[210:213], v[118:121]
	v_mfma_f32_16x16x32_bf16 v[114:117], v[178:181], v[210:213], v[114:117]
	s_setprio 0
	s_barrier
; #define PG8_STAGE(bufoff, gbase, voff) do { _Pragma("unroll") for (int _i = 0; _i < 2; ++_i) \
;         __builtin_amdgcn_global_load_lds((const unsigned*)((const char*)(gbase) + (voff)[_i]), (LAS unsigned*)(lds + (bufoff) + ldsw + _i * 8192), 16, 0, 0); } while (0)
; #define PG8_LDA(dst, b, h) do { _Pragma("unroll") for (int m = 0; m < 4; ++m) _Pragma("unroll") for (int k = 0; k < 2; ++k) dst[m][k] = *(const LAS bf16x8*)(lds + PG8_SA(b, h) + aoff + m * 2048 + k * 1024); } while (0)
; #define PG8_LDB(dst, b, h) do { _Pragma("unroll") for (int n = 0; n < 2; ++n) _Pragma("unroll") for (int k = 0; k < 2; ++k) dst[n][k] = *(const LAS bf16x8*)(lds + PG8_SB(b, h) + boff + n * 2048 + k * 1024); } while (0)
; #define PG8_MMA(ai, bj, At, Bt) do { __builtin_amdgcn_s_setprio(1); _Pragma("unroll") for (int m = 0; m < 4; ++m) _Pragma("unroll") for (int n = 0; n < 2; ++n) _Pragma("unroll") for (int k = 0; k < 2; ++k) \
;         acc[ai][bj][m][n] = __builtin_amdgcn_mfma_f32_16x16x32_bf16(Bt[n][k], At[m][k], acc[ai][bj][m][n], 0, 0, 0); __builtin_amdgcn_s_setprio(0); } while (0)
; #define PG8_WAIT_V(n) asm volatile("s_waitcnt vmcnt(" #n ")" ::: "memory")
; #define PG8_WAIT_L(n) asm volatile("s_waitcnt lgkmcnt(" #n ")" ::: "memory")
; #define PG8_BAR __builtin_amdgcn_s_barrier()
; #define PG8_SCHED __builtin_amdgcn_sched_barrier(0)
; template <class Epi, class Sched, bool ALIGN_EPI, class Hook = NoHook>
; __device__ __forceinline__ void gemm_phase(LAS unsigned char* lds, const Gemm g, const Sched& S, const Epi& E, const Hook& H = Hook()) {
;     ...
;             PG8_LDB(B0, 1, 0); PG8_LDB(B1, 1, 1); PG8_SCHED; PG8_LDA(At, 1, 0); PG8_STAGE(PG8_SA(0, 1), a2 + hA, voffA);
;             PG8_WAIT_V(8); PG8_WAIT_L(0); PG8_BAR; PG8_MMA(0, 0, At, B0); PG8_MMA(0, 1, At, B1); PG8_BAR; PG8_SCHED;
;             PG8_LDA(At, 1, 1); PG8_STAGE(PG8_SB(1, 0), b3, voffB); PG8_STAGE(PG8_SB(1, 1), b3 + hB, voffB); PG8_STAGE(PG8_SA(1, 0), a3, voffA);
;             PG8_WAIT_V(8); PG8_WAIT_L(0); PG8_BAR; PG8_MMA(1, 0, At, B0); PG8_MMA(1, 1, At, B1); PG8_BAR; PG8_SCHED;
;         }
	ds_read_b128 v[146:149], v144
	ds_read_b128 v[150:153], v144 offset:1024
	s_add_u32 s20, s20, 0x2b0000
	s_addc_u32 s21, s21, 0
	s_mov_b32 m0, s28
	s_nop 0
	global_load_lds_dwordx4 v130, s[20:21]
	ds_read_b128 v[154:157], v144 offset:2048
	ds_read_b128 v[158:161], v144 offset:3072
	ds_read_b128 v[164:167], v145
	ds_read_b128 v[170:173], v145 offset:1024
	ds_read_b128 v[174:177], v145 offset:2048
	ds_read_b128 v[178:181], v145 offset:3072
	ds_read_b128 v[182:185], v143 offset:32768
	s_mov_b32 m0, s38
	s_nop 0
	global_load_lds_dwordx4 v134, s[20:21]
	ds_read_b128 v[186:189], v143 offset:33792
	ds_read_b128 v[190:193], v143 offset:34816
	ds_read_b128 v[194:197], v143 offset:35840
	ds_read_b128 v[198:201], v143 offset:36864
	ds_read_b128 v[202:205], v143 offset:37888
	ds_read_b128 v[206:209], v143 offset:38912
	ds_read_b128 v[210:213], v143 offset:39936
	s_waitcnt vmcnt(8)
	s_waitcnt lgkmcnt(0)
	s_barrier
	s_setprio 1
	s_waitcnt lgkmcnt(0)
	v_mfma_f32_16x16x32_bf16 v[82:85], v[146:149], v[182:185], v[82:85]
	v_mfma_f32_16x16x32_bf16 v[54:57], v[154:157], v[182:185], v[54:57]
	v_mfma_f32_16x16x32_bf16 v[58:61], v[146:149], v[190:193], v[58:61]
	v_mfma_f32_16x16x32_bf16 v[42:45], v[154:157], v[190:193], v[42:45]
	v_mfma_f32_16x16x32_bf16 v[70:73], v[146:149], v[198:201], v[70:73]
	v_mfma_f32_16x16x32_bf16 v[50:53], v[154:157], v[198:201], v[50:53]
	v_mfma_f32_16x16x32_bf16 v[86:89], v[146:149], v[206:209], v[86:89]
	v_mfma_f32_16x16x32_bf16 v[74:77], v[154:157], v[206:209], v[74:77]
	v_mfma_f32_16x16x32_bf16 v[82:85], v[150:153], v[186:189], v[82:85]
	v_mfma_f32_16x16x32_bf16 v[54:57], v[158:161], v[186:189], v[54:57]
	v_mfma_f32_16x16x32_bf16 v[58:61], v[150:153], v[194:197], v[58:61]
	v_mfma_f32_16x16x32_bf16 v[42:45], v[158:161], v[194:197], v[42:45]
	v_mfma_f32_16x16x32_bf16 v[70:73], v[150:153], v[202:205], v[70:73]
	v_mfma_f32_16x16x32_bf16 v[50:53], v[158:161], v[202:205], v[50:53]
	v_mfma_f32_16x16x32_bf16 v[86:89], v[150:153], v[210:213], v[86:89]
	v_mfma_f32_16x16x32_bf16 v[74:77], v[158:161], v[210:213], v[74:77]
	s_setprio 0
	s_setprio 1
	v_mfma_f32_16x16x32_bf16 v[14:17], v[164:167], v[182:185], v[14:17]
	v_mfma_f32_16x16x32_bf16 v[2:5], v[174:177], v[182:185], v[2:5]
	v_mfma_f32_16x16x32_bf16 v[18:21], v[164:167], v[190:193], v[18:21]
	v_mfma_f32_16x16x32_bf16 v[6:9], v[174:177], v[190:193], v[6:9]
	v_mfma_f32_16x16x32_bf16 v[22:25], v[164:167], v[198:201], v[22:25]
	v_mfma_f32_16x16x32_bf16 v[10:13], v[174:177], v[198:201], v[10:13]
	v_mfma_f32_16x16x32_bf16 v[30:33], v[164:167], v[206:209], v[30:33]
	v_mfma_f32_16x16x32_bf16 v[26:29], v[174:177], v[206:209], v[26:29]
	v_mfma_f32_16x16x32_bf16 v[14:17], v[170:173], v[186:189], v[14:17]
	v_mfma_f32_16x16x32_bf16 v[2:5], v[178:181], v[186:189], v[2:5]
	v_mfma_f32_16x16x32_bf16 v[18:21], v[170:173], v[194:197], v[18:21]
	v_mfma_f32_16x16x32_bf16 v[6:9], v[178:181], v[194:197], v[6:9]
	v_mfma_f32_16x16x32_bf16 v[22:25], v[170:173], v[202:205], v[22:25]
	v_mfma_f32_16x16x32_bf16 v[10:13], v[178:181], v[202:205], v[10:13]
	v_mfma_f32_16x16x32_bf16 v[30:33], v[170:173], v[210:213], v[30:33]
	v_mfma_f32_16x16x32_bf16 v[26:29], v[178:181], v[210:213], v[26:29]
	s_setprio 0
	s_barrier
	s_mov_b32 m0, s48
	s_add_u32 s54, s14, s2
	s_addc_u32 s55, s15, s3
	s_add_u32 s14, s14, 0x2b0080
	ds_read_b128 v[182:185], v143 offset:49152
	ds_read_b128 v[186:189], v143 offset:50176
	global_load_lds_dwordx4 v132, s[54:55]
	ds_read_b128 v[190:193], v143 offset:51200
	s_mov_b32 m0, s49
	s_addc_u32 s15, s15, 0
	global_load_lds_dwordx4 v136, s[54:55]
	ds_read_b128 v[194:197], v143 offset:52224
	s_mov_b32 m0, s50
	s_nop 0
	global_load_lds_dwordx4 v132, s[14:15]
	ds_read_b128 v[198:201], v143 offset:53248
	s_mov_b32 m0, s51
	s_nop 0
	global_load_lds_dwordx4 v136, s[14:15]
	ds_read_b128 v[202:205], v143 offset:54272
	s_mov_b32 m0, s39
	s_nop 0
	global_load_lds_dwordx4 v130, s[56:57]
	ds_read_b128 v[206:209], v143 offset:55296
	s_mov_b32 m0, s40
	s_nop 0
	global_load_lds_dwordx4 v134, s[56:57]
	ds_read_b128 v[210:213], v143 offset:56320
	s_waitcnt vmcnt(8)
	s_waitcnt lgkmcnt(0)
	s_barrier
	s_setprio 1
	s_waitcnt lgkmcnt(0)
	v_mfma_f32_16x16x32_bf16 v[94:97], v[146:149], v[182:185], v[94:97]
	v_mfma_f32_16x16x32_bf16 v[90:93], v[154:157], v[182:185], v[90:93]
	v_mfma_f32_16x16x32_bf16 v[106:109], v[146:149], v[190:193], v[106:109]
	v_mfma_f32_16x16x32_bf16 v[98:101], v[154:157], v[190:193], v[98:101]
	v_mfma_f32_16x16x32_bf16 v[110:113], v[146:149], v[198:201], v[110:113]
	v_mfma_f32_16x16x32_bf16 v[102:105], v[154:157], v[198:201], v[102:105]
	v_mfma_f32_16x16x32_bf16 v[126:129], v[146:149], v[206:209], v[126:129]
	v_mfma_f32_16x16x32_bf16 v[122:125], v[154:157], v[206:209], v[122:125]
	v_mfma_f32_16x16x32_bf16 v[94:97], v[150:153], v[186:189], v[94:97]
	v_mfma_f32_16x16x32_bf16 v[90:93], v[158:161], v[186:189], v[90:93]
	v_mfma_f32_16x16x32_bf16 v[106:109], v[150:153], v[194:197], v[106:109]
	v_mfma_f32_16x16x32_bf16 v[98:101], v[158:161], v[194:197], v[98:101]
	v_mfma_f32_16x16x32_bf16 v[110:113], v[150:153], v[202:205], v[110:113]
	v_mfma_f32_16x16x32_bf16 v[102:105], v[158:161], v[202:205], v[102:105]
	v_mfma_f32_16x16x32_bf16 v[126:129], v[150:153], v[210:213], v[126:129]
	v_mfma_f32_16x16x32_bf16 v[122:125], v[158:161], v[210:213], v[122:125]
	s_setprio 0
	s_setprio 1
	v_mfma_f32_16x16x32_bf16 v[38:41], v[164:167], v[182:185], v[38:41]
	v_mfma_f32_16x16x32_bf16 v[34:37], v[174:177], v[182:185], v[34:37]
	v_mfma_f32_16x16x32_bf16 v[66:69], v[164:167], v[190:193], v[66:69]
	v_mfma_f32_16x16x32_bf16 v[46:49], v[174:177], v[190:193], v[46:49]
	v_mfma_f32_16x16x32_bf16 v[78:81], v[164:167], v[198:201], v[78:81]
	v_mfma_f32_16x16x32_bf16 v[62:65], v[174:177], v[198:201], v[62:65]
	v_mfma_f32_16x16x32_bf16 v[118:121], v[164:167], v[206:209], v[118:121]
	v_mfma_f32_16x16x32_bf16 v[114:117], v[174:177], v[206:209], v[114:117]
	v_mfma_f32_16x16x32_bf16 v[38:41], v[170:173], v[186:189], v[38:41]
	v_mfma_f32_16x16x32_bf16 v[34:37], v[178:181], v[186:189], v[34:37]
	v_mfma_f32_16x16x32_bf16 v[66:69], v[170:173], v[194:197], v[66:69]
	v_mfma_f32_16x16x32_bf16 v[46:49], v[178:181], v[194:197], v[46:49]
	v_mfma_f32_16x16x32_bf16 v[78:81], v[170:173], v[202:205], v[78:81]
	v_mfma_f32_16x16x32_bf16 v[62:65], v[178:181], v[202:205], v[62:65]
	v_mfma_f32_16x16x32_bf16 v[118:121], v[170:173], v[210:213], v[118:121]
	v_mfma_f32_16x16x32_bf16 v[114:117], v[178:181], v[210:213], v[114:117]
	s_setprio 0
	s_barrier
	s_add_i32 s41, s41, 2
	s_add_u32 s4, s4, 0x100
	s_addc_u32 s5, s5, 0
	s_cmpk_gt_u32 s41, 0xa9
	s_cbranch_scc0 .LBB0_1360
	s_cmpk_lt_u32 s26, 0x100
	s_cbranch_scc0 .LBB0_1363
	s_barrier

; #define PG8_STAGE(bufoff, gbase, voff) do { _Pragma("unroll") for (int _i = 0; _i < 2; ++_i) \
;         __builtin_amdgcn_global_load_lds((const unsigned*)((const char*)(gbase) + (voff)[_i]), (LAS unsigned*)(lds + (bufoff) + ldsw + _i * 8192), 16, 0, 0); } while (0)
; #define PG8_LDA(dst, b, h) do { _Pragma("unroll") for (int m = 0; m < 4; ++m) _Pragma("unroll") for (int k = 0; k < 2; ++k) dst[m][k] = *(const LAS bf16x8*)(lds + PG8_SA(b, h) + aoff + m * 2048 + k * 1024); } while (0)
; #define PG8_LDB(dst, b, h) do { _Pragma("unroll") for (int n = 0; n < 2; ++n) _Pragma("unroll") for (int k = 0; k < 2; ++k) dst[n][k] = *(const LAS bf16x8*)(lds + PG8_SB(b, h) + boff + n * 2048 + k * 1024); } while (0)
; #define PG8_MMA(ai, bj, At, Bt) do { __builtin_amdgcn_s_setprio(1); _Pragma("unroll") for (int m = 0; m < 4; ++m) _Pragma("unroll") for (int n = 0; n < 2; ++n) _Pragma("unroll") for (int k = 0; k < 2; ++k) \
;         acc[ai][bj][m][n] = __builtin_amdgcn_mfma_f32_16x16x32_bf16(Bt[n][k], At[m][k], acc[ai][bj][m][n], 0, 0, 0); __builtin_amdgcn_s_setprio(0); } while (0)
; #define PG8_WAIT_V(n) asm volatile("s_waitcnt vmcnt(" #n ")" ::: "memory")
; #define PG8_WAIT_L(n) asm volatile("s_waitcnt lgkmcnt(" #n ")" ::: "memory")
; #define PG8_BAR __builtin_amdgcn_s_barrier()
; template <class Epi, class Sched, bool ALIGN_EPI, class Hook = NoHook>
; __device__ __forceinline__ void gemm_phase(LAS unsigned char* lds, const Gemm g, const Sched& S, const Epi& E, const Hook& H = Hook()) {
;     ...
;             const bool last = (t == nt - 2);
;             const char* a1 = cA + (size_t)(t + 1) * kstep;
;             const char* a2 = last ? nA : cA + (size_t)(t + 2) * kstep; const char* b2 = last ? nB : cB + (size_t)(t + 2) * kstep;
;             const char* a3 = a2 + kstep; const char* b3 = b2 + kstep;
;             if (last && has_next) S.a_ready(nxt);
;             PG8_LDB(B0, 0, 0); PG8_LDB(B1, 0, 1); PG8_SCHED; PG8_LDA(At, 0, 0); PG8_STAGE(PG8_SA(1, 1), a1 + hA, voffA);
;             PG8_WAIT_V(8); PG8_WAIT_L(0); PG8_BAR; PG8_MMA(0, 0, At, B0); PG8_MMA(0, 1, At, B1); PG8_BAR; PG8_SCHED;
;             PG8_LDA(At, 0, 1); PG8_STAGE(PG8_SB(0, 0), b2, voffB); PG8_STAGE(PG8_SB(0, 1), b2 + hB, voffB); PG8_STAGE(PG8_SA(0, 0), a2, voffA);
;             PG8_WAIT_V(8); PG8_WAIT_L(0); PG8_BAR; PG8_MMA(1, 0, At, B0); PG8_MMA(1, 1, At, B1); PG8_BAR; PG8_SCHED;
.LBB0_1406:
	ds_read_b128 v[146:149], v140
	ds_read_b128 v[150:153], v140 offset:1024
	s_add_u32 s10, s4, 0xbb050080
	s_addc_u32 s11, s5, -1
	s_cmpk_lg_i32 s18, 0xa8
	s_cselect_b32 s10, s10, 0
	s_cselect_b32 s11, s11, 0
	s_add_u32 s16, s0, s10
	s_addc_u32 s17, s1, s11
	s_add_u32 s10, s12, s10
	s_addc_u32 s11, s13, s11
	s_mov_b32 m0, s19
	ds_read_b128 v[154:157], v140 offset:2048
	ds_read_b128 v[158:161], v140 offset:3072
	ds_read_b128 v[170:173], v141
	ds_read_b128 v[174:177], v141 offset:1024
	ds_read_b128 v[178:181], v141 offset:2048
	ds_read_b128 v[182:185], v141 offset:3072
	v_lshl_add_u64 v[218:219], v[136:137], 0, s[4:5]
	global_load_lds_dwordx4 v[218:219], off
	ds_read_b128 v[186:189], v142
	ds_read_b128 v[190:193], v142 offset:1024
	ds_read_b128 v[194:197], v142 offset:2048
	ds_read_b128 v[198:201], v142 offset:3072
	ds_read_b128 v[202:205], v142 offset:4096
	ds_read_b128 v[206:209], v142 offset:5120
	ds_read_b128 v[210:213], v142 offset:6144
	ds_read_b128 v[214:217], v142 offset:7168
	v_lshl_add_u64 v[218:219], v[138:139], 0, s[4:5]
	s_mov_b32 m0, s31
	s_nop 0
	global_load_lds_dwordx4 v[218:219], off
	s_waitcnt vmcnt(8)
	s_waitcnt lgkmcnt(0)
	s_barrier
	s_setprio 1
	s_waitcnt lgkmcnt(0)
	v_mfma_f32_16x16x32_bf16 v[82:85], v[146:149], v[186:189], v[82:85]
	v_mfma_f32_16x16x32_bf16 v[54:57], v[154:157], v[186:189], v[54:57]
	v_mfma_f32_16x16x32_bf16 v[58:61], v[146:149], v[194:197], v[58:61]
	v_mfma_f32_16x16x32_bf16 v[42:45], v[154:157], v[194:197], v[42:45]
	v_mfma_f32_16x16x32_bf16 v[70:73], v[146:149], v[202:205], v[70:73]
	v_mfma_f32_16x16x32_bf16 v[50:53], v[154:157], v[202:205], v[50:53]
	v_mfma_f32_16x16x32_bf16 v[86:89], v[146:149], v[210:213], v[86:89]
	v_mfma_f32_16x16x32_bf16 v[74:77], v[154:157], v[210:213], v[74:77]
	v_mfma_f32_16x16x32_bf16 v[82:85], v[150:153], v[190:193], v[82:85]
	v_mfma_f32_16x16x32_bf16 v[54:57], v[158:161], v[190:193], v[54:57]
	v_mfma_f32_16x16x32_bf16 v[58:61], v[150:153], v[198:201], v[58:61]
	v_mfma_f32_16x16x32_bf16 v[42:45], v[158:161], v[198:201], v[42:45]
	v_mfma_f32_16x16x32_bf16 v[70:73], v[150:153], v[206:209], v[70:73]
	v_mfma_f32_16x16x32_bf16 v[50:53], v[158:161], v[206:209], v[50:53]
	v_mfma_f32_16x16x32_bf16 v[86:89], v[150:153], v[214:217], v[86:89]
	v_mfma_f32_16x16x32_bf16 v[74:77], v[158:161], v[214:217], v[74:77]
	s_setprio 0
	s_setprio 1
	v_mfma_f32_16x16x32_bf16 v[14:17], v[170:173], v[186:189], v[14:17]
	v_mfma_f32_16x16x32_bf16 v[2:5], v[178:181], v[186:189], v[2:5]
	v_mfma_f32_16x16x32_bf16 v[18:21], v[170:173], v[194:197], v[18:21]
	v_mfma_f32_16x16x32_bf16 v[6:9], v[178:181], v[194:197], v[6:9]
	v_mfma_f32_16x16x32_bf16 v[22:25], v[170:173], v[202:205], v[22:25]
	v_mfma_f32_16x16x32_bf16 v[10:13], v[178:181], v[202:205], v[10:13]
	v_mfma_f32_16x16x32_bf16 v[30:33], v[170:173], v[210:213], v[30:33]
	v_mfma_f32_16x16x32_bf16 v[26:29], v[178:181], v[210:213], v[26:29]
	v_mfma_f32_16x16x32_bf16 v[14:17], v[174:177], v[190:193], v[14:17]
	v_mfma_f32_16x16x32_bf16 v[2:5], v[182:185], v[190:193], v[2:5]
	v_mfma_f32_16x16x32_bf16 v[18:21], v[174:177], v[198:201], v[18:21]
	v_mfma_f32_16x16x32_bf16 v[6:9], v[182:185], v[198:201], v[6:9]
	v_mfma_f32_16x16x32_bf16 v[22:25], v[174:177], v[206:209], v[22:25]
	v_mfma_f32_16x16x32_bf16 v[10:13], v[182:185], v[206:209], v[10:13]
	v_mfma_f32_16x16x32_bf16 v[30:33], v[174:177], v[214:217], v[30:33]
	v_mfma_f32_16x16x32_bf16 v[26:29], v[182:185], v[214:217], v[26:29]
	s_setprio 0
	s_barrier
	s_mov_b32 m0, s33
	s_add_u32 s46, s10, 0x2b0000
	ds_read_b128 v[186:189], v142 offset:16384
	ds_read_b128 v[190:193], v142 offset:17408
	global_load_lds_dwordx4 v162, s[10:11]
	ds_read_b128 v[194:197], v142 offset:18432
	s_mov_b32 m0, s34
	s_addc_u32 s47, s11, 0
	global_load_lds_dwordx4 v134, s[10:11]
	ds_read_b128 v[198:201], v142 offset:19456
	s_mov_b32 m0, s35
	s_nop 0
	global_load_lds_dwordx4 v162, s[46:47]
	ds_read_b128 v[202:205], v142 offset:20480
	s_mov_b32 m0, s43
	s_nop 0
	global_load_lds_dwordx4 v134, s[46:47]
	ds_read_b128 v[206:209], v142 offset:21504
	s_add_u32 s54, s16, s2
	s_addc_u32 s55, s17, s3
	s_mov_b32 m0, s27
	s_nop 0
	global_load_lds_dwordx4 v130, s[16:17]
	ds_read_b128 v[210:213], v142 offset:22528
	s_mov_b32 m0, s28
	s_nop 0
	global_load_lds_dwordx4 v132, s[16:17]
	ds_read_b128 v[214:217], v142 offset:23552
	s_waitcnt vmcnt(8)
	s_waitcnt lgkmcnt(0)
	s_barrier
	s_setprio 1
	s_waitcnt lgkmcnt(0)
	v_mfma_f32_16x16x32_bf16 v[94:97], v[146:149], v[186:189], v[94:97]
	v_mfma_f32_16x16x32_bf16 v[90:93], v[154:157], v[186:189], v[90:93]
	v_mfma_f32_16x16x32_bf16 v[118:121], v[146:149], v[194:197], v[118:121]
	v_mfma_f32_16x16x32_bf16 v[98:101], v[154:157], v[194:197], v[98:101]
	v_mfma_f32_16x16x32_bf16 v[126:129], v[146:149], v[202:205], v[126:129]
	v_mfma_f32_16x16x32_bf16 v[110:113], v[154:157], v[202:205], v[110:113]
	v_mfma_f32_16x16x32_bf16 v[122:125], v[146:149], v[210:213], v[122:125]
	v_mfma_f32_16x16x32_bf16 v[114:117], v[154:157], v[210:213], v[114:117]
	v_mfma_f32_16x16x32_bf16 v[94:97], v[150:153], v[190:193], v[94:97]
	v_mfma_f32_16x16x32_bf16 v[90:93], v[158:161], v[190:193], v[90:93]
	v_mfma_f32_16x16x32_bf16 v[118:121], v[150:153], v[198:201], v[118:121]
	v_mfma_f32_16x16x32_bf16 v[98:101], v[158:161], v[198:201], v[98:101]
	v_mfma_f32_16x16x32_bf16 v[126:129], v[150:153], v[206:209], v[126:129]
	v_mfma_f32_16x16x32_bf16 v[110:113], v[158:161], v[206:209], v[110:113]
	v_mfma_f32_16x16x32_bf16 v[122:125], v[150:153], v[214:217], v[122:125]
	v_mfma_f32_16x16x32_bf16 v[114:117], v[158:161], v[214:217], v[114:117]
	s_setprio 0
	s_setprio 1
	v_mfma_f32_16x16x32_bf16 v[38:41], v[170:173], v[186:189], v[38:41]
	v_mfma_f32_16x16x32_bf16 v[34:37], v[178:181], v[186:189], v[34:37]
	v_mfma_f32_16x16x32_bf16 v[66:69], v[170:173], v[194:197], v[66:69]
	v_mfma_f32_16x16x32_bf16 v[46:49], v[178:181], v[194:197], v[46:49]
	v_mfma_f32_16x16x32_bf16 v[78:81], v[170:173], v[202:205], v[78:81]
	v_mfma_f32_16x16x32_bf16 v[62:65], v[178:181], v[202:205], v[62:65]
	v_mfma_f32_16x16x32_bf16 v[106:109], v[170:173], v[210:213], v[106:109]
	v_mfma_f32_16x16x32_bf16 v[102:105], v[178:181], v[210:213], v[102:105]
	v_mfma_f32_16x16x32_bf16 v[38:41], v[174:177], v[190:193], v[38:41]
	v_mfma_f32_16x16x32_bf16 v[34:37], v[182:185], v[190:193], v[34:37]
	v_mfma_f32_16x16x32_bf16 v[66:69], v[174:177], v[198:201], v[66:69]
	v_mfma_f32_16x16x32_bf16 v[46:49], v[182:185], v[198:201], v[46:49]
	v_mfma_f32_16x16x32_bf16 v[78:81], v[174:177], v[206:209], v[78:81]
	v_mfma_f32_16x16x32_bf16 v[62:65], v[182:185], v[206:209], v[62:65]
	v_mfma_f32_16x16x32_bf16 v[106:109], v[174:177], v[214:217], v[106:109]
	v_mfma_f32_16x16x32_bf16 v[102:105], v[182:185], v[214:217], v[102:105]
	s_setprio 0
	s_barrier
; #define PG8_STAGE(bufoff, gbase, voff) do { _Pragma("unroll") for (int _i = 0; _i < 2; ++_i) \
;         __builtin_amdgcn_global_load_lds((const unsigned*)((const char*)(gbase) + (voff)[_i]), (LAS unsigned*)(lds + (bufoff) + ldsw + _i * 8192), 16, 0, 0); } while (0)
; #define PG8_LDA(dst, b, h) do { _Pragma("unroll") for (int m = 0; m < 4; ++m) _Pragma("unroll") for (int k = 0; k < 2; ++k) dst[m][k] = *(const LAS bf16x8*)(lds + PG8_SA(b, h) + aoff + m * 2048 + k * 1024); } while (0)
; #define PG8_LDB(dst, b, h) do { _Pragma("unroll") for (int n = 0; n < 2; ++n) _Pragma("unroll") for (int k = 0; k < 2; ++k) dst[n][k] = *(const LAS bf16x8*)(lds + PG8_SB(b, h) + boff + n * 2048 + k * 1024); } while (0)
; #define PG8_BAR __builtin_amdgcn_s_barrier()
; template <class Epi, class Sched, bool ALIGN_EPI, class Hook = NoHook>
; __device__ __forceinline__ void gemm_phase(LAS unsigned char* lds, const Gemm g, const Sched& S, const Epi& E, const Hook& H = Hook()) {
;     ...
;         for (int t = tb; t < te; t += 2) {
;             const bool last = (t == nt - 2);
;             const char* a1 = cA + (size_t)(t + 1) * kstep;
;             const char* a2 = last ? nA : cA + (size_t)(t + 2) * kstep; const char* b2 = last ? nB : cB + (size_t)(t + 2) * kstep;
;             const char* a3 = a2 + kstep; const char* b3 = b2 + kstep;
;             if (last && has_next) S.a_ready(nxt);
;             PG8_LDB(B0, 0, 0); PG8_LDB(B1, 0, 1); PG8_SCHED; PG8_LDA(At, 0, 0); PG8_STAGE(PG8_SA(1, 1), a1 + hA, voffA);
;             PG8_WAIT_V(8); PG8_WAIT_L(0); PG8_BAR; PG8_MMA(0, 0, At, B0); PG8_MMA(0, 1, At, B1); PG8_BAR; PG8_SCHED;
;             PG8_LDA(At, 0, 1); PG8_STAGE(PG8_SB(0, 0), b2, voffB); PG8_STAGE(PG8_SB(0, 1), b2 + hB, voffB); PG8_STAGE(PG8_SA(0, 0), a2, voffA);
;             PG8_WAIT_V(8); PG8_WAIT_L(0); PG8_BAR; PG8_MMA(1, 0, At, B0); PG8_MMA(1, 1, At, B1); PG8_BAR; PG8_SCHED;
;             PG8_LDB(B0, 1, 0); PG8_LDB(B1, 1, 1); PG8_SCHED; PG8_LDA(At, 1, 0); PG8_STAGE(PG8_SA(0, 1), a2 + hA, voffA);
;             PG8_WAIT_V(8); PG8_WAIT_L(0); PG8_BAR; PG8_MMA(0, 0, At, B0); PG8_MMA(0, 1, At, B1); PG8_BAR; PG8_SCHED;
;             PG8_LDA(At, 1, 1); PG8_STAGE(PG8_SB(1, 0), b3, voffB); PG8_STAGE(PG8_SB(1, 1), b3 + hB, voffB); PG8_STAGE(PG8_SA(1, 0), a3, voffA);
;             PG8_WAIT_V(8); PG8_WAIT_L(0); PG8_BAR; PG8_MMA(1, 0, At, B0); PG8_MMA(1, 1, At, B1); PG8_BAR; PG8_SCHED;
	ds_read_b128 v[146:149], v143
	ds_read_b128 v[150:153], v143 offset:1024
	s_add_u32 s16, s16, 0x2b0000
	s_addc_u32 s17, s17, 0
	s_mov_b32 m0, s29
	s_nop 0
	global_load_lds_dwordx4 v130, s[16:17]
	ds_read_b128 v[154:157], v143 offset:2048
	ds_read_b128 v[158:161], v143 offset:3072
	ds_read_b128 v[170:173], v144
	ds_read_b128 v[174:177], v144 offset:1024
	ds_read_b128 v[178:181], v144 offset:2048
	ds_read_b128 v[182:185], v144 offset:3072
	ds_read_b128 v[186:189], v142 offset:32768
	s_mov_b32 m0, s39
	s_nop 0
	global_load_lds_dwordx4 v132, s[16:17]
	ds_read_b128 v[190:193], v142 offset:33792
	ds_read_b128 v[194:197], v142 offset:34816
	ds_read_b128 v[198:201], v142 offset:35840
	ds_read_b128 v[202:205], v142 offset:36864
	ds_read_b128 v[206:209], v142 offset:37888
	ds_read_b128 v[210:213], v142 offset:38912
	ds_read_b128 v[214:217], v142 offset:39936
	s_waitcnt vmcnt(8)
	s_waitcnt lgkmcnt(0)
	s_barrier
	s_setprio 1
	s_waitcnt lgkmcnt(0)
	v_mfma_f32_16x16x32_bf16 v[82:85], v[146:149], v[186:189], v[82:85]
	v_mfma_f32_16x16x32_bf16 v[54:57], v[154:157], v[186:189], v[54:57]
	v_mfma_f32_16x16x32_bf16 v[58:61], v[146:149], v[194:197], v[58:61]
	v_mfma_f32_16x16x32_bf16 v[42:45], v[154:157], v[194:197], v[42:45]
	v_mfma_f32_16x16x32_bf16 v[70:73], v[146:149], v[202:205], v[70:73]
	v_mfma_f32_16x16x32_bf16 v[50:53], v[154:157], v[202:205], v[50:53]
	v_mfma_f32_16x16x32_bf16 v[86:89], v[146:149], v[210:213], v[86:89]
	v_mfma_f32_16x16x32_bf16 v[74:77], v[154:157], v[210:213], v[74:77]
	v_mfma_f32_16x16x32_bf16 v[82:85], v[150:153], v[190:193], v[82:85]
	v_mfma_f32_16x16x32_bf16 v[54:57], v[158:161], v[190:193], v[54:57]
	v_mfma_f32_16x16x32_bf16 v[58:61], v[150:153], v[198:201], v[58:61]
	v_mfma_f32_16x16x32_bf16 v[42:45], v[158:161], v[198:201], v[42:45]
	v_mfma_f32_16x16x32_bf16 v[70:73], v[150:153], v[206:209], v[70:73]
	v_mfma_f32_16x16x32_bf16 v[50:53], v[158:161], v[206:209], v[50:53]
	v_mfma_f32_16x16x32_bf16 v[86:89], v[150:153], v[214:217], v[86:89]
	v_mfma_f32_16x16x32_bf16 v[74:77], v[158:161], v[214:217], v[74:77]
	s_setprio 0
	s_setprio 1
	v_mfma_f32_16x16x32_bf16 v[14:17], v[170:173], v[186:189], v[14:17]
	v_mfma_f32_16x16x32_bf16 v[2:5], v[178:181], v[186:189], v[2:5]
	v_mfma_f32_16x16x32_bf16 v[18:21], v[170:173], v[194:197], v[18:21]
	v_mfma_f32_16x16x32_bf16 v[6:9], v[178:181], v[194:197], v[6:9]
	v_mfma_f32_16x16x32_bf16 v[22:25], v[170:173], v[202:205], v[22:25]
	v_mfma_f32_16x16x32_bf16 v[10:13], v[178:181], v[202:205], v[10:13]
	v_mfma_f32_16x16x32_bf16 v[30:33], v[170:173], v[210:213], v[30:33]
	v_mfma_f32_16x16x32_bf16 v[26:29], v[178:181], v[210:213], v[26:29]
	v_mfma_f32_16x16x32_bf16 v[14:17], v[174:177], v[190:193], v[14:17]
	v_mfma_f32_16x16x32_bf16 v[2:5], v[182:185], v[190:193], v[2:5]
	v_mfma_f32_16x16x32_bf16 v[18:21], v[174:177], v[198:201], v[18:21]
	v_mfma_f32_16x16x32_bf16 v[6:9], v[182:185], v[198:201], v[6:9]
	v_mfma_f32_16x16x32_bf16 v[22:25], v[174:177], v[206:209], v[22:25]
	v_mfma_f32_16x16x32_bf16 v[10:13], v[182:185], v[206:209], v[10:13]
	v_mfma_f32_16x16x32_bf16 v[30:33], v[174:177], v[214:217], v[30:33]
	v_mfma_f32_16x16x32_bf16 v[26:29], v[182:185], v[214:217], v[26:29]
	s_setprio 0
	s_barrier
	s_mov_b32 m0, s36
	s_add_u32 s52, s10, s2
	s_addc_u32 s53, s11, s3
	s_add_u32 s10, s10, 0x2b0080
	ds_read_b128 v[186:189], v142 offset:49152
	ds_read_b128 v[190:193], v142 offset:50176
	global_load_lds_dwordx4 v162, s[52:53]
	ds_read_b128 v[194:197], v142 offset:51200
	s_mov_b32 m0, s44
	s_addc_u32 s11, s11, 0
	global_load_lds_dwordx4 v134, s[52:53]
	ds_read_b128 v[198:201], v142 offset:52224
	s_mov_b32 m0, s37
	s_nop 0
	global_load_lds_dwordx4 v162, s[10:11]
	ds_read_b128 v[202:205], v142 offset:53248
	s_mov_b32 m0, s45
	s_nop 0
	global_load_lds_dwordx4 v134, s[10:11]
	ds_read_b128 v[206:209], v142 offset:54272
	s_mov_b32 m0, s41
	s_nop 0
	global_load_lds_dwordx4 v130, s[54:55]
	ds_read_b128 v[210:213], v142 offset:55296
	s_mov_b32 m0, s42
	s_nop 0
	global_load_lds_dwordx4 v132, s[54:55]
	ds_read_b128 v[214:217], v142 offset:56320
	s_waitcnt vmcnt(8)
	s_waitcnt lgkmcnt(0)
	s_barrier
	s_setprio 1
	s_waitcnt lgkmcnt(0)
	v_mfma_f32_16x16x32_bf16 v[94:97], v[146:149], v[186:189], v[94:97]
	v_mfma_f32_16x16x32_bf16 v[90:93], v[154:157], v[186:189], v[90:93]
	v_mfma_f32_16x16x32_bf16 v[118:121], v[146:149], v[194:197], v[118:121]
	v_mfma_f32_16x16x32_bf16 v[98:101], v[154:157], v[194:197], v[98:101]
	v_mfma_f32_16x16x32_bf16 v[126:129], v[146:149], v[202:205], v[126:129]
	v_mfma_f32_16x16x32_bf16 v[110:113], v[154:157], v[202:205], v[110:113]
	v_mfma_f32_16x16x32_bf16 v[122:125], v[146:149], v[210:213], v[122:125]
	v_mfma_f32_16x16x32_bf16 v[114:117], v[154:157], v[210:213], v[114:117]
	v_mfma_f32_16x16x32_bf16 v[94:97], v[150:153], v[190:193], v[94:97]
	v_mfma_f32_16x16x32_bf16 v[90:93], v[158:161], v[190:193], v[90:93]
	v_mfma_f32_16x16x32_bf16 v[118:121], v[150:153], v[198:201], v[118:121]
	v_mfma_f32_16x16x32_bf16 v[98:101], v[158:161], v[198:201], v[98:101]
	v_mfma_f32_16x16x32_bf16 v[126:129], v[150:153], v[206:209], v[126:129]
	v_mfma_f32_16x16x32_bf16 v[110:113], v[158:161], v[206:209], v[110:113]
	v_mfma_f32_16x16x32_bf16 v[122:125], v[150:153], v[214:217], v[122:125]
	v_mfma_f32_16x16x32_bf16 v[114:117], v[158:161], v[214:217], v[114:117]
	s_setprio 0
	s_setprio 1
	v_mfma_f32_16x16x32_bf16 v[38:41], v[170:173], v[186:189], v[38:41]
	v_mfma_f32_16x16x32_bf16 v[34:37], v[178:181], v[186:189], v[34:37]
	v_mfma_f32_16x16x32_bf16 v[66:69], v[170:173], v[194:197], v[66:69]
	v_mfma_f32_16x16x32_bf16 v[46:49], v[178:181], v[194:197], v[46:49]
	v_mfma_f32_16x16x32_bf16 v[78:81], v[170:173], v[202:205], v[78:81]
	v_mfma_f32_16x16x32_bf16 v[62:65], v[178:181], v[202:205], v[62:65]
	v_mfma_f32_16x16x32_bf16 v[106:109], v[170:173], v[210:213], v[106:109]
	v_mfma_f32_16x16x32_bf16 v[102:105], v[178:181], v[210:213], v[102:105]
	v_mfma_f32_16x16x32_bf16 v[38:41], v[174:177], v[190:193], v[38:41]
	v_mfma_f32_16x16x32_bf16 v[34:37], v[182:185], v[190:193], v[34:37]
	v_mfma_f32_16x16x32_bf16 v[66:69], v[174:177], v[198:201], v[66:69]
	v_mfma_f32_16x16x32_bf16 v[46:49], v[182:185], v[198:201], v[46:49]
	v_mfma_f32_16x16x32_bf16 v[78:81], v[174:177], v[206:209], v[78:81]
	v_mfma_f32_16x16x32_bf16 v[62:65], v[182:185], v[206:209], v[62:65]
	v_mfma_f32_16x16x32_bf16 v[106:109], v[174:177], v[214:217], v[106:109]
	v_mfma_f32_16x16x32_bf16 v[102:105], v[182:185], v[214:217], v[102:105]
	s_setprio 0
	s_barrier
	s_add_i32 s18, s18, 2
	s_add_u32 s4, s4, 0x100
	s_addc_u32 s5, s5, 0
	s_cmpk_gt_u32 s18, 0xa9
	s_cbranch_scc0 .LBB0_1406
	s_cmpk_lt_u32 s22, 0x100
	s_cbranch_scc0 .LBB0_1409
	s_barrier
